# same unit-boundary store-drain relaxation applied to in-proj, out-proj and FF2 K-loops (both layers)
# baseline (speedup 1.0000x reference)
.LBB13_353:
	s_waitcnt vmcnt(16)
	v_add_f32_e32 v8, v4, v5
	v_add_f32_e32 v14, v6, v7
	v_add_f32_e32 v8, v8, v14
	v_add_f32_e32 v14, v0, v1
	v_add_f32_e32 v15, v2, v3
	v_add_f32_e32 v14, v14, v15
	v_add_f32_e32 v8, v8, v14
	ds_swizzle_b32 v14, v8 offset:swizzle(SWAP,1)
	s_and_saveexec_b64 s[10:11], s[6:7]
	s_cbranch_execz .LBB13_355
	s_waitcnt lgkmcnt(0)
	v_add_f32_e32 v8, v8, v14
	v_fmamk_f32 v8, v8, 0x3a800000, v199
	v_mul_f32_e32 v14, 0x4b800000, v8
	v_cmp_gt_f32_e32 vcc, s73, v8
	s_lshl_b32 s12, s77, 11
	s_and_b32 s12, s12, 0x800
	v_cndmask_b32_e32 v8, v8, v14, vcc
	v_rsq_f32_e32 v8, v8
	s_nop 0
	v_mul_f32_e32 v14, 0x45800000, v8
	v_cndmask_b32_e32 v8, v8, v14, vcc
	v_add_u32_e32 v14, s12, v177
	ds_write_b32 v14, v8

;     __device__ float mid(int row) const { return rg(row) / ra(row); }
; #define PG8_STAGE(bufoff, gbase, voff) do { const char* gb_ = (const char*)(gbase); asm volatile("" : "+s"(gb_));     \
;         _Pragma("unroll") for (int _i = 0; _i < 2; ++_i) \
;         __builtin_amdgcn_global_load_lds((const unsigned*)(gb_ + (voff)[_i]), (PG8_LAS unsigned*)(lds + (bufoff) + ldsw + _i * 8192), 16, 0, 0); } while (0)
; #define PG8_LDA(dst, b, h) do { _Pragma("unroll") for (int m = 0; m < 4; ++m) _Pragma("unroll") for (int k = 0; k < 2; ++k) dst[m][k] = *(const PG8_LAS bf16x8*)(lds + PG8_SA(b, h) + aoff + m * 2048 + k * 1024); } while (0)
; #define PG8_LDB(dst, b, h) do { _Pragma("unroll") for (int n = 0; n < 2; ++n) _Pragma("unroll") for (int k = 0; k < 2; ++k) dst[n][k] = *(const PG8_LAS bf16x8*)(lds + PG8_SB(b, h) + boff + n * 2048 + k * 1024); } while (0)
; #define PG8_MMA(ai, bj, At, Bt) do { __builtin_amdgcn_s_setprio(1); _Pragma("unroll") for (int m = 0; m < 4; ++m) _Pragma("unroll") for (int n = 0; n < 2; ++n) _Pragma("unroll") for (int k = 0; k < 2; ++k) \
;         acc[ai][bj][m][n] = __builtin_amdgcn_mfma_f32_16x16x32_bf16(Bt[n][k], At[m][k], acc[ai][bj][m][n], 0, 0, 0); __builtin_amdgcn_s_setprio(0); } while (0)
; template <class Epi, class Sched, bool ALIGN_EPI = false, bool SP2 = false>
; __device__ __forceinline__ void gemm_phase(PG8_LAS unsigned char* lds, const Gemm g, const Sched& S, const Epi& E, int wid0) {
;     ...
;         for (int t = 0; t < nt; t += 2) {
;             const bool last = (t == nt - 2);
;             const char* a1 = cA + (size_t)(t + 1) * kstep;
;             const char* a2 = last ? nA : cA + (size_t)(t + 2) * kstep; const char* b2 = last ? nB : cB + (size_t)(t + 2) * kstep;
;             const char* a3 = a2 + kstep; const char* b3 = b2 + kstep;
;             if (last && has_next) S.a_ready(nxt);
;             if constexpr (Epi::HAS_MID) { if (t == Epi::MID_T) E.mid(acc, cur, wr, fr); }
;             unsigned vA_[2] = {voffA[0], voffA[1]}, vB_[2] = {voffB[0], voffB[1]};
;             asm volatile("" : "+v"(vA_[0]), "+v"(vA_[1]), "+v"(vB_[0]), "+v"(vB_[1]));
;             if constexpr (SP2) {
;             PG8_LDB(B0, 0, 0); PG8_LDB(B1, 0, 1); PG8_SCHED; PG8_LDA(At, 0, 0); PG8_STAGE(PG8_SA(1, 1), a1 + hstepA, vA_);
;             PG8_WAIT_V(8); PG8_WAIT_L(0); PG8_BAR; PG8_MMA(0, 0, At, B0); PG8_MMA(0, 1, At, B1); PG8_BAR; PG8_SCHED;
.LBB13_358:
	v_mov_b32_e32 v8, v174
	v_mov_b32_e32 v220, v200
	v_mov_b32_e32 v221, v176
	v_mov_b32_e32 v222, v178
	ds_read_b128 v[82:85], v201
	ds_read_b128 v[90:93], v201 offset:1024
	ds_read_b128 v[94:97], v201 offset:2048
	ds_read_b128 v[102:105], v201 offset:3072
	ds_read_b128 v[158:161], v202
	ds_read_b128 v[162:165], v202 offset:1024
	ds_read_b128 v[166:169], v202 offset:2048
	ds_read_b128 v[170:173], v202 offset:3072
	s_add_u32 s8, s2, 0x100
	s_addc_u32 s9, s3, 0
	s_cmp_eq_u32 s82, 12
	s_cselect_b32 s58, s78, s8
	s_cselect_b32 s59, s47, s9
	s_cselect_b32 s12, s79, s80
	s_cselect_b32 s13, s49, s81
	s_add_u32 s10, s58, 0x80
	s_addc_u32 s11, s59, 0
	s_add_u32 s2, s2, 0x40080
	s_addc_u32 s3, s3, 0
	s_add_i32 m0, s57, 0xc000
	ds_read_b128 v[180:183], v203
	ds_read_b128 v[184:187], v203 offset:1024
	ds_read_b128 v[188:191], v203 offset:2048
	ds_read_b128 v[192:195], v203 offset:3072
	ds_read_b128 v[204:207], v203 offset:4096
	ds_read_b128 v[208:211], v203 offset:5120
	ds_read_b128 v[212:215], v203 offset:6144
	ds_read_b128 v[216:219], v203 offset:7168
	s_nop 0
	global_load_lds_dwordx4 v8, s[2:3]
	s_add_i32 m0, s57, 0xe000
	s_nop 0
	global_load_lds_dwordx4 v221, s[2:3]
	s_cmp_lg_u32 s82, -2
	s_cbranch_scc1 .LinA_w8_0
	s_cmp_eq_u32 s77, 0
	s_cbranch_scc1 .LinA_w8_0
	s_waitcnt vmcnt(24)
	s_branch .LinA_wd_0

; #define PG8_STAGE(bufoff, gbase, voff) do { const char* gb_ = (const char*)(gbase); asm volatile("" : "+s"(gb_));     \
;         _Pragma("unroll") for (int _i = 0; _i < 2; ++_i) \
;         __builtin_amdgcn_global_load_lds((const unsigned*)(gb_ + (voff)[_i]), (PG8_LAS unsigned*)(lds + (bufoff) + ldsw + _i * 8192), 16, 0, 0); } while (0)
; #define PG8_LDA(dst, b, h) do { _Pragma("unroll") for (int m = 0; m < 4; ++m) _Pragma("unroll") for (int k = 0; k < 2; ++k) dst[m][k] = *(const PG8_LAS bf16x8*)(lds + PG8_SA(b, h) + aoff + m * 2048 + k * 1024); } while (0)
; #define PG8_MMA(ai, bj, At, Bt) do { __builtin_amdgcn_s_setprio(1); _Pragma("unroll") for (int m = 0; m < 4; ++m) _Pragma("unroll") for (int n = 0; n < 2; ++n) _Pragma("unroll") for (int k = 0; k < 2; ++k) \
;         acc[ai][bj][m][n] = __builtin_amdgcn_mfma_f32_16x16x32_bf16(Bt[n][k], At[m][k], acc[ai][bj][m][n], 0, 0, 0); __builtin_amdgcn_s_setprio(0); } while (0)
; #define PG8_WAIT_V(n) asm volatile("s_waitcnt vmcnt(" #n ")" ::: "memory")
; #define PG8_WAIT_L(n) asm volatile("s_waitcnt lgkmcnt(" #n ")" ::: "memory")
; #define PG8_BAR __builtin_amdgcn_s_barrier()
; #define PG8_SCHED __builtin_amdgcn_sched_barrier(0)
; template <class Epi, class Sched, bool ALIGN_EPI = false, bool SP2 = false>
; __device__ __forceinline__ void gemm_phase(PG8_LAS unsigned char* lds, const Gemm g, const Sched& S, const Epi& E, int wid0) {
;     ...
;             PG8_WAIT_V(8); PG8_WAIT_L(0); PG8_BAR; PG8_MMA(0, 0, At, B0); PG8_MMA(0, 1, At, B1); PG8_BAR; PG8_SCHED;
;             PG8_LDA(At, 0, 1); PG8_STAGE(PG8_SB(0, 0), b2, vB_); PG8_STAGE(PG8_SB(0, 1), b2 + hstep, vB_); PG8_STAGE(PG8_SA(0, 0), a2, vA_);
;             PG8_WAIT_V(8); PG8_WAIT_L(0); PG8_BAR; PG8_MMA(1, 0, At, B0); PG8_MMA(1, 1, At, B1); PG8_BAR; PG8_SCHED;
.LinA_wd_0:
	s_waitcnt lgkmcnt(0)
	s_barrier
	s_setprio 1
	s_waitcnt lgkmcnt(0)
	v_mfma_f32_16x16x32_bf16 v[154:157], v[82:85], v[180:183], v[154:157]
	v_mfma_f32_16x16x32_bf16 v[150:153], v[94:97], v[180:183], v[150:153]
	v_mfma_f32_16x16x32_bf16 v[138:141], v[82:85], v[188:191], v[138:141]
	v_mfma_f32_16x16x32_bf16 v[134:137], v[94:97], v[188:191], v[134:137]
	v_mfma_f32_16x16x32_bf16 v[122:125], v[82:85], v[204:207], v[122:125]
	v_mfma_f32_16x16x32_bf16 v[118:121], v[94:97], v[204:207], v[118:121]
	v_mfma_f32_16x16x32_bf16 v[106:109], v[82:85], v[212:215], v[106:109]
	v_mfma_f32_16x16x32_bf16 v[98:101], v[94:97], v[212:215], v[98:101]
	v_mfma_f32_16x16x32_bf16 v[154:157], v[90:93], v[184:187], v[154:157]
	v_mfma_f32_16x16x32_bf16 v[150:153], v[102:105], v[184:187], v[150:153]
	v_mfma_f32_16x16x32_bf16 v[138:141], v[90:93], v[192:195], v[138:141]
	v_mfma_f32_16x16x32_bf16 v[134:137], v[102:105], v[192:195], v[134:137]
	v_mfma_f32_16x16x32_bf16 v[122:125], v[90:93], v[208:211], v[122:125]
	v_mfma_f32_16x16x32_bf16 v[118:121], v[102:105], v[208:211], v[118:121]
	v_mfma_f32_16x16x32_bf16 v[106:109], v[90:93], v[216:219], v[106:109]
	v_mfma_f32_16x16x32_bf16 v[98:101], v[102:105], v[216:219], v[98:101]
	s_setprio 0
	s_setprio 1
	v_mfma_f32_16x16x32_bf16 v[146:149], v[158:161], v[180:183], v[146:149]
	v_mfma_f32_16x16x32_bf16 v[142:145], v[166:169], v[180:183], v[142:145]
	v_mfma_f32_16x16x32_bf16 v[130:133], v[158:161], v[188:191], v[130:133]
	v_mfma_f32_16x16x32_bf16 v[126:129], v[166:169], v[188:191], v[126:129]
	v_mfma_f32_16x16x32_bf16 v[114:117], v[158:161], v[204:207], v[114:117]
	v_mfma_f32_16x16x32_bf16 v[110:113], v[166:169], v[204:207], v[110:113]
	v_mfma_f32_16x16x32_bf16 v[86:89], v[158:161], v[212:215], v[86:89]
	v_mfma_f32_16x16x32_bf16 v[78:81], v[166:169], v[212:215], v[78:81]
	v_mfma_f32_16x16x32_bf16 v[146:149], v[162:165], v[184:187], v[146:149]
	v_mfma_f32_16x16x32_bf16 v[142:145], v[170:173], v[184:187], v[142:145]
	v_mfma_f32_16x16x32_bf16 v[130:133], v[162:165], v[192:195], v[130:133]
	v_mfma_f32_16x16x32_bf16 v[126:129], v[170:173], v[192:195], v[126:129]
	v_mfma_f32_16x16x32_bf16 v[114:117], v[162:165], v[208:211], v[114:117]
	v_mfma_f32_16x16x32_bf16 v[110:113], v[170:173], v[208:211], v[110:113]
	v_mfma_f32_16x16x32_bf16 v[86:89], v[162:165], v[216:219], v[86:89]
	v_mfma_f32_16x16x32_bf16 v[78:81], v[170:173], v[216:219], v[78:81]
	s_setprio 0
	s_barrier
	s_add_i32 s83, s74, s55
	s_mov_b64 s[2:3], s[12:13]
	s_mov_b32 m0, s83
	ds_read_b128 v[180:183], v203 offset:16384
	ds_read_b128 v[184:187], v203 offset:17408
	ds_read_b128 v[188:191], v203 offset:18432
	ds_read_b128 v[192:195], v203 offset:19456
	ds_read_b128 v[204:207], v203 offset:20480
	ds_read_b128 v[208:211], v203 offset:21504
	ds_read_b128 v[212:215], v203 offset:22528
	ds_read_b128 v[216:219], v203 offset:23552
	s_nop 0
	global_load_lds_dwordx4 v220, s[2:3]
	s_add_i32 m0, s83, 0x2000
	s_nop 0
	global_load_lds_dwordx4 v222, s[2:3]
	s_add_u32 s2, s12, 0x40000
	s_addc_u32 s3, s13, 0
	s_add_i32 s83, s75, s55
	s_mov_b32 m0, s83
	s_nop 0
	global_load_lds_dwordx4 v220, s[2:3]
	s_add_i32 m0, s83, 0x2000
	s_nop 0
	global_load_lds_dwordx4 v222, s[2:3]
	s_mov_b64 s[2:3], s[58:59]
	s_mov_b32 m0, s57
	s_nop 0
	global_load_lds_dwordx4 v8, s[2:3]
	s_mov_b32 m0, s63
	s_nop 0
	global_load_lds_dwordx4 v221, s[2:3]
	s_cmp_lg_u32 s82, -2
	s_cbranch_scc1 .LinA_w8_1
	s_cmp_eq_u32 s77, 0
	s_cbranch_scc1 .LinA_w8_1
	s_waitcnt vmcnt(24)
	s_branch .LinA_wd_1

; #define PG8_STAGE(bufoff, gbase, voff) do { const char* gb_ = (const char*)(gbase); asm volatile("" : "+s"(gb_));     \
;         _Pragma("unroll") for (int _i = 0; _i < 2; ++_i) \
;         __builtin_amdgcn_global_load_lds((const unsigned*)(gb_ + (voff)[_i]), (PG8_LAS unsigned*)(lds + (bufoff) + ldsw + _i * 8192), 16, 0, 0); } while (0)
; #define PG8_LDA(dst, b, h) do { _Pragma("unroll") for (int m = 0; m < 4; ++m) _Pragma("unroll") for (int k = 0; k < 2; ++k) dst[m][k] = *(const PG8_LAS bf16x8*)(lds + PG8_SA(b, h) + aoff + m * 2048 + k * 1024); } while (0)
; #define PG8_LDB(dst, b, h) do { _Pragma("unroll") for (int n = 0; n < 2; ++n) _Pragma("unroll") for (int k = 0; k < 2; ++k) dst[n][k] = *(const PG8_LAS bf16x8*)(lds + PG8_SB(b, h) + boff + n * 2048 + k * 1024); } while (0)
; #define PG8_MMA(ai, bj, At, Bt) do { __builtin_amdgcn_s_setprio(1); _Pragma("unroll") for (int m = 0; m < 4; ++m) _Pragma("unroll") for (int n = 0; n < 2; ++n) _Pragma("unroll") for (int k = 0; k < 2; ++k) \
;         acc[ai][bj][m][n] = __builtin_amdgcn_mfma_f32_16x16x32_bf16(Bt[n][k], At[m][k], acc[ai][bj][m][n], 0, 0, 0); __builtin_amdgcn_s_setprio(0); } while (0)
; #define PG8_WAIT_V(n) asm volatile("s_waitcnt vmcnt(" #n ")" ::: "memory")
; #define PG8_WAIT_L(n) asm volatile("s_waitcnt lgkmcnt(" #n ")" ::: "memory")
; #define PG8_BAR __builtin_amdgcn_s_barrier()
; #define PG8_SCHED __builtin_amdgcn_sched_barrier(0)
; template <class Epi, class Sched, bool ALIGN_EPI = false, bool SP2 = false>
; __device__ __forceinline__ void gemm_phase(PG8_LAS unsigned char* lds, const Gemm g, const Sched& S, const Epi& E, int wid0) {
;     ...
;             PG8_WAIT_V(8); PG8_WAIT_L(0); PG8_BAR; PG8_MMA(1, 0, At, B0); PG8_MMA(1, 1, At, B1); PG8_BAR; PG8_SCHED;
;             PG8_LDB(B0, 1, 0); PG8_LDB(B1, 1, 1); PG8_SCHED; PG8_LDA(At, 1, 0); PG8_STAGE(PG8_SA(0, 1), a2 + hstepA, vA_);
;             PG8_WAIT_V(8); PG8_WAIT_L(0); PG8_BAR; PG8_MMA(0, 0, At, B0); PG8_MMA(0, 1, At, B1); PG8_BAR; PG8_SCHED;
.LinA_wd_1:
	s_waitcnt lgkmcnt(0)
	s_barrier
	s_setprio 1
	s_waitcnt lgkmcnt(0)
	v_mfma_f32_16x16x32_bf16 v[74:77], v[82:85], v[180:183], v[74:77]
	v_mfma_f32_16x16x32_bf16 v[70:73], v[94:97], v[180:183], v[70:73]
	v_mfma_f32_16x16x32_bf16 v[58:61], v[82:85], v[188:191], v[58:61]
	v_mfma_f32_16x16x32_bf16 v[54:57], v[94:97], v[188:191], v[54:57]
	v_mfma_f32_16x16x32_bf16 v[42:45], v[82:85], v[204:207], v[42:45]
	v_mfma_f32_16x16x32_bf16 v[38:41], v[94:97], v[204:207], v[38:41]
	v_mfma_f32_16x16x32_bf16 v[26:29], v[82:85], v[212:215], v[26:29]
	v_mfma_f32_16x16x32_bf16 v[22:25], v[94:97], v[212:215], v[22:25]
	v_mfma_f32_16x16x32_bf16 v[74:77], v[90:93], v[184:187], v[74:77]
	v_mfma_f32_16x16x32_bf16 v[70:73], v[102:105], v[184:187], v[70:73]
	v_mfma_f32_16x16x32_bf16 v[58:61], v[90:93], v[192:195], v[58:61]
	v_mfma_f32_16x16x32_bf16 v[54:57], v[102:105], v[192:195], v[54:57]
	v_mfma_f32_16x16x32_bf16 v[42:45], v[90:93], v[208:211], v[42:45]
	v_mfma_f32_16x16x32_bf16 v[38:41], v[102:105], v[208:211], v[38:41]
	v_mfma_f32_16x16x32_bf16 v[26:29], v[90:93], v[216:219], v[26:29]
	v_mfma_f32_16x16x32_bf16 v[22:25], v[102:105], v[216:219], v[22:25]
	s_setprio 0
	s_setprio 1
	v_mfma_f32_16x16x32_bf16 v[66:69], v[158:161], v[180:183], v[66:69]
	v_mfma_f32_16x16x32_bf16 v[62:65], v[166:169], v[180:183], v[62:65]
	v_mfma_f32_16x16x32_bf16 v[50:53], v[158:161], v[188:191], v[50:53]
	v_mfma_f32_16x16x32_bf16 v[46:49], v[166:169], v[188:191], v[46:49]
	v_mfma_f32_16x16x32_bf16 v[34:37], v[158:161], v[204:207], v[34:37]
	v_mfma_f32_16x16x32_bf16 v[30:33], v[166:169], v[204:207], v[30:33]
	v_mfma_f32_16x16x32_bf16 v[18:21], v[158:161], v[212:215], v[18:21]
	v_mfma_f32_16x16x32_bf16 v[14:17], v[166:169], v[212:215], v[14:17]
	v_mfma_f32_16x16x32_bf16 v[66:69], v[162:165], v[184:187], v[66:69]
	v_mfma_f32_16x16x32_bf16 v[62:65], v[170:173], v[184:187], v[62:65]
	v_mfma_f32_16x16x32_bf16 v[50:53], v[162:165], v[192:195], v[50:53]
	v_mfma_f32_16x16x32_bf16 v[46:49], v[170:173], v[192:195], v[46:49]
	v_mfma_f32_16x16x32_bf16 v[34:37], v[162:165], v[208:211], v[34:37]
	v_mfma_f32_16x16x32_bf16 v[30:33], v[170:173], v[208:211], v[30:33]
	v_mfma_f32_16x16x32_bf16 v[18:21], v[162:165], v[216:219], v[18:21]
	v_mfma_f32_16x16x32_bf16 v[14:17], v[170:173], v[216:219], v[14:17]
	s_setprio 0
	s_barrier
	s_add_i32 s83, 0, 0x18000
	s_add_i32 s84, 0, 0x1c000
	v_add_u32_e32 v102, s83, v175
	v_add_u32_e32 v170, s84, v175
	ds_read_b128 v[82:85], v102
	ds_read_b128 v[90:93], v102 offset:1024
	ds_read_b128 v[94:97], v102 offset:2048
	ds_read_b128 v[102:105], v102 offset:3072
	ds_read_b128 v[158:161], v170
	ds_read_b128 v[162:165], v170 offset:1024
	ds_read_b128 v[166:169], v170 offset:2048
	ds_read_b128 v[170:173], v170 offset:3072
	s_add_u32 s2, s58, 0x40000
	s_addc_u32 s3, s59, 0
	s_mov_b32 m0, s64
	ds_read_b128 v[180:183], v203 offset:32768
	ds_read_b128 v[184:187], v203 offset:33792
	ds_read_b128 v[188:191], v203 offset:34816
	ds_read_b128 v[192:195], v203 offset:35840
	ds_read_b128 v[204:207], v203 offset:36864
	ds_read_b128 v[208:211], v203 offset:37888
	ds_read_b128 v[212:215], v203 offset:38912
	ds_read_b128 v[216:219], v203 offset:39936
	s_nop 0
	global_load_lds_dwordx4 v8, s[2:3]
	s_mov_b32 m0, s65
	s_nop 0
	global_load_lds_dwordx4 v221, s[2:3]
	s_waitcnt vmcnt(8)
	s_waitcnt lgkmcnt(0)
	s_barrier
	s_setprio 1
	s_waitcnt lgkmcnt(0)
	v_mfma_f32_16x16x32_bf16 v[154:157], v[82:85], v[180:183], v[154:157]
	v_mfma_f32_16x16x32_bf16 v[150:153], v[94:97], v[180:183], v[150:153]
	v_mfma_f32_16x16x32_bf16 v[138:141], v[82:85], v[188:191], v[138:141]
	v_mfma_f32_16x16x32_bf16 v[134:137], v[94:97], v[188:191], v[134:137]
	v_mfma_f32_16x16x32_bf16 v[122:125], v[82:85], v[204:207], v[122:125]
	v_mfma_f32_16x16x32_bf16 v[118:121], v[94:97], v[204:207], v[118:121]
	v_mfma_f32_16x16x32_bf16 v[106:109], v[82:85], v[212:215], v[106:109]
	v_mfma_f32_16x16x32_bf16 v[98:101], v[94:97], v[212:215], v[98:101]
	v_mfma_f32_16x16x32_bf16 v[154:157], v[90:93], v[184:187], v[154:157]
	v_mfma_f32_16x16x32_bf16 v[150:153], v[102:105], v[184:187], v[150:153]
	v_mfma_f32_16x16x32_bf16 v[138:141], v[90:93], v[192:195], v[138:141]
	v_mfma_f32_16x16x32_bf16 v[134:137], v[102:105], v[192:195], v[134:137]
	v_mfma_f32_16x16x32_bf16 v[122:125], v[90:93], v[208:211], v[122:125]
	v_mfma_f32_16x16x32_bf16 v[118:121], v[102:105], v[208:211], v[118:121]
	v_mfma_f32_16x16x32_bf16 v[106:109], v[90:93], v[216:219], v[106:109]
	v_mfma_f32_16x16x32_bf16 v[98:101], v[102:105], v[216:219], v[98:101]
	s_setprio 0
	s_setprio 1
	v_mfma_f32_16x16x32_bf16 v[146:149], v[158:161], v[180:183], v[146:149]
	v_mfma_f32_16x16x32_bf16 v[142:145], v[166:169], v[180:183], v[142:145]
	v_mfma_f32_16x16x32_bf16 v[130:133], v[158:161], v[188:191], v[130:133]
	v_mfma_f32_16x16x32_bf16 v[126:129], v[166:169], v[188:191], v[126:129]
	v_mfma_f32_16x16x32_bf16 v[114:117], v[158:161], v[204:207], v[114:117]
	v_mfma_f32_16x16x32_bf16 v[110:113], v[166:169], v[204:207], v[110:113]
	v_mfma_f32_16x16x32_bf16 v[86:89], v[158:161], v[212:215], v[86:89]
	v_mfma_f32_16x16x32_bf16 v[78:81], v[166:169], v[212:215], v[78:81]
	v_mfma_f32_16x16x32_bf16 v[146:149], v[162:165], v[184:187], v[146:149]
	v_mfma_f32_16x16x32_bf16 v[142:145], v[170:173], v[184:187], v[142:145]
	v_mfma_f32_16x16x32_bf16 v[130:133], v[162:165], v[192:195], v[130:133]
	v_mfma_f32_16x16x32_bf16 v[126:129], v[170:173], v[192:195], v[126:129]
	v_mfma_f32_16x16x32_bf16 v[114:117], v[162:165], v[208:211], v[114:117]
	v_mfma_f32_16x16x32_bf16 v[110:113], v[170:173], v[208:211], v[110:113]
	v_mfma_f32_16x16x32_bf16 v[86:89], v[162:165], v[216:219], v[86:89]
	v_mfma_f32_16x16x32_bf16 v[78:81], v[170:173], v[216:219], v[78:81]
	s_setprio 0
	s_barrier
; #define PG8_STAGE(bufoff, gbase, voff) do { const char* gb_ = (const char*)(gbase); asm volatile("" : "+s"(gb_));     \
;         _Pragma("unroll") for (int _i = 0; _i < 2; ++_i) \
;         __builtin_amdgcn_global_load_lds((const unsigned*)(gb_ + (voff)[_i]), (PG8_LAS unsigned*)(lds + (bufoff) + ldsw + _i * 8192), 16, 0, 0); } while (0)
; #define PG8_LDA(dst, b, h) do { _Pragma("unroll") for (int m = 0; m < 4; ++m) _Pragma("unroll") for (int k = 0; k < 2; ++k) dst[m][k] = *(const PG8_LAS bf16x8*)(lds + PG8_SA(b, h) + aoff + m * 2048 + k * 1024); } while (0)
; #define PG8_MMA(ai, bj, At, Bt) do { __builtin_amdgcn_s_setprio(1); _Pragma("unroll") for (int m = 0; m < 4; ++m) _Pragma("unroll") for (int n = 0; n < 2; ++n) _Pragma("unroll") for (int k = 0; k < 2; ++k) \
;         acc[ai][bj][m][n] = __builtin_amdgcn_mfma_f32_16x16x32_bf16(Bt[n][k], At[m][k], acc[ai][bj][m][n], 0, 0, 0); __builtin_amdgcn_s_setprio(0); } while (0)
; #define PG8_WAIT_V(n) asm volatile("s_waitcnt vmcnt(" #n ")" ::: "memory")
; #define PG8_WAIT_L(n) asm volatile("s_waitcnt lgkmcnt(" #n ")" ::: "memory")
; #define PG8_BAR __builtin_amdgcn_s_barrier()
; #define PG8_SCHED __builtin_amdgcn_sched_barrier(0)
; template <class Epi, class Sched, bool ALIGN_EPI = false, bool SP2 = false>
; __device__ __forceinline__ void gemm_phase(PG8_LAS unsigned char* lds, const Gemm g, const Sched& S, const Epi& E, int wid0) {
;     ...
;             PG8_LDA(At, 1, 1); PG8_STAGE(PG8_SB(1, 0), b3, vB_); PG8_STAGE(PG8_SB(1, 1), b3 + hstep, vB_); PG8_STAGE(PG8_SA(1, 0), a3, vA_);
;             PG8_WAIT_V(8); PG8_WAIT_L(0); PG8_BAR; PG8_MMA(1, 0, At, B0); PG8_MMA(1, 1, At, B1); PG8_BAR; PG8_SCHED;
	s_add_u32 s2, s12, 0x80
	s_addc_u32 s3, s13, 0
	s_add_i32 s58, s83, s55
	s_mov_b32 m0, s58
	ds_read_b128 v[180:183], v203 offset:49152
	ds_read_b128 v[184:187], v203 offset:50176
	ds_read_b128 v[188:191], v203 offset:51200
	ds_read_b128 v[192:195], v203 offset:52224
	ds_read_b128 v[204:207], v203 offset:53248
	ds_read_b128 v[208:211], v203 offset:54272
	ds_read_b128 v[212:215], v203 offset:55296
	ds_read_b128 v[216:219], v203 offset:56320
	s_nop 0
	global_load_lds_dwordx4 v220, s[2:3]
	s_add_i32 m0, s58, 0x2000
	s_nop 0
	global_load_lds_dwordx4 v222, s[2:3]
	s_add_u32 s2, s12, 0x40080
	s_addc_u32 s3, s13, 0
	s_add_i32 s12, s84, s55
	s_mov_b32 m0, s12
	s_nop 0
	global_load_lds_dwordx4 v220, s[2:3]
	s_add_i32 m0, s12, 0x2000
	s_nop 0
	global_load_lds_dwordx4 v222, s[2:3]
	s_mov_b32 m0, s68
	s_nop 0
	global_load_lds_dwordx4 v8, s[10:11]
	s_mov_b32 m0, s69
	s_nop 0
	global_load_lds_dwordx4 v221, s[10:11]
	s_waitcnt vmcnt(8)
	s_waitcnt lgkmcnt(0)
	s_barrier
	s_setprio 1
	s_waitcnt lgkmcnt(0)
	v_mfma_f32_16x16x32_bf16 v[74:77], v[82:85], v[180:183], v[74:77]
	v_mfma_f32_16x16x32_bf16 v[70:73], v[94:97], v[180:183], v[70:73]
	v_mfma_f32_16x16x32_bf16 v[58:61], v[82:85], v[188:191], v[58:61]
	v_mfma_f32_16x16x32_bf16 v[54:57], v[94:97], v[188:191], v[54:57]
	v_mfma_f32_16x16x32_bf16 v[42:45], v[82:85], v[204:207], v[42:45]
	v_mfma_f32_16x16x32_bf16 v[38:41], v[94:97], v[204:207], v[38:41]
	v_mfma_f32_16x16x32_bf16 v[26:29], v[82:85], v[212:215], v[26:29]
	v_mfma_f32_16x16x32_bf16 v[22:25], v[94:97], v[212:215], v[22:25]
	v_mfma_f32_16x16x32_bf16 v[74:77], v[90:93], v[184:187], v[74:77]
	v_mfma_f32_16x16x32_bf16 v[70:73], v[102:105], v[184:187], v[70:73]
	v_mfma_f32_16x16x32_bf16 v[58:61], v[90:93], v[192:195], v[58:61]
	v_mfma_f32_16x16x32_bf16 v[54:57], v[102:105], v[192:195], v[54:57]
	v_mfma_f32_16x16x32_bf16 v[42:45], v[90:93], v[208:211], v[42:45]
	v_mfma_f32_16x16x32_bf16 v[38:41], v[102:105], v[208:211], v[38:41]
	v_mfma_f32_16x16x32_bf16 v[26:29], v[90:93], v[216:219], v[26:29]
	v_mfma_f32_16x16x32_bf16 v[22:25], v[102:105], v[216:219], v[22:25]
	s_setprio 0
	s_setprio 1
	v_mfma_f32_16x16x32_bf16 v[66:69], v[158:161], v[180:183], v[66:69]
	v_mfma_f32_16x16x32_bf16 v[62:65], v[166:169], v[180:183], v[62:65]
	v_mfma_f32_16x16x32_bf16 v[50:53], v[158:161], v[188:191], v[50:53]
	v_mfma_f32_16x16x32_bf16 v[46:49], v[166:169], v[188:191], v[46:49]
	v_mfma_f32_16x16x32_bf16 v[34:37], v[158:161], v[204:207], v[34:37]
	v_mfma_f32_16x16x32_bf16 v[30:33], v[166:169], v[204:207], v[30:33]
	v_mfma_f32_16x16x32_bf16 v[18:21], v[158:161], v[212:215], v[18:21]
	v_mfma_f32_16x16x32_bf16 v[14:17], v[166:169], v[212:215], v[14:17]
	v_mfma_f32_16x16x32_bf16 v[66:69], v[162:165], v[184:187], v[66:69]
	v_mfma_f32_16x16x32_bf16 v[62:65], v[170:173], v[184:187], v[62:65]
	v_mfma_f32_16x16x32_bf16 v[50:53], v[162:165], v[192:195], v[50:53]
	v_mfma_f32_16x16x32_bf16 v[46:49], v[170:173], v[192:195], v[46:49]
	v_mfma_f32_16x16x32_bf16 v[34:37], v[162:165], v[208:211], v[34:37]
	v_mfma_f32_16x16x32_bf16 v[30:33], v[170:173], v[208:211], v[30:33]
	v_mfma_f32_16x16x32_bf16 v[18:21], v[162:165], v[216:219], v[18:21]
	v_mfma_f32_16x16x32_bf16 v[14:17], v[170:173], v[216:219], v[14:17]
	s_setprio 0
	s_barrier
	s_add_i32 s82, s82, 2
	s_add_u32 s80, s80, 0x100
	s_addc_u32 s81, s81, 0
	s_cmp_gt_u32 s82, 13
	s_mov_b64 s[2:3], s[8:9]
	s_cbranch_scc0 .LBB13_358
	s_and_b64 vcc, exec, s[42:43]
	s_cbranch_vccz .LBB13_361
	s_barrier

; __device__ __forceinline__ float swz_xor1(float v) { return __int_as_float(__builtin_amdgcn_ds_swizzle(__float_as_int(v), 0x041F)); }
; #define PG8_LAS __attribute__((address_space(3)))
; __device__ __forceinline__ float hsum4(const f32x4& a) { return (a[0] + a[1]) + (a[2] + a[3]); }
;     __device__ __forceinline__ void pre_issue(const Unit& u, int tid, f32x4& q0, f32x4& q1, f32x4&) const {
;         const unsigned off = (unsigned)((u.pm * BM + (tid >> 1)) * 64 + (tid & 1) * 32); q0 = ldb<f32x4>(ssqy, off); q1 = ldb<f32x4>(ssqy, off + 16); }
;     __device__ __forceinline__ void pre_finish(PG8_LAS unsigned char* lds, const Unit& u, int tid, const f32x4& q0, const f32x4& q1, const f32x4&) const {
;         const float s = hsum4(q0) + hsum4(q1), o = swz_xor1(s); const bool odd = tid & 1; const float sg = odd ? o : s, sa = odd ? s : o;
;         if (!odd) { f32x2 r; r.x = sqrtf((sa * (1.f / 512) + EPS) / (sg * (1.f / 512) + EPS)); r.y = rsqrtf(sa * (1.f / 512) + EPS);
;             *(PG8_LAS f32x2*)(lds + RSTAT_OFF + (u.ui & 1) * 2048 + (tid >> 1) * 8) = r; } }
.LBB13_936:
	s_waitcnt vmcnt(16)
	v_add_f32_e32 v9, v4, v5
	v_add_f32_e32 v10, v6, v7
	v_add_f32_e32 v9, v9, v10
	v_add_f32_e32 v10, v0, v1
	v_add_f32_e32 v11, v2, v3
	v_add_f32_e32 v10, v10, v11
	v_add_f32_e32 v11, v9, v10
	ds_swizzle_b32 v10, v11 offset:swizzle(SWAP,1)
	s_and_saveexec_b64 s[6:7], s[4:5]
	s_xor_b64 s[6:7], exec, s[6:7]
	s_lshl_b32 s31, s29, 11
	s_and_b32 s31, s31, 0x800
	s_or_saveexec_b64 s[36:37], s[6:7]
	v_mov_b32_e32 v140, s31
	s_xor_b64 exec, exec, s[36:37]
	s_cbranch_execz .LBB13_940
	s_waitcnt lgkmcnt(0)
	v_pk_fma_f32 v[10:11], v[10:11], s[26:27], v[164:165] op_sel_hi:[1,0,0]
	s_nop 0
	v_div_scale_f32 v9, s[6:7], v11, v11, v10
	v_rcp_f32_e32 v12, v9
	v_div_scale_f32 v13, vcc, v10, v11, v10
	v_fma_f32 v14, -v9, v12, 1.0
	v_fmac_f32_e32 v12, v14, v12
	v_mul_f32_e32 v14, v13, v12
	v_fma_f32 v15, -v9, v14, v13
	v_fmac_f32_e32 v14, v15, v12
	v_fma_f32 v9, -v9, v14, v13
	v_div_fmas_f32 v9, v9, v12, v14
	v_div_fixup_f32 v9, v9, v11, v10
	v_mul_f32_e32 v11, 0x4f800000, v9
	v_cmp_gt_f32_e32 vcc, s62, v9
	s_nop 1
	v_cndmask_b32_e32 v9, v9, v11, vcc
	v_sqrt_f32_e32 v11, v9
	s_nop 0
	v_add_u32_e32 v12, -1, v11
	v_fma_f32 v13, -v12, v11, v9
	v_cmp_ge_f32_e64 s[6:7], 0, v13
	v_add_u32_e32 v13, 1, v11
	s_nop 0
	v_cndmask_b32_e64 v12, v11, v12, s[6:7]
	v_fma_f32 v11, -v13, v11, v9
	v_cmp_lt_f32_e64 s[6:7], 0, v11
	s_nop 1
	v_cndmask_b32_e64 v11, v12, v13, s[6:7]
	v_mul_f32_e32 v13, 0x4b800000, v10
	v_cmp_gt_f32_e64 s[6:7], s63, v10
	v_mul_f32_e32 v12, 0x37800000, v11
	s_nop 0
	v_cndmask_b32_e64 v10, v10, v13, s[6:7]
	v_rsq_f32_e32 v13, v10
	v_cndmask_b32_e32 v10, v11, v12, vcc
	v_cmp_class_f32_e32 vcc, v9, v163
	s_nop 1
	v_cndmask_b32_e32 v10, v10, v9, vcc
	v_mul_f32_e32 v9, 0x45800000, v13
	v_cndmask_b32_e64 v11, v13, v9, s[6:7]
	s_lshl_b32 s6, s29, 11
	s_and_b32 s6, s6, 0x800
	v_add_u32_e32 v9, s6, v159
	v_mov_b32_e32 v140, s6
	ds_write_b64 v9, v[10:11]

;     __device__ float mid(int row) const { return rg(row) / ra(row); }
; #define PG8_STAGE(bufoff, gbase, voff) do { const char* gb_ = (const char*)(gbase); asm volatile("" : "+s"(gb_));     \
;         _Pragma("unroll") for (int _i = 0; _i < 2; ++_i) \
;         __builtin_amdgcn_global_load_lds((const unsigned*)(gb_ + (voff)[_i]), (PG8_LAS unsigned*)(lds + (bufoff) + ldsw + _i * 8192), 16, 0, 0); } while (0)
; #define PG8_LDA(dst, b, h) do { _Pragma("unroll") for (int m = 0; m < 4; ++m) _Pragma("unroll") for (int k = 0; k < 2; ++k) dst[m][k] = *(const PG8_LAS bf16x8*)(lds + PG8_SA(b, h) + aoff + m * 2048 + k * 1024); } while (0)
; #define PG8_LDB(dst, b, h) do { _Pragma("unroll") for (int n = 0; n < 2; ++n) _Pragma("unroll") for (int k = 0; k < 2; ++k) dst[n][k] = *(const PG8_LAS bf16x8*)(lds + PG8_SB(b, h) + boff + n * 2048 + k * 1024); } while (0)
; #define PG8_MMA(ai, bj, At, Bt) do { __builtin_amdgcn_s_setprio(1); _Pragma("unroll") for (int m = 0; m < 4; ++m) _Pragma("unroll") for (int n = 0; n < 2; ++n) _Pragma("unroll") for (int k = 0; k < 2; ++k) \
;         acc[ai][bj][m][n] = __builtin_amdgcn_mfma_f32_16x16x32_bf16(Bt[n][k], At[m][k], acc[ai][bj][m][n], 0, 0, 0); __builtin_amdgcn_s_setprio(0); } while (0)
; template <class Epi, class Sched, bool ALIGN_EPI = false, bool SP2 = false>
; __device__ __forceinline__ void gemm_phase(PG8_LAS unsigned char* lds, const Gemm g, const Sched& S, const Epi& E, int wid0) {
;     ...
;         for (int t = 0; t < nt; t += 2) {
;             const bool last = (t == nt - 2);
;             const char* a1 = cA + (size_t)(t + 1) * kstep;
;             const char* a2 = last ? nA : cA + (size_t)(t + 2) * kstep; const char* b2 = last ? nB : cB + (size_t)(t + 2) * kstep;
;             const char* a3 = a2 + kstep; const char* b3 = b2 + kstep;
;             if (last && has_next) S.a_ready(nxt);
;             if constexpr (Epi::HAS_MID) { if (t == Epi::MID_T) E.mid(acc, cur, wr, fr); }
;             unsigned vA_[2] = {voffA[0], voffA[1]}, vB_[2] = {voffB[0], voffB[1]};
;             asm volatile("" : "+v"(vA_[0]), "+v"(vA_[1]), "+v"(vB_[0]), "+v"(vB_[1]));
;             if constexpr (SP2) {
;             PG8_LDB(B0, 0, 0); PG8_LDB(B1, 0, 1); PG8_SCHED; PG8_LDA(At, 0, 0); PG8_STAGE(PG8_SA(1, 1), a1 + hstepA, vA_);
;             PG8_WAIT_V(8); PG8_WAIT_L(0); PG8_BAR; PG8_MMA(0, 0, At, B0); PG8_MMA(0, 1, At, B1); PG8_BAR; PG8_SCHED;
.LBB13_942:
	v_mov_b32_e32 v9, v160
	v_mov_b32_e32 v154, v162
	v_mov_b32_e32 v155, v156
	v_mov_b32_e32 v166, v158
	v_add_u32_e32 v10, s64, v157
	ds_read_b128 v[142:145], v10
	ds_read_b128 v[146:149], v10 offset:1024
	ds_read_b128 v[150:153], v10 offset:2048
	ds_read_b128 v[168:171], v10 offset:3072
	v_add_u32_e32 v10, s65, v157
	s_add_u32 s6, s42, 0x100
	ds_read_b128 v[172:175], v10
	ds_read_b128 v[176:179], v10 offset:1024
	ds_read_b128 v[180:183], v10 offset:2048
	ds_read_b128 v[184:187], v10 offset:3072
	s_addc_u32 s7, s43, 0
	s_cmp_eq_u32 s70, 12
	s_cselect_b32 s50, s35, s6
	s_cselect_b32 s51, s29, s7
	s_cselect_b32 s45, s31, s69
	s_cselect_b32 s44, s67, s68
	s_add_u32 s46, s50, 0x80
	s_addc_u32 s47, s51, 0
	s_add_u32 s48, s44, 0x80
	s_addc_u32 s49, s45, 0
	s_add_u32 s42, s42, 0x80080
	s_addc_u32 s43, s43, 0
	s_add_i32 m0, s13, 0xc000
	ds_read_b128 v[188:191], v167
	ds_read_b128 v[192:195], v167 offset:1024
	ds_read_b128 v[196:199], v167 offset:2048
	ds_read_b128 v[200:203], v167 offset:3072
	ds_read_b128 v[204:207], v167 offset:4096
	ds_read_b128 v[208:211], v167 offset:5120
	ds_read_b128 v[212:215], v167 offset:6144
	ds_read_b128 v[216:219], v167 offset:7168
	s_nop 0
	global_load_lds_dwordx4 v155, s[42:43]
	s_add_i32 m0, s13, 0xe000
	s_nop 0
	global_load_lds_dwordx4 v9, s[42:43]
	s_cmp_lg_u32 s70, -2
	s_cbranch_scc1 .LoutA_w8_0
	s_cmp_eq_u32 s66, 1
	s_cbranch_scc1 .LoutA_w8_0
	s_waitcnt vmcnt(24)
	s_branch .LoutA_wd_0

; #define PG8_STAGE(bufoff, gbase, voff) do { const char* gb_ = (const char*)(gbase); asm volatile("" : "+s"(gb_));     \
;         _Pragma("unroll") for (int _i = 0; _i < 2; ++_i) \
;         __builtin_amdgcn_global_load_lds((const unsigned*)(gb_ + (voff)[_i]), (PG8_LAS unsigned*)(lds + (bufoff) + ldsw + _i * 8192), 16, 0, 0); } while (0)
; #define PG8_LDA(dst, b, h) do { _Pragma("unroll") for (int m = 0; m < 4; ++m) _Pragma("unroll") for (int k = 0; k < 2; ++k) dst[m][k] = *(const PG8_LAS bf16x8*)(lds + PG8_SA(b, h) + aoff + m * 2048 + k * 1024); } while (0)
; #define PG8_LDB(dst, b, h) do { _Pragma("unroll") for (int n = 0; n < 2; ++n) _Pragma("unroll") for (int k = 0; k < 2; ++k) dst[n][k] = *(const PG8_LAS bf16x8*)(lds + PG8_SB(b, h) + boff + n * 2048 + k * 1024); } while (0)
; #define PG8_MMA(ai, bj, At, Bt) do { __builtin_amdgcn_s_setprio(1); _Pragma("unroll") for (int m = 0; m < 4; ++m) _Pragma("unroll") for (int n = 0; n < 2; ++n) _Pragma("unroll") for (int k = 0; k < 2; ++k) \
;         acc[ai][bj][m][n] = __builtin_amdgcn_mfma_f32_16x16x32_bf16(Bt[n][k], At[m][k], acc[ai][bj][m][n], 0, 0, 0); __builtin_amdgcn_s_setprio(0); } while (0)
; #define PG8_WAIT_V(n) asm volatile("s_waitcnt vmcnt(" #n ")" ::: "memory")
; #define PG8_WAIT_L(n) asm volatile("s_waitcnt lgkmcnt(" #n ")" ::: "memory")
; #define PG8_BAR __builtin_amdgcn_s_barrier()
; #define PG8_SCHED __builtin_amdgcn_sched_barrier(0)
; template <class Epi, class Sched, bool ALIGN_EPI = false, bool SP2 = false>
; __device__ __forceinline__ void gemm_phase(PG8_LAS unsigned char* lds, const Gemm g, const Sched& S, const Epi& E, int wid0) {
;     ...
;             PG8_LDB(B0, 0, 0); PG8_LDB(B1, 0, 1); PG8_SCHED; PG8_LDA(At, 0, 0); PG8_STAGE(PG8_SA(1, 1), a1 + hstepA, vA_);
;             PG8_WAIT_V(8); PG8_WAIT_L(0); PG8_BAR; PG8_MMA(0, 0, At, B0); PG8_MMA(0, 1, At, B1); PG8_BAR; PG8_SCHED;
;             PG8_LDA(At, 0, 1); PG8_STAGE(PG8_SB(0, 0), b2, vB_); PG8_STAGE(PG8_SB(0, 1), b2 + hstep, vB_); PG8_STAGE(PG8_SA(0, 0), a2, vA_);
.LoutA_wd_0:
	s_waitcnt lgkmcnt(0)
	s_barrier
	s_setprio 1
	s_waitcnt lgkmcnt(0)
	v_mfma_f32_16x16x32_bf16 v[136:139], v[142:145], v[188:191], v[136:139]
	v_mfma_f32_16x16x32_bf16 v[132:135], v[150:153], v[188:191], v[132:135]
	v_mfma_f32_16x16x32_bf16 v[128:131], v[142:145], v[196:199], v[128:131]
	v_mfma_f32_16x16x32_bf16 v[124:127], v[150:153], v[196:199], v[124:127]
	v_mfma_f32_16x16x32_bf16 v[120:123], v[142:145], v[204:207], v[120:123]
	v_mfma_f32_16x16x32_bf16 v[116:119], v[150:153], v[204:207], v[116:119]
	v_mfma_f32_16x16x32_bf16 v[112:115], v[142:145], v[212:215], v[112:115]
	v_mfma_f32_16x16x32_bf16 v[108:111], v[150:153], v[212:215], v[108:111]
	v_mfma_f32_16x16x32_bf16 v[136:139], v[146:149], v[192:195], v[136:139]
	v_mfma_f32_16x16x32_bf16 v[132:135], v[168:171], v[192:195], v[132:135]
	v_mfma_f32_16x16x32_bf16 v[128:131], v[146:149], v[200:203], v[128:131]
	v_mfma_f32_16x16x32_bf16 v[124:127], v[168:171], v[200:203], v[124:127]
	v_mfma_f32_16x16x32_bf16 v[120:123], v[146:149], v[208:211], v[120:123]
	v_mfma_f32_16x16x32_bf16 v[116:119], v[168:171], v[208:211], v[116:119]
	v_mfma_f32_16x16x32_bf16 v[112:115], v[146:149], v[216:219], v[112:115]
	v_mfma_f32_16x16x32_bf16 v[108:111], v[168:171], v[216:219], v[108:111]
	s_setprio 0
	s_setprio 1
	v_mfma_f32_16x16x32_bf16 v[72:75], v[172:175], v[188:191], v[72:75]
	v_mfma_f32_16x16x32_bf16 v[68:71], v[180:183], v[188:191], v[68:71]
	v_mfma_f32_16x16x32_bf16 v[64:67], v[172:175], v[196:199], v[64:67]
	v_mfma_f32_16x16x32_bf16 v[60:63], v[180:183], v[196:199], v[60:63]
	v_mfma_f32_16x16x32_bf16 v[56:59], v[172:175], v[204:207], v[56:59]
	v_mfma_f32_16x16x32_bf16 v[52:55], v[180:183], v[204:207], v[52:55]
	v_mfma_f32_16x16x32_bf16 v[48:51], v[172:175], v[212:215], v[48:51]
	v_mfma_f32_16x16x32_bf16 v[44:47], v[180:183], v[212:215], v[44:47]
	v_mfma_f32_16x16x32_bf16 v[72:75], v[176:179], v[192:195], v[72:75]
	v_mfma_f32_16x16x32_bf16 v[68:71], v[184:187], v[192:195], v[68:71]
	v_mfma_f32_16x16x32_bf16 v[64:67], v[176:179], v[200:203], v[64:67]
	v_mfma_f32_16x16x32_bf16 v[60:63], v[184:187], v[200:203], v[60:63]
	v_mfma_f32_16x16x32_bf16 v[56:59], v[176:179], v[208:211], v[56:59]
	v_mfma_f32_16x16x32_bf16 v[52:55], v[184:187], v[208:211], v[52:55]
	v_mfma_f32_16x16x32_bf16 v[48:51], v[176:179], v[216:219], v[48:51]
	v_mfma_f32_16x16x32_bf16 v[44:47], v[184:187], v[216:219], v[44:47]
	s_setprio 0
	s_barrier
	s_add_i32 s71, s64, s27
	s_mov_b64 s[42:43], s[44:45]
	s_mov_b32 m0, s71
	ds_read_b128 v[188:191], v167 offset:16384
	ds_read_b128 v[192:195], v167 offset:17408
	ds_read_b128 v[196:199], v167 offset:18432
	ds_read_b128 v[200:203], v167 offset:19456
	ds_read_b128 v[204:207], v167 offset:20480
	ds_read_b128 v[208:211], v167 offset:21504
	ds_read_b128 v[212:215], v167 offset:22528
	ds_read_b128 v[216:219], v167 offset:23552
	s_nop 0
	global_load_lds_dwordx4 v166, s[42:43]
	s_add_i32 m0, s71, 0x2000
	s_nop 0
	global_load_lds_dwordx4 v154, s[42:43]
	s_add_u32 s42, s44, 0x40000
	s_addc_u32 s43, s45, 0
	s_add_i32 s71, s65, s27
	s_mov_b32 m0, s71
	s_nop 0
	global_load_lds_dwordx4 v166, s[42:43]
	s_add_i32 m0, s71, 0x2000
	s_nop 0
	global_load_lds_dwordx4 v154, s[42:43]
	s_mov_b64 s[42:43], s[50:51]
	s_mov_b32 m0, s13
	s_nop 0
	global_load_lds_dwordx4 v155, s[42:43]
	s_mov_b32 m0, s53
	s_nop 0
	global_load_lds_dwordx4 v9, s[42:43]
	s_cmp_lg_u32 s70, -2
	s_cbranch_scc1 .LoutA_w8_1
	s_cmp_eq_u32 s66, 1
	s_cbranch_scc1 .LoutA_w8_1
	s_waitcnt vmcnt(24)
	s_branch .LoutA_wd_1

; #define PG8_STAGE(bufoff, gbase, voff) do { const char* gb_ = (const char*)(gbase); asm volatile("" : "+s"(gb_));     \
;         _Pragma("unroll") for (int _i = 0; _i < 2; ++_i) \
;         __builtin_amdgcn_global_load_lds((const unsigned*)(gb_ + (voff)[_i]), (PG8_LAS unsigned*)(lds + (bufoff) + ldsw + _i * 8192), 16, 0, 0); } while (0)
; #define PG8_LDA(dst, b, h) do { _Pragma("unroll") for (int m = 0; m < 4; ++m) _Pragma("unroll") for (int k = 0; k < 2; ++k) dst[m][k] = *(const PG8_LAS bf16x8*)(lds + PG8_SA(b, h) + aoff + m * 2048 + k * 1024); } while (0)
; #define PG8_LDB(dst, b, h) do { _Pragma("unroll") for (int n = 0; n < 2; ++n) _Pragma("unroll") for (int k = 0; k < 2; ++k) dst[n][k] = *(const PG8_LAS bf16x8*)(lds + PG8_SB(b, h) + boff + n * 2048 + k * 1024); } while (0)
; #define PG8_MMA(ai, bj, At, Bt) do { __builtin_amdgcn_s_setprio(1); _Pragma("unroll") for (int m = 0; m < 4; ++m) _Pragma("unroll") for (int n = 0; n < 2; ++n) _Pragma("unroll") for (int k = 0; k < 2; ++k) \
;         acc[ai][bj][m][n] = __builtin_amdgcn_mfma_f32_16x16x32_bf16(Bt[n][k], At[m][k], acc[ai][bj][m][n], 0, 0, 0); __builtin_amdgcn_s_setprio(0); } while (0)
; #define PG8_WAIT_V(n) asm volatile("s_waitcnt vmcnt(" #n ")" ::: "memory")
; #define PG8_WAIT_L(n) asm volatile("s_waitcnt lgkmcnt(" #n ")" ::: "memory")
; #define PG8_BAR __builtin_amdgcn_s_barrier()
; #define PG8_SCHED __builtin_amdgcn_sched_barrier(0)
; template <class Epi, class Sched, bool ALIGN_EPI = false, bool SP2 = false>
; __device__ __forceinline__ void gemm_phase(PG8_LAS unsigned char* lds, const Gemm g, const Sched& S, const Epi& E, int wid0) {
;     ...
;             PG8_WAIT_V(8); PG8_WAIT_L(0); PG8_BAR; PG8_MMA(1, 0, At, B0); PG8_MMA(1, 1, At, B1); PG8_BAR; PG8_SCHED;
;             PG8_LDB(B0, 1, 0); PG8_LDB(B1, 1, 1); PG8_SCHED; PG8_LDA(At, 1, 0); PG8_STAGE(PG8_SA(0, 1), a2 + hstepA, vA_);
;             PG8_WAIT_V(8); PG8_WAIT_L(0); PG8_BAR; PG8_MMA(0, 0, At, B0); PG8_MMA(0, 1, At, B1); PG8_BAR; PG8_SCHED;
.LoutA_wd_1:
	s_waitcnt lgkmcnt(0)
	s_barrier
	s_setprio 1
	s_waitcnt lgkmcnt(0)
	v_mfma_f32_16x16x32_bf16 v[104:107], v[142:145], v[188:191], v[104:107]
	v_mfma_f32_16x16x32_bf16 v[100:103], v[150:153], v[188:191], v[100:103]
	v_mfma_f32_16x16x32_bf16 v[96:99], v[142:145], v[196:199], v[96:99]
	v_mfma_f32_16x16x32_bf16 v[92:95], v[150:153], v[196:199], v[92:95]
	v_mfma_f32_16x16x32_bf16 v[88:91], v[142:145], v[204:207], v[88:91]
	v_mfma_f32_16x16x32_bf16 v[84:87], v[150:153], v[204:207], v[84:87]
	v_mfma_f32_16x16x32_bf16 v[80:83], v[142:145], v[212:215], v[80:83]
	v_mfma_f32_16x16x32_bf16 v[76:79], v[150:153], v[212:215], v[76:79]
	v_mfma_f32_16x16x32_bf16 v[104:107], v[146:149], v[192:195], v[104:107]
	v_mfma_f32_16x16x32_bf16 v[100:103], v[168:171], v[192:195], v[100:103]
	v_mfma_f32_16x16x32_bf16 v[96:99], v[146:149], v[200:203], v[96:99]
	v_mfma_f32_16x16x32_bf16 v[92:95], v[168:171], v[200:203], v[92:95]
	v_mfma_f32_16x16x32_bf16 v[88:91], v[146:149], v[208:211], v[88:91]
	v_mfma_f32_16x16x32_bf16 v[84:87], v[168:171], v[208:211], v[84:87]
	v_mfma_f32_16x16x32_bf16 v[80:83], v[146:149], v[216:219], v[80:83]
	v_mfma_f32_16x16x32_bf16 v[76:79], v[168:171], v[216:219], v[76:79]
	s_setprio 0
	s_setprio 1
	v_mfma_f32_16x16x32_bf16 v[40:43], v[172:175], v[188:191], v[40:43]
	v_mfma_f32_16x16x32_bf16 v[36:39], v[180:183], v[188:191], v[36:39]
	v_mfma_f32_16x16x32_bf16 v[32:35], v[172:175], v[196:199], v[32:35]
	v_mfma_f32_16x16x32_bf16 v[28:31], v[180:183], v[196:199], v[28:31]
	v_mfma_f32_16x16x32_bf16 v[24:27], v[172:175], v[204:207], v[24:27]
	v_mfma_f32_16x16x32_bf16 v[20:23], v[180:183], v[204:207], v[20:23]
	v_mfma_f32_16x16x32_bf16 v[16:19], v[172:175], v[212:215], v[16:19]
	v_mfma_f32_16x16x32_bf16 v[10:13], v[180:183], v[212:215], v[12:15]
	v_mfma_f32_16x16x32_bf16 v[40:43], v[176:179], v[192:195], v[40:43]
	v_mfma_f32_16x16x32_bf16 v[36:39], v[184:187], v[192:195], v[36:39]
	v_mfma_f32_16x16x32_bf16 v[32:35], v[176:179], v[200:203], v[32:35]
	v_mfma_f32_16x16x32_bf16 v[28:31], v[184:187], v[200:203], v[28:31]
	v_mfma_f32_16x16x32_bf16 v[24:27], v[176:179], v[208:211], v[24:27]
	v_mfma_f32_16x16x32_bf16 v[20:23], v[184:187], v[208:211], v[20:23]
	v_mfma_f32_16x16x32_bf16 v[16:19], v[176:179], v[216:219], v[16:19]
	v_mfma_f32_16x16x32_bf16 v[10:13], v[184:187], v[216:219], v[10:13]
	s_setprio 0
	s_barrier
	s_add_i32 s71, 0, 0x18000
	v_add_u32_e32 v14, s71, v157
	s_add_i32 s72, 0, 0x1c000
	ds_read_b128 v[142:145], v14
	ds_read_b128 v[146:149], v14 offset:1024
	ds_read_b128 v[150:153], v14 offset:2048
	ds_read_b128 v[168:171], v14 offset:3072
	v_add_u32_e32 v14, s72, v157
	ds_read_b128 v[172:175], v14
	ds_read_b128 v[176:179], v14 offset:1024
	ds_read_b128 v[180:183], v14 offset:2048
	ds_read_b128 v[184:187], v14 offset:3072
	s_add_u32 s42, s50, 0x80000
	s_addc_u32 s43, s51, 0
	s_mov_b32 m0, s54
	ds_read_b128 v[188:191], v167 offset:32768
	ds_read_b128 v[192:195], v167 offset:33792
	ds_read_b128 v[196:199], v167 offset:34816
	ds_read_b128 v[200:203], v167 offset:35840
	ds_read_b128 v[204:207], v167 offset:36864
	ds_read_b128 v[208:211], v167 offset:37888
	ds_read_b128 v[212:215], v167 offset:38912
	ds_read_b128 v[216:219], v167 offset:39936
	s_nop 0
	global_load_lds_dwordx4 v155, s[42:43]
	s_mov_b32 m0, s55
	s_nop 0
	global_load_lds_dwordx4 v9, s[42:43]
	s_waitcnt vmcnt(8)
	s_waitcnt lgkmcnt(0)
	s_barrier
	s_setprio 1
	s_waitcnt lgkmcnt(0)
	v_mfma_f32_16x16x32_bf16 v[136:139], v[142:145], v[188:191], v[136:139]
	v_mfma_f32_16x16x32_bf16 v[132:135], v[150:153], v[188:191], v[132:135]
	v_mfma_f32_16x16x32_bf16 v[128:131], v[142:145], v[196:199], v[128:131]
	v_mfma_f32_16x16x32_bf16 v[124:127], v[150:153], v[196:199], v[124:127]
	v_mfma_f32_16x16x32_bf16 v[120:123], v[142:145], v[204:207], v[120:123]
	v_mfma_f32_16x16x32_bf16 v[116:119], v[150:153], v[204:207], v[116:119]
	v_mfma_f32_16x16x32_bf16 v[112:115], v[142:145], v[212:215], v[112:115]
	v_mfma_f32_16x16x32_bf16 v[108:111], v[150:153], v[212:215], v[108:111]
	v_mfma_f32_16x16x32_bf16 v[136:139], v[146:149], v[192:195], v[136:139]
	v_mfma_f32_16x16x32_bf16 v[132:135], v[168:171], v[192:195], v[132:135]
	v_mfma_f32_16x16x32_bf16 v[128:131], v[146:149], v[200:203], v[128:131]
	v_mfma_f32_16x16x32_bf16 v[124:127], v[168:171], v[200:203], v[124:127]
	v_mfma_f32_16x16x32_bf16 v[120:123], v[146:149], v[208:211], v[120:123]
	v_mfma_f32_16x16x32_bf16 v[116:119], v[168:171], v[208:211], v[116:119]
	v_mfma_f32_16x16x32_bf16 v[112:115], v[146:149], v[216:219], v[112:115]
	v_mfma_f32_16x16x32_bf16 v[108:111], v[168:171], v[216:219], v[108:111]
	s_setprio 0
	s_setprio 1
	v_mfma_f32_16x16x32_bf16 v[72:75], v[172:175], v[188:191], v[72:75]
	v_mfma_f32_16x16x32_bf16 v[68:71], v[180:183], v[188:191], v[68:71]
	v_mfma_f32_16x16x32_bf16 v[64:67], v[172:175], v[196:199], v[64:67]
	v_mfma_f32_16x16x32_bf16 v[60:63], v[180:183], v[196:199], v[60:63]
	v_mfma_f32_16x16x32_bf16 v[56:59], v[172:175], v[204:207], v[56:59]
	v_mfma_f32_16x16x32_bf16 v[52:55], v[180:183], v[204:207], v[52:55]
	v_mfma_f32_16x16x32_bf16 v[48:51], v[172:175], v[212:215], v[48:51]
	v_mfma_f32_16x16x32_bf16 v[44:47], v[180:183], v[212:215], v[44:47]
	v_mfma_f32_16x16x32_bf16 v[72:75], v[176:179], v[192:195], v[72:75]
	v_mfma_f32_16x16x32_bf16 v[68:71], v[184:187], v[192:195], v[68:71]
	v_mfma_f32_16x16x32_bf16 v[64:67], v[176:179], v[200:203], v[64:67]
	v_mfma_f32_16x16x32_bf16 v[60:63], v[184:187], v[200:203], v[60:63]
	v_mfma_f32_16x16x32_bf16 v[56:59], v[176:179], v[208:211], v[56:59]
	v_mfma_f32_16x16x32_bf16 v[52:55], v[184:187], v[208:211], v[52:55]
	v_mfma_f32_16x16x32_bf16 v[48:51], v[176:179], v[216:219], v[48:51]
	v_mfma_f32_16x16x32_bf16 v[44:47], v[184:187], v[216:219], v[44:47]
	s_setprio 0
	s_barrier
; #define PG8_STAGE(bufoff, gbase, voff) do { const char* gb_ = (const char*)(gbase); asm volatile("" : "+s"(gb_));     \
;         _Pragma("unroll") for (int _i = 0; _i < 2; ++_i) \
;         __builtin_amdgcn_global_load_lds((const unsigned*)(gb_ + (voff)[_i]), (PG8_LAS unsigned*)(lds + (bufoff) + ldsw + _i * 8192), 16, 0, 0); } while (0)
; #define PG8_LDA(dst, b, h) do { _Pragma("unroll") for (int m = 0; m < 4; ++m) _Pragma("unroll") for (int k = 0; k < 2; ++k) dst[m][k] = *(const PG8_LAS bf16x8*)(lds + PG8_SA(b, h) + aoff + m * 2048 + k * 1024); } while (0)
; #define PG8_MMA(ai, bj, At, Bt) do { __builtin_amdgcn_s_setprio(1); _Pragma("unroll") for (int m = 0; m < 4; ++m) _Pragma("unroll") for (int n = 0; n < 2; ++n) _Pragma("unroll") for (int k = 0; k < 2; ++k) \
;         acc[ai][bj][m][n] = __builtin_amdgcn_mfma_f32_16x16x32_bf16(Bt[n][k], At[m][k], acc[ai][bj][m][n], 0, 0, 0); __builtin_amdgcn_s_setprio(0); } while (0)
; #define PG8_WAIT_V(n) asm volatile("s_waitcnt vmcnt(" #n ")" ::: "memory")
; #define PG8_WAIT_L(n) asm volatile("s_waitcnt lgkmcnt(" #n ")" ::: "memory")
; #define PG8_BAR __builtin_amdgcn_s_barrier()
; #define PG8_SCHED __builtin_amdgcn_sched_barrier(0)
; template <class Epi, class Sched, bool ALIGN_EPI = false, bool SP2 = false>
; __device__ __forceinline__ void gemm_phase(PG8_LAS unsigned char* lds, const Gemm g, const Sched& S, const Epi& E, int wid0) {
;     ...
;         for (int t = 0; t < nt; t += 2) {
;     ...
;             PG8_LDA(At, 1, 1); PG8_STAGE(PG8_SB(1, 0), b3, vB_); PG8_STAGE(PG8_SB(1, 1), b3 + hstep, vB_); PG8_STAGE(PG8_SA(1, 0), a3, vA_);
;             PG8_WAIT_V(8); PG8_WAIT_L(0); PG8_BAR; PG8_MMA(1, 0, At, B0); PG8_MMA(1, 1, At, B1); PG8_BAR; PG8_SCHED;
	s_add_i32 s42, s71, s27
	s_mov_b32 m0, s42
	ds_read_b128 v[188:191], v167 offset:49152
	ds_read_b128 v[192:195], v167 offset:50176
	ds_read_b128 v[196:199], v167 offset:51200
	ds_read_b128 v[200:203], v167 offset:52224
	ds_read_b128 v[204:207], v167 offset:53248
	ds_read_b128 v[208:211], v167 offset:54272
	ds_read_b128 v[212:215], v167 offset:55296
	ds_read_b128 v[216:219], v167 offset:56320
	s_nop 0
	global_load_lds_dwordx4 v166, s[48:49]
	s_add_i32 m0, s42, 0x2000
	s_add_u32 s42, s44, 0x40080
	s_addc_u32 s43, s45, 0
	s_add_i32 s44, s72, s27
	global_load_lds_dwordx4 v154, s[48:49]
	s_mov_b32 m0, s44
	s_nop 0
	global_load_lds_dwordx4 v166, s[42:43]
	s_add_i32 m0, s44, 0x2000
	s_nop 0
	global_load_lds_dwordx4 v154, s[42:43]
	s_mov_b32 m0, s59
	s_nop 0
	global_load_lds_dwordx4 v155, s[46:47]
	s_mov_b32 m0, s60
	s_nop 0
	global_load_lds_dwordx4 v9, s[46:47]
	s_waitcnt vmcnt(8)
	s_waitcnt lgkmcnt(0)
	s_barrier
	s_setprio 1
	s_waitcnt lgkmcnt(0)
	v_mfma_f32_16x16x32_bf16 v[104:107], v[142:145], v[188:191], v[104:107]
	v_mfma_f32_16x16x32_bf16 v[100:103], v[150:153], v[188:191], v[100:103]
	v_mfma_f32_16x16x32_bf16 v[96:99], v[142:145], v[196:199], v[96:99]
	v_mfma_f32_16x16x32_bf16 v[92:95], v[150:153], v[196:199], v[92:95]
	v_mfma_f32_16x16x32_bf16 v[88:91], v[142:145], v[204:207], v[88:91]
	v_mfma_f32_16x16x32_bf16 v[84:87], v[150:153], v[204:207], v[84:87]
	v_mfma_f32_16x16x32_bf16 v[80:83], v[142:145], v[212:215], v[80:83]
	v_mfma_f32_16x16x32_bf16 v[76:79], v[150:153], v[212:215], v[76:79]
	v_mfma_f32_16x16x32_bf16 v[104:107], v[146:149], v[192:195], v[104:107]
	v_mfma_f32_16x16x32_bf16 v[100:103], v[168:171], v[192:195], v[100:103]
	v_mfma_f32_16x16x32_bf16 v[96:99], v[146:149], v[200:203], v[96:99]
	v_mfma_f32_16x16x32_bf16 v[92:95], v[168:171], v[200:203], v[92:95]
	v_mfma_f32_16x16x32_bf16 v[88:91], v[146:149], v[208:211], v[88:91]
	v_mfma_f32_16x16x32_bf16 v[84:87], v[168:171], v[208:211], v[84:87]
	v_mfma_f32_16x16x32_bf16 v[80:83], v[146:149], v[216:219], v[80:83]
	v_mfma_f32_16x16x32_bf16 v[76:79], v[168:171], v[216:219], v[76:79]
	s_setprio 0
	s_setprio 1
	v_mfma_f32_16x16x32_bf16 v[40:43], v[172:175], v[188:191], v[40:43]
	v_mfma_f32_16x16x32_bf16 v[36:39], v[180:183], v[188:191], v[36:39]
	v_mfma_f32_16x16x32_bf16 v[32:35], v[172:175], v[196:199], v[32:35]
	v_mfma_f32_16x16x32_bf16 v[28:31], v[180:183], v[196:199], v[28:31]
	v_mfma_f32_16x16x32_bf16 v[24:27], v[172:175], v[204:207], v[24:27]
	v_mfma_f32_16x16x32_bf16 v[20:23], v[180:183], v[204:207], v[20:23]
	v_mfma_f32_16x16x32_bf16 v[14:17], v[172:175], v[212:215], v[16:19]
	v_mfma_f32_16x16x32_bf16 v[10:13], v[180:183], v[212:215], v[10:13]
	v_mfma_f32_16x16x32_bf16 v[40:43], v[176:179], v[192:195], v[40:43]
	v_mfma_f32_16x16x32_bf16 v[36:39], v[184:187], v[192:195], v[36:39]
	v_mfma_f32_16x16x32_bf16 v[32:35], v[176:179], v[200:203], v[32:35]
	v_mfma_f32_16x16x32_bf16 v[28:31], v[184:187], v[200:203], v[28:31]
	v_mfma_f32_16x16x32_bf16 v[24:27], v[176:179], v[208:211], v[24:27]
	v_mfma_f32_16x16x32_bf16 v[20:23], v[184:187], v[208:211], v[20:23]
	v_mfma_f32_16x16x32_bf16 v[16:19], v[176:179], v[216:219], v[14:17]
	v_mfma_f32_16x16x32_bf16 v[12:15], v[184:187], v[216:219], v[10:13]
	s_setprio 0
	s_barrier
	s_add_i32 s70, s70, 2
	s_add_u32 s68, s68, 0x100
	s_addc_u32 s69, s69, 0
	s_cmp_gt_u32 s70, 13
	s_cbranch_scc1 .LBB13_944
	s_mov_b64 s[42:43], s[6:7]
	s_cmp_lg_u32 s70, 6
	s_cbranch_scc0 .LBB13_941
	s_branch .LBB13_942

;     __device__ float mid(int row) const { return rg(row) / ra(row); }
; #define PG8_STAGE(bufoff, gbase, voff) do { const char* gb_ = (const char*)(gbase); asm volatile("" : "+s"(gb_));     \
;         _Pragma("unroll") for (int _i = 0; _i < 2; ++_i) \
;         __builtin_amdgcn_global_load_lds((const unsigned*)(gb_ + (voff)[_i]), (PG8_LAS unsigned*)(lds + (bufoff) + ldsw + _i * 8192), 16, 0, 0); } while (0)
; #define PG8_LDA(dst, b, h) do { _Pragma("unroll") for (int m = 0; m < 4; ++m) _Pragma("unroll") for (int k = 0; k < 2; ++k) dst[m][k] = *(const PG8_LAS bf16x8*)(lds + PG8_SA(b, h) + aoff + m * 2048 + k * 1024); } while (0)
; #define PG8_LDB(dst, b, h) do { _Pragma("unroll") for (int n = 0; n < 2; ++n) _Pragma("unroll") for (int k = 0; k < 2; ++k) dst[n][k] = *(const PG8_LAS bf16x8*)(lds + PG8_SB(b, h) + boff + n * 2048 + k * 1024); } while (0)
; #define PG8_SCHED __builtin_amdgcn_sched_barrier(0)
; template <class Epi, class Sched, bool ALIGN_EPI = false, bool SP2 = false>
; __device__ __forceinline__ void gemm_phase(PG8_LAS unsigned char* lds, const Gemm g, const Sched& S, const Epi& E, int wid0) {
;     ...
;         for (int t = 0; t < nt; t += 2) {
;             const bool last = (t == nt - 2);
;             const char* a1 = cA + (size_t)(t + 1) * kstep;
;             const char* a2 = last ? nA : cA + (size_t)(t + 2) * kstep; const char* b2 = last ? nB : cB + (size_t)(t + 2) * kstep;
;             const char* a3 = a2 + kstep; const char* b3 = b2 + kstep;
;             if (last && has_next) S.a_ready(nxt);
;             if constexpr (Epi::HAS_MID) { if (t == Epi::MID_T) E.mid(acc, cur, wr, fr); }
;             unsigned vA_[2] = {voffA[0], voffA[1]}, vB_[2] = {voffB[0], voffB[1]};
;             asm volatile("" : "+v"(vA_[0]), "+v"(vA_[1]), "+v"(vB_[0]), "+v"(vB_[1]));
;             if constexpr (SP2) {
;             PG8_LDB(B0, 0, 0); PG8_LDB(B1, 0, 1); PG8_SCHED; PG8_LDA(At, 0, 0); PG8_STAGE(PG8_SA(1, 1), a1 + hstepA, vA_);
.LBB13_1187:
	v_mov_b32_e32 v181, v162
	v_mov_b32_e32 v202, v156
	v_mov_b32_e32 v203, v158
	v_mov_b32_e32 v204, v160
	ds_read_b128 v[128:131], v161
	ds_read_b128 v[132:135], v161 offset:1024
	ds_read_b128 v[136:139], v161 offset:2048
	ds_read_b128 v[140:143], v161 offset:3072
	ds_read_b128 v[144:147], v163
	ds_read_b128 v[148:151], v163 offset:1024
	ds_read_b128 v[152:155], v163 offset:2048
	ds_read_b128 v[164:167], v163 offset:3072
	s_add_u32 s34, s30, 0x100
	s_addc_u32 s35, s31, 0
	s_cmp_eq_u32 s60, 60
	s_cselect_b32 s40, s27, s34
	s_cselect_b32 s41, s17, s35
	s_cselect_b32 s38, s57, s58
	s_cselect_b32 s39, s19, s59
	s_add_u32 s36, s40, 0x80
	s_addc_u32 s37, s41, 0
	s_add_u32 s30, s30, 0x100080
	s_addc_u32 s31, s31, 0
	s_add_i32 m0, s29, 0xc000
	ds_read_b128 v[168:171], v180
	ds_read_b128 v[172:175], v180 offset:1024
	ds_read_b128 v[176:179], v180 offset:2048
	ds_read_b128 v[182:185], v180 offset:3072
	ds_read_b128 v[186:189], v180 offset:4096
	ds_read_b128 v[190:193], v180 offset:5120
	ds_read_b128 v[194:197], v180 offset:6144
	ds_read_b128 v[198:201], v180 offset:7168
	s_nop 0
	global_load_lds_dwordx4 v202, s[30:31]
	s_add_i32 m0, s29, 0xe000
	s_nop 0
	global_load_lds_dwordx4 v204, s[30:31]
	s_cmp_lg_u32 s60, -2
	s_cbranch_scc1 .Lff2A_w8_0
	s_cmp_eq_u32 s49, 1
	s_cbranch_scc1 .Lff2A_w8_0
	s_waitcnt vmcnt(32)
	s_branch .Lff2A_wd_0

; #define PG8_STAGE(bufoff, gbase, voff) do { const char* gb_ = (const char*)(gbase); asm volatile("" : "+s"(gb_));     \
;         _Pragma("unroll") for (int _i = 0; _i < 2; ++_i) \
;         __builtin_amdgcn_global_load_lds((const unsigned*)(gb_ + (voff)[_i]), (PG8_LAS unsigned*)(lds + (bufoff) + ldsw + _i * 8192), 16, 0, 0); } while (0)
; #define PG8_LDA(dst, b, h) do { _Pragma("unroll") for (int m = 0; m < 4; ++m) _Pragma("unroll") for (int k = 0; k < 2; ++k) dst[m][k] = *(const PG8_LAS bf16x8*)(lds + PG8_SA(b, h) + aoff + m * 2048 + k * 1024); } while (0)
; #define PG8_MMA(ai, bj, At, Bt) do { __builtin_amdgcn_s_setprio(1); _Pragma("unroll") for (int m = 0; m < 4; ++m) _Pragma("unroll") for (int n = 0; n < 2; ++n) _Pragma("unroll") for (int k = 0; k < 2; ++k) \
;         acc[ai][bj][m][n] = __builtin_amdgcn_mfma_f32_16x16x32_bf16(Bt[n][k], At[m][k], acc[ai][bj][m][n], 0, 0, 0); __builtin_amdgcn_s_setprio(0); } while (0)
; #define PG8_WAIT_V(n) asm volatile("s_waitcnt vmcnt(" #n ")" ::: "memory")
; #define PG8_WAIT_L(n) asm volatile("s_waitcnt lgkmcnt(" #n ")" ::: "memory")
; #define PG8_BAR __builtin_amdgcn_s_barrier()
; #define PG8_SCHED __builtin_amdgcn_sched_barrier(0)
; template <class Epi, class Sched, bool ALIGN_EPI = false, bool SP2 = false>
; __device__ __forceinline__ void gemm_phase(PG8_LAS unsigned char* lds, const Gemm g, const Sched& S, const Epi& E, int wid0) {
;     ...
;             PG8_WAIT_V(8); PG8_WAIT_L(0); PG8_BAR; PG8_MMA(0, 0, At, B0); PG8_MMA(0, 1, At, B1); PG8_BAR; PG8_SCHED;
;             PG8_LDA(At, 0, 1); PG8_STAGE(PG8_SB(0, 0), b2, vB_); PG8_STAGE(PG8_SB(0, 1), b2 + hstep, vB_); PG8_STAGE(PG8_SA(0, 0), a2, vA_);
.Lff2A_wd_0:
	s_waitcnt lgkmcnt(0)
	s_barrier
	s_setprio 1
	s_waitcnt lgkmcnt(0)
	v_mfma_f32_16x16x32_bf16 v[124:127], v[128:131], v[168:171], v[124:127]
	v_mfma_f32_16x16x32_bf16 v[120:123], v[136:139], v[168:171], v[120:123]
	v_mfma_f32_16x16x32_bf16 v[116:119], v[128:131], v[176:179], v[116:119]
	v_mfma_f32_16x16x32_bf16 v[112:115], v[136:139], v[176:179], v[112:115]
	v_mfma_f32_16x16x32_bf16 v[108:111], v[128:131], v[186:189], v[108:111]
	v_mfma_f32_16x16x32_bf16 v[104:107], v[136:139], v[186:189], v[104:107]
	v_mfma_f32_16x16x32_bf16 v[100:103], v[128:131], v[194:197], v[100:103]
	v_mfma_f32_16x16x32_bf16 v[96:99], v[136:139], v[194:197], v[96:99]
	v_mfma_f32_16x16x32_bf16 v[124:127], v[132:135], v[172:175], v[124:127]
	v_mfma_f32_16x16x32_bf16 v[120:123], v[140:143], v[172:175], v[120:123]
	v_mfma_f32_16x16x32_bf16 v[116:119], v[132:135], v[182:185], v[116:119]
	v_mfma_f32_16x16x32_bf16 v[112:115], v[140:143], v[182:185], v[112:115]
	v_mfma_f32_16x16x32_bf16 v[108:111], v[132:135], v[190:193], v[108:111]
	v_mfma_f32_16x16x32_bf16 v[104:107], v[140:143], v[190:193], v[104:107]
	v_mfma_f32_16x16x32_bf16 v[100:103], v[132:135], v[198:201], v[100:103]
	v_mfma_f32_16x16x32_bf16 v[96:99], v[140:143], v[198:201], v[96:99]
	s_setprio 0
	s_setprio 1
	v_mfma_f32_16x16x32_bf16 v[60:63], v[144:147], v[168:171], v[60:63]
	v_mfma_f32_16x16x32_bf16 v[56:59], v[152:155], v[168:171], v[56:59]
	v_mfma_f32_16x16x32_bf16 v[52:55], v[144:147], v[176:179], v[52:55]
	v_mfma_f32_16x16x32_bf16 v[48:51], v[152:155], v[176:179], v[48:51]
	v_mfma_f32_16x16x32_bf16 v[44:47], v[144:147], v[186:189], v[44:47]
	v_mfma_f32_16x16x32_bf16 v[40:43], v[152:155], v[186:189], v[40:43]
	v_mfma_f32_16x16x32_bf16 v[36:39], v[144:147], v[194:197], v[36:39]
	v_mfma_f32_16x16x32_bf16 v[32:35], v[152:155], v[194:197], v[32:35]
	v_mfma_f32_16x16x32_bf16 v[60:63], v[148:151], v[172:175], v[60:63]
	v_mfma_f32_16x16x32_bf16 v[56:59], v[164:167], v[172:175], v[56:59]
	v_mfma_f32_16x16x32_bf16 v[52:55], v[148:151], v[182:185], v[52:55]
	v_mfma_f32_16x16x32_bf16 v[48:51], v[164:167], v[182:185], v[48:51]
	v_mfma_f32_16x16x32_bf16 v[44:47], v[148:151], v[190:193], v[44:47]
	v_mfma_f32_16x16x32_bf16 v[40:43], v[164:167], v[190:193], v[40:43]
	v_mfma_f32_16x16x32_bf16 v[36:39], v[148:151], v[198:201], v[36:39]
	v_mfma_f32_16x16x32_bf16 v[32:35], v[164:167], v[198:201], v[32:35]
	s_setprio 0
	s_barrier
	s_add_i32 s61, s55, s33
	s_mov_b64 s[30:31], s[38:39]
	s_mov_b32 m0, s61
	ds_read_b128 v[168:171], v180 offset:16384
	ds_read_b128 v[172:175], v180 offset:17408
	ds_read_b128 v[176:179], v180 offset:18432
	ds_read_b128 v[182:185], v180 offset:19456
	ds_read_b128 v[186:189], v180 offset:20480
	ds_read_b128 v[190:193], v180 offset:21504
	ds_read_b128 v[194:197], v180 offset:22528
	ds_read_b128 v[198:201], v180 offset:23552
	s_nop 0
	global_load_lds_dwordx4 v203, s[30:31]
	s_add_i32 m0, s61, 0x2000
	s_nop 0
	global_load_lds_dwordx4 v181, s[30:31]
	s_add_u32 s30, s38, 0x100000
	s_addc_u32 s31, s39, 0
	s_add_i32 s61, s56, s33
	s_mov_b32 m0, s61
	s_nop 0
	global_load_lds_dwordx4 v203, s[30:31]
	s_add_i32 m0, s61, 0x2000
	s_nop 0
	global_load_lds_dwordx4 v181, s[30:31]
	s_mov_b64 s[30:31], s[40:41]
	s_mov_b32 m0, s29
	s_nop 0
	global_load_lds_dwordx4 v202, s[30:31]
	s_mov_b32 m0, s46
	s_nop 0
	global_load_lds_dwordx4 v204, s[30:31]
	s_cmp_lg_u32 s60, -2
	s_cbranch_scc1 .Lff2A_w8_1
	s_cmp_eq_u32 s49, 1
	s_cbranch_scc1 .Lff2A_w8_1
	s_waitcnt vmcnt(32)
	s_branch .Lff2A_wd_1

; #define PG8_STAGE(bufoff, gbase, voff) do { const char* gb_ = (const char*)(gbase); asm volatile("" : "+s"(gb_));     \
;         _Pragma("unroll") for (int _i = 0; _i < 2; ++_i) \
;         __builtin_amdgcn_global_load_lds((const unsigned*)(gb_ + (voff)[_i]), (PG8_LAS unsigned*)(lds + (bufoff) + ldsw + _i * 8192), 16, 0, 0); } while (0)
; #define PG8_LDA(dst, b, h) do { _Pragma("unroll") for (int m = 0; m < 4; ++m) _Pragma("unroll") for (int k = 0; k < 2; ++k) dst[m][k] = *(const PG8_LAS bf16x8*)(lds + PG8_SA(b, h) + aoff + m * 2048 + k * 1024); } while (0)
; #define PG8_LDB(dst, b, h) do { _Pragma("unroll") for (int n = 0; n < 2; ++n) _Pragma("unroll") for (int k = 0; k < 2; ++k) dst[n][k] = *(const PG8_LAS bf16x8*)(lds + PG8_SB(b, h) + boff + n * 2048 + k * 1024); } while (0)
; #define PG8_MMA(ai, bj, At, Bt) do { __builtin_amdgcn_s_setprio(1); _Pragma("unroll") for (int m = 0; m < 4; ++m) _Pragma("unroll") for (int n = 0; n < 2; ++n) _Pragma("unroll") for (int k = 0; k < 2; ++k) \
;         acc[ai][bj][m][n] = __builtin_amdgcn_mfma_f32_16x16x32_bf16(Bt[n][k], At[m][k], acc[ai][bj][m][n], 0, 0, 0); __builtin_amdgcn_s_setprio(0); } while (0)
; #define PG8_WAIT_V(n) asm volatile("s_waitcnt vmcnt(" #n ")" ::: "memory")
; #define PG8_WAIT_L(n) asm volatile("s_waitcnt lgkmcnt(" #n ")" ::: "memory")
; #define PG8_BAR __builtin_amdgcn_s_barrier()
; #define PG8_SCHED __builtin_amdgcn_sched_barrier(0)
; template <class Epi, class Sched, bool ALIGN_EPI = false, bool SP2 = false>
; __device__ __forceinline__ void gemm_phase(PG8_LAS unsigned char* lds, const Gemm g, const Sched& S, const Epi& E, int wid0) {
;     ...
;             PG8_WAIT_V(8); PG8_WAIT_L(0); PG8_BAR; PG8_MMA(1, 0, At, B0); PG8_MMA(1, 1, At, B1); PG8_BAR; PG8_SCHED;
;             PG8_LDB(B0, 1, 0); PG8_LDB(B1, 1, 1); PG8_SCHED; PG8_LDA(At, 1, 0); PG8_STAGE(PG8_SA(0, 1), a2 + hstepA, vA_);
;             PG8_WAIT_V(8); PG8_WAIT_L(0); PG8_BAR; PG8_MMA(0, 0, At, B0); PG8_MMA(0, 1, At, B1); PG8_BAR; PG8_SCHED;
.Lff2A_wd_1:
	s_waitcnt lgkmcnt(0)
	s_barrier
	s_setprio 1
	s_waitcnt lgkmcnt(0)
	v_mfma_f32_16x16x32_bf16 v[92:95], v[128:131], v[168:171], v[92:95]
	v_mfma_f32_16x16x32_bf16 v[88:91], v[136:139], v[168:171], v[88:91]
	v_mfma_f32_16x16x32_bf16 v[84:87], v[128:131], v[176:179], v[84:87]
	v_mfma_f32_16x16x32_bf16 v[80:83], v[136:139], v[176:179], v[80:83]
	v_mfma_f32_16x16x32_bf16 v[76:79], v[128:131], v[186:189], v[76:79]
	v_mfma_f32_16x16x32_bf16 v[72:75], v[136:139], v[186:189], v[72:75]
	v_mfma_f32_16x16x32_bf16 v[68:71], v[128:131], v[194:197], v[68:71]
	v_mfma_f32_16x16x32_bf16 v[64:67], v[136:139], v[194:197], v[64:67]
	v_mfma_f32_16x16x32_bf16 v[92:95], v[132:135], v[172:175], v[92:95]
	v_mfma_f32_16x16x32_bf16 v[88:91], v[140:143], v[172:175], v[88:91]
	v_mfma_f32_16x16x32_bf16 v[84:87], v[132:135], v[182:185], v[84:87]
	v_mfma_f32_16x16x32_bf16 v[80:83], v[140:143], v[182:185], v[80:83]
	v_mfma_f32_16x16x32_bf16 v[76:79], v[132:135], v[190:193], v[76:79]
	v_mfma_f32_16x16x32_bf16 v[72:75], v[140:143], v[190:193], v[72:75]
	v_mfma_f32_16x16x32_bf16 v[68:71], v[132:135], v[198:201], v[68:71]
	v_mfma_f32_16x16x32_bf16 v[64:67], v[140:143], v[198:201], v[64:67]
	s_setprio 0
	s_setprio 1
	v_mfma_f32_16x16x32_bf16 v[28:31], v[144:147], v[168:171], v[28:31]
	v_mfma_f32_16x16x32_bf16 v[24:27], v[152:155], v[168:171], v[24:27]
	v_mfma_f32_16x16x32_bf16 v[20:23], v[144:147], v[176:179], v[20:23]
	v_mfma_f32_16x16x32_bf16 v[16:19], v[152:155], v[176:179], v[16:19]
	v_mfma_f32_16x16x32_bf16 v[12:15], v[144:147], v[186:189], v[12:15]
	v_mfma_f32_16x16x32_bf16 v[8:11], v[152:155], v[186:189], v[8:11]
	v_mfma_f32_16x16x32_bf16 v[4:7], v[144:147], v[194:197], v[4:7]
	v_mfma_f32_16x16x32_bf16 v[0:3], v[152:155], v[194:197], v[0:3]
	v_mfma_f32_16x16x32_bf16 v[28:31], v[148:151], v[172:175], v[28:31]
	v_mfma_f32_16x16x32_bf16 v[24:27], v[164:167], v[172:175], v[24:27]
	v_mfma_f32_16x16x32_bf16 v[20:23], v[148:151], v[182:185], v[20:23]
	v_mfma_f32_16x16x32_bf16 v[16:19], v[164:167], v[182:185], v[16:19]
	v_mfma_f32_16x16x32_bf16 v[12:15], v[148:151], v[190:193], v[12:15]
	v_mfma_f32_16x16x32_bf16 v[8:11], v[164:167], v[190:193], v[8:11]
	v_mfma_f32_16x16x32_bf16 v[4:7], v[148:151], v[198:201], v[4:7]
	v_mfma_f32_16x16x32_bf16 v[0:3], v[164:167], v[198:201], v[0:3]
	s_setprio 0
	s_barrier
	s_add_i32 s61, 0, 0x18000
	s_add_i32 s62, 0, 0x1c000
	v_add_u32_e32 v140, s61, v157
	v_add_u32_e32 v164, s62, v157
	ds_read_b128 v[128:131], v140
	ds_read_b128 v[132:135], v140 offset:1024
	ds_read_b128 v[136:139], v140 offset:2048
	ds_read_b128 v[140:143], v140 offset:3072
	ds_read_b128 v[144:147], v164
	ds_read_b128 v[148:151], v164 offset:1024
	ds_read_b128 v[152:155], v164 offset:2048
	ds_read_b128 v[164:167], v164 offset:3072
	s_add_u32 s30, s40, 0x100000
	s_addc_u32 s31, s41, 0
	s_mov_b32 m0, s47
	ds_read_b128 v[168:171], v180 offset:32768
	ds_read_b128 v[172:175], v180 offset:33792
	ds_read_b128 v[176:179], v180 offset:34816
	ds_read_b128 v[182:185], v180 offset:35840
	ds_read_b128 v[186:189], v180 offset:36864
	ds_read_b128 v[190:193], v180 offset:37888
	ds_read_b128 v[194:197], v180 offset:38912
	ds_read_b128 v[198:201], v180 offset:39936
	s_nop 0
	global_load_lds_dwordx4 v202, s[30:31]
	s_mov_b32 m0, s48
	s_nop 0
	global_load_lds_dwordx4 v204, s[30:31]
	s_waitcnt vmcnt(8)
	s_waitcnt lgkmcnt(0)
	s_barrier
	s_setprio 1
	s_waitcnt lgkmcnt(0)
	v_mfma_f32_16x16x32_bf16 v[124:127], v[128:131], v[168:171], v[124:127]
	v_mfma_f32_16x16x32_bf16 v[120:123], v[136:139], v[168:171], v[120:123]
	v_mfma_f32_16x16x32_bf16 v[116:119], v[128:131], v[176:179], v[116:119]
	v_mfma_f32_16x16x32_bf16 v[112:115], v[136:139], v[176:179], v[112:115]
	v_mfma_f32_16x16x32_bf16 v[108:111], v[128:131], v[186:189], v[108:111]
	v_mfma_f32_16x16x32_bf16 v[104:107], v[136:139], v[186:189], v[104:107]
	v_mfma_f32_16x16x32_bf16 v[100:103], v[128:131], v[194:197], v[100:103]
	v_mfma_f32_16x16x32_bf16 v[96:99], v[136:139], v[194:197], v[96:99]
	v_mfma_f32_16x16x32_bf16 v[124:127], v[132:135], v[172:175], v[124:127]
	v_mfma_f32_16x16x32_bf16 v[120:123], v[140:143], v[172:175], v[120:123]
	v_mfma_f32_16x16x32_bf16 v[116:119], v[132:135], v[182:185], v[116:119]
	v_mfma_f32_16x16x32_bf16 v[112:115], v[140:143], v[182:185], v[112:115]
	v_mfma_f32_16x16x32_bf16 v[108:111], v[132:135], v[190:193], v[108:111]
	v_mfma_f32_16x16x32_bf16 v[104:107], v[140:143], v[190:193], v[104:107]
	v_mfma_f32_16x16x32_bf16 v[100:103], v[132:135], v[198:201], v[100:103]
	v_mfma_f32_16x16x32_bf16 v[96:99], v[140:143], v[198:201], v[96:99]
	s_setprio 0
	s_setprio 1
	v_mfma_f32_16x16x32_bf16 v[60:63], v[144:147], v[168:171], v[60:63]
	v_mfma_f32_16x16x32_bf16 v[56:59], v[152:155], v[168:171], v[56:59]
	v_mfma_f32_16x16x32_bf16 v[52:55], v[144:147], v[176:179], v[52:55]
	v_mfma_f32_16x16x32_bf16 v[48:51], v[152:155], v[176:179], v[48:51]
	v_mfma_f32_16x16x32_bf16 v[44:47], v[144:147], v[186:189], v[44:47]
	v_mfma_f32_16x16x32_bf16 v[40:43], v[152:155], v[186:189], v[40:43]
	v_mfma_f32_16x16x32_bf16 v[36:39], v[144:147], v[194:197], v[36:39]
	v_mfma_f32_16x16x32_bf16 v[32:35], v[152:155], v[194:197], v[32:35]
	v_mfma_f32_16x16x32_bf16 v[60:63], v[148:151], v[172:175], v[60:63]
	v_mfma_f32_16x16x32_bf16 v[56:59], v[164:167], v[172:175], v[56:59]
	v_mfma_f32_16x16x32_bf16 v[52:55], v[148:151], v[182:185], v[52:55]
	v_mfma_f32_16x16x32_bf16 v[48:51], v[164:167], v[182:185], v[48:51]
	v_mfma_f32_16x16x32_bf16 v[44:47], v[148:151], v[190:193], v[44:47]
	v_mfma_f32_16x16x32_bf16 v[40:43], v[164:167], v[190:193], v[40:43]
	v_mfma_f32_16x16x32_bf16 v[36:39], v[148:151], v[198:201], v[36:39]
	v_mfma_f32_16x16x32_bf16 v[32:35], v[164:167], v[198:201], v[32:35]
	s_setprio 0
	s_barrier
; #define PG8_STAGE(bufoff, gbase, voff) do { const char* gb_ = (const char*)(gbase); asm volatile("" : "+s"(gb_));     \
;         _Pragma("unroll") for (int _i = 0; _i < 2; ++_i) \
;         __builtin_amdgcn_global_load_lds((const unsigned*)(gb_ + (voff)[_i]), (PG8_LAS unsigned*)(lds + (bufoff) + ldsw + _i * 8192), 16, 0, 0); } while (0)
; #define PG8_LDA(dst, b, h) do { _Pragma("unroll") for (int m = 0; m < 4; ++m) _Pragma("unroll") for (int k = 0; k < 2; ++k) dst[m][k] = *(const PG8_LAS bf16x8*)(lds + PG8_SA(b, h) + aoff + m * 2048 + k * 1024); } while (0)
; #define PG8_MMA(ai, bj, At, Bt) do { __builtin_amdgcn_s_setprio(1); _Pragma("unroll") for (int m = 0; m < 4; ++m) _Pragma("unroll") for (int n = 0; n < 2; ++n) _Pragma("unroll") for (int k = 0; k < 2; ++k) \
;         acc[ai][bj][m][n] = __builtin_amdgcn_mfma_f32_16x16x32_bf16(Bt[n][k], At[m][k], acc[ai][bj][m][n], 0, 0, 0); __builtin_amdgcn_s_setprio(0); } while (0)
; #define PG8_WAIT_V(n) asm volatile("s_waitcnt vmcnt(" #n ")" ::: "memory")
; #define PG8_WAIT_L(n) asm volatile("s_waitcnt lgkmcnt(" #n ")" ::: "memory")
; #define PG8_BAR __builtin_amdgcn_s_barrier()
; #define PG8_SCHED __builtin_amdgcn_sched_barrier(0)
; template <class Epi, class Sched, bool ALIGN_EPI = false, bool SP2 = false>
; __device__ __forceinline__ void gemm_phase(PG8_LAS unsigned char* lds, const Gemm g, const Sched& S, const Epi& E, int wid0) {
;     ...
;         for (int t = 0; t < nt; t += 2) {
;     ...
;             PG8_LDA(At, 1, 1); PG8_STAGE(PG8_SB(1, 0), b3, vB_); PG8_STAGE(PG8_SB(1, 1), b3 + hstep, vB_); PG8_STAGE(PG8_SA(1, 0), a3, vA_);
;             PG8_WAIT_V(8); PG8_WAIT_L(0); PG8_BAR; PG8_MMA(1, 0, At, B0); PG8_MMA(1, 1, At, B1); PG8_BAR; PG8_SCHED;
	s_add_u32 s30, s38, 0x80
	s_addc_u32 s31, s39, 0
	s_add_i32 s40, s61, s33
	s_mov_b32 m0, s40
	ds_read_b128 v[168:171], v180 offset:49152
	ds_read_b128 v[172:175], v180 offset:50176
	ds_read_b128 v[176:179], v180 offset:51200
	ds_read_b128 v[182:185], v180 offset:52224
	ds_read_b128 v[186:189], v180 offset:53248
	ds_read_b128 v[190:193], v180 offset:54272
	ds_read_b128 v[194:197], v180 offset:55296
	ds_read_b128 v[198:201], v180 offset:56320
	s_nop 0
	global_load_lds_dwordx4 v203, s[30:31]
	s_add_i32 m0, s40, 0x2000
	s_nop 0
	global_load_lds_dwordx4 v181, s[30:31]
	s_add_u32 s30, s38, 0x100080
	s_addc_u32 s31, s39, 0
	s_add_i32 s38, s62, s33
	s_mov_b32 m0, s38
	s_nop 0
	global_load_lds_dwordx4 v203, s[30:31]
	s_add_i32 m0, s38, 0x2000
	s_nop 0
	global_load_lds_dwordx4 v181, s[30:31]
	s_mov_b32 m0, s53
	s_nop 0
	global_load_lds_dwordx4 v202, s[36:37]
	s_mov_b32 m0, s54
	s_nop 0
	global_load_lds_dwordx4 v204, s[36:37]
	s_waitcnt vmcnt(8)
	s_waitcnt lgkmcnt(0)
	s_barrier
	s_setprio 1
	s_waitcnt lgkmcnt(0)
	v_mfma_f32_16x16x32_bf16 v[92:95], v[128:131], v[168:171], v[92:95]
	v_mfma_f32_16x16x32_bf16 v[88:91], v[136:139], v[168:171], v[88:91]
	v_mfma_f32_16x16x32_bf16 v[84:87], v[128:131], v[176:179], v[84:87]
	v_mfma_f32_16x16x32_bf16 v[80:83], v[136:139], v[176:179], v[80:83]
	v_mfma_f32_16x16x32_bf16 v[76:79], v[128:131], v[186:189], v[76:79]
	v_mfma_f32_16x16x32_bf16 v[72:75], v[136:139], v[186:189], v[72:75]
	v_mfma_f32_16x16x32_bf16 v[68:71], v[128:131], v[194:197], v[68:71]
	v_mfma_f32_16x16x32_bf16 v[64:67], v[136:139], v[194:197], v[64:67]
	v_mfma_f32_16x16x32_bf16 v[92:95], v[132:135], v[172:175], v[92:95]
	v_mfma_f32_16x16x32_bf16 v[88:91], v[140:143], v[172:175], v[88:91]
	v_mfma_f32_16x16x32_bf16 v[84:87], v[132:135], v[182:185], v[84:87]
	v_mfma_f32_16x16x32_bf16 v[80:83], v[140:143], v[182:185], v[80:83]
	v_mfma_f32_16x16x32_bf16 v[76:79], v[132:135], v[190:193], v[76:79]
	v_mfma_f32_16x16x32_bf16 v[72:75], v[140:143], v[190:193], v[72:75]
	v_mfma_f32_16x16x32_bf16 v[68:71], v[132:135], v[198:201], v[68:71]
	v_mfma_f32_16x16x32_bf16 v[64:67], v[140:143], v[198:201], v[64:67]
	s_setprio 0
	s_setprio 1
	v_mfma_f32_16x16x32_bf16 v[28:31], v[144:147], v[168:171], v[28:31]
	v_mfma_f32_16x16x32_bf16 v[24:27], v[152:155], v[168:171], v[24:27]
	v_mfma_f32_16x16x32_bf16 v[20:23], v[144:147], v[176:179], v[20:23]
	v_mfma_f32_16x16x32_bf16 v[16:19], v[152:155], v[176:179], v[16:19]
	v_mfma_f32_16x16x32_bf16 v[12:15], v[144:147], v[186:189], v[12:15]
	v_mfma_f32_16x16x32_bf16 v[8:11], v[152:155], v[186:189], v[8:11]
	v_mfma_f32_16x16x32_bf16 v[4:7], v[144:147], v[194:197], v[4:7]
	v_mfma_f32_16x16x32_bf16 v[0:3], v[152:155], v[194:197], v[0:3]
	v_mfma_f32_16x16x32_bf16 v[28:31], v[148:151], v[172:175], v[28:31]
	v_mfma_f32_16x16x32_bf16 v[24:27], v[164:167], v[172:175], v[24:27]
	v_mfma_f32_16x16x32_bf16 v[20:23], v[148:151], v[182:185], v[20:23]
	v_mfma_f32_16x16x32_bf16 v[16:19], v[164:167], v[182:185], v[16:19]
	v_mfma_f32_16x16x32_bf16 v[12:15], v[148:151], v[190:193], v[12:15]
	v_mfma_f32_16x16x32_bf16 v[8:11], v[164:167], v[190:193], v[8:11]
	v_mfma_f32_16x16x32_bf16 v[4:7], v[148:151], v[198:201], v[4:7]
	v_mfma_f32_16x16x32_bf16 v[0:3], v[164:167], v[198:201], v[0:3]
	s_setprio 0
	s_barrier
	s_add_i32 s60, s60, 2
	s_add_u32 s58, s58, 0x100
	s_addc_u32 s59, s59, 0
	s_cmp_gt_u32 s60, 61
	s_mov_b64 s[30:31], s[34:35]
	s_cbranch_scc0 .LBB13_1187
	s_and_b64 vcc, exec, s[14:15]
	s_cbranch_vccz .LBB13_1190
	s_barrier

; template <class Epi, class Sched, bool ALIGN_EPI = false, bool SP2 = false>
; __device__ __forceinline__ void gemm_phase(PG8_LAS unsigned char* lds, const Gemm g, const Sched& S, const Epi& E, int wid0) {
;     ...
;         if constexpr (Epi::HAS_PRE) E.pre_finish(lds, cur, tid, pq0, pq1, pq2);
.LBB13_1331:
	s_waitcnt vmcnt(16)
	v_add_f32_e32 v8, v4, v5
	v_add_f32_e32 v14, v6, v7
	v_add_f32_e32 v8, v8, v14
	v_add_f32_e32 v14, v0, v1
	v_add_f32_e32 v15, v2, v3
	v_add_f32_e32 v14, v14, v15
	v_add_f32_e32 v8, v8, v14
	ds_swizzle_b32 v14, v8 offset:swizzle(SWAP,1)
	s_and_saveexec_b64 s[10:11], s[6:7]
	s_cbranch_execz .LBB13_1333
	s_waitcnt lgkmcnt(0)
	v_add_f32_e32 v8, v8, v14
	v_fmamk_f32 v8, v8, 0x3a800000, v199
	v_mul_f32_e32 v14, 0x4b800000, v8
	v_cmp_gt_f32_e32 vcc, s74, v8
	s_lshl_b32 s12, s33, 11
	s_and_b32 s12, s12, 0x800
	v_cndmask_b32_e32 v8, v8, v14, vcc
	v_rsq_f32_e32 v8, v8
	s_nop 0
	v_mul_f32_e32 v14, 0x45800000, v8
	v_cndmask_b32_e32 v8, v8, v14, vcc
	v_add_u32_e32 v14, s12, v177
	ds_write_b32 v14, v8

;     __device__ float mid(int row) const { return rg(row) / ra(row); }
; #define PG8_STAGE(bufoff, gbase, voff) do { const char* gb_ = (const char*)(gbase); asm volatile("" : "+s"(gb_));     \
;         _Pragma("unroll") for (int _i = 0; _i < 2; ++_i) \
;         __builtin_amdgcn_global_load_lds((const unsigned*)(gb_ + (voff)[_i]), (PG8_LAS unsigned*)(lds + (bufoff) + ldsw + _i * 8192), 16, 0, 0); } while (0)
; #define PG8_LDA(dst, b, h) do { _Pragma("unroll") for (int m = 0; m < 4; ++m) _Pragma("unroll") for (int k = 0; k < 2; ++k) dst[m][k] = *(const PG8_LAS bf16x8*)(lds + PG8_SA(b, h) + aoff + m * 2048 + k * 1024); } while (0)
; #define PG8_LDB(dst, b, h) do { _Pragma("unroll") for (int n = 0; n < 2; ++n) _Pragma("unroll") for (int k = 0; k < 2; ++k) dst[n][k] = *(const PG8_LAS bf16x8*)(lds + PG8_SB(b, h) + boff + n * 2048 + k * 1024); } while (0)
; #define PG8_SCHED __builtin_amdgcn_sched_barrier(0)
; template <class Epi, class Sched, bool ALIGN_EPI = false, bool SP2 = false>
; __device__ __forceinline__ void gemm_phase(PG8_LAS unsigned char* lds, const Gemm g, const Sched& S, const Epi& E, int wid0) {
;     ...
;         for (int t = 0; t < nt; t += 2) {
;             const bool last = (t == nt - 2);
;             const char* a1 = cA + (size_t)(t + 1) * kstep;
;             const char* a2 = last ? nA : cA + (size_t)(t + 2) * kstep; const char* b2 = last ? nB : cB + (size_t)(t + 2) * kstep;
;             const char* a3 = a2 + kstep; const char* b3 = b2 + kstep;
;             if (last && has_next) S.a_ready(nxt);
;             if constexpr (Epi::HAS_MID) { if (t == Epi::MID_T) E.mid(acc, cur, wr, fr); }
;             unsigned vA_[2] = {voffA[0], voffA[1]}, vB_[2] = {voffB[0], voffB[1]};
;             asm volatile("" : "+v"(vA_[0]), "+v"(vA_[1]), "+v"(vB_[0]), "+v"(vB_[1]));
;             if constexpr (SP2) {
;             PG8_LDB(B0, 0, 0); PG8_LDB(B1, 0, 1); PG8_SCHED; PG8_LDA(At, 0, 0); PG8_STAGE(PG8_SA(1, 1), a1 + hstepA, vA_);
.LBB13_1336:
	v_mov_b32_e32 v8, v178
	v_mov_b32_e32 v220, v174
	v_mov_b32_e32 v221, v200
	v_mov_b32_e32 v222, v176
	ds_read_b128 v[82:85], v201
	ds_read_b128 v[90:93], v201 offset:1024
	ds_read_b128 v[94:97], v201 offset:2048
	ds_read_b128 v[102:105], v201 offset:3072
	ds_read_b128 v[158:161], v202
	ds_read_b128 v[162:165], v202 offset:1024
	ds_read_b128 v[166:169], v202 offset:2048
	ds_read_b128 v[170:173], v202 offset:3072
	s_add_u32 s8, s2, 0x100
	s_addc_u32 s9, s3, 0
	s_cmp_eq_u32 s82, 12
	s_cselect_b32 s58, s78, s8
	s_cselect_b32 s59, s47, s9
	s_cselect_b32 s12, s79, s80
	s_cselect_b32 s13, s49, s81
	s_add_u32 s10, s58, 0x80
	s_addc_u32 s11, s59, 0
	s_add_u32 s2, s2, 0x40080
	s_addc_u32 s3, s3, 0
	s_add_i32 m0, s57, 0xc000
	ds_read_b128 v[180:183], v203
	ds_read_b128 v[184:187], v203 offset:1024
	ds_read_b128 v[188:191], v203 offset:2048
	ds_read_b128 v[192:195], v203 offset:3072
	ds_read_b128 v[204:207], v203 offset:4096
	ds_read_b128 v[208:211], v203 offset:5120
	ds_read_b128 v[212:215], v203 offset:6144
	ds_read_b128 v[216:219], v203 offset:7168
	s_nop 0
	global_load_lds_dwordx4 v220, s[2:3]
	s_add_i32 m0, s57, 0xe000
	s_nop 0
	global_load_lds_dwordx4 v222, s[2:3]
	s_cmp_lg_u32 s82, -2
	s_cbranch_scc1 .LinB_w8_0
	s_cmp_eq_u32 s33, 0
	s_cbranch_scc1 .LinB_w8_0
	s_waitcnt vmcnt(24)
	s_branch .LinB_wd_0

; #define PG8_STAGE(bufoff, gbase, voff) do { const char* gb_ = (const char*)(gbase); asm volatile("" : "+s"(gb_));     \
;         _Pragma("unroll") for (int _i = 0; _i < 2; ++_i) \
;         __builtin_amdgcn_global_load_lds((const unsigned*)(gb_ + (voff)[_i]), (PG8_LAS unsigned*)(lds + (bufoff) + ldsw + _i * 8192), 16, 0, 0); } while (0)
; #define PG8_LDA(dst, b, h) do { _Pragma("unroll") for (int m = 0; m < 4; ++m) _Pragma("unroll") for (int k = 0; k < 2; ++k) dst[m][k] = *(const PG8_LAS bf16x8*)(lds + PG8_SA(b, h) + aoff + m * 2048 + k * 1024); } while (0)
; #define PG8_MMA(ai, bj, At, Bt) do { __builtin_amdgcn_s_setprio(1); _Pragma("unroll") for (int m = 0; m < 4; ++m) _Pragma("unroll") for (int n = 0; n < 2; ++n) _Pragma("unroll") for (int k = 0; k < 2; ++k) \
;         acc[ai][bj][m][n] = __builtin_amdgcn_mfma_f32_16x16x32_bf16(Bt[n][k], At[m][k], acc[ai][bj][m][n], 0, 0, 0); __builtin_amdgcn_s_setprio(0); } while (0)
; #define PG8_WAIT_V(n) asm volatile("s_waitcnt vmcnt(" #n ")" ::: "memory")
; #define PG8_WAIT_L(n) asm volatile("s_waitcnt lgkmcnt(" #n ")" ::: "memory")
; #define PG8_BAR __builtin_amdgcn_s_barrier()
; #define PG8_SCHED __builtin_amdgcn_sched_barrier(0)
; template <class Epi, class Sched, bool ALIGN_EPI = false, bool SP2 = false>
; __device__ __forceinline__ void gemm_phase(PG8_LAS unsigned char* lds, const Gemm g, const Sched& S, const Epi& E, int wid0) {
;     ...
;             PG8_WAIT_V(8); PG8_WAIT_L(0); PG8_BAR; PG8_MMA(0, 0, At, B0); PG8_MMA(0, 1, At, B1); PG8_BAR; PG8_SCHED;
;             PG8_LDA(At, 0, 1); PG8_STAGE(PG8_SB(0, 0), b2, vB_); PG8_STAGE(PG8_SB(0, 1), b2 + hstep, vB_); PG8_STAGE(PG8_SA(0, 0), a2, vA_);
.LinB_wd_0:
	s_waitcnt lgkmcnt(0)
	s_barrier
	s_setprio 1
	s_waitcnt lgkmcnt(0)
	v_mfma_f32_16x16x32_bf16 v[154:157], v[82:85], v[180:183], v[154:157]
	v_mfma_f32_16x16x32_bf16 v[150:153], v[94:97], v[180:183], v[150:153]
	v_mfma_f32_16x16x32_bf16 v[138:141], v[82:85], v[188:191], v[138:141]
	v_mfma_f32_16x16x32_bf16 v[134:137], v[94:97], v[188:191], v[134:137]
	v_mfma_f32_16x16x32_bf16 v[122:125], v[82:85], v[204:207], v[122:125]
	v_mfma_f32_16x16x32_bf16 v[118:121], v[94:97], v[204:207], v[118:121]
	v_mfma_f32_16x16x32_bf16 v[106:109], v[82:85], v[212:215], v[106:109]
	v_mfma_f32_16x16x32_bf16 v[98:101], v[94:97], v[212:215], v[98:101]
	v_mfma_f32_16x16x32_bf16 v[154:157], v[90:93], v[184:187], v[154:157]
	v_mfma_f32_16x16x32_bf16 v[150:153], v[102:105], v[184:187], v[150:153]
	v_mfma_f32_16x16x32_bf16 v[138:141], v[90:93], v[192:195], v[138:141]
	v_mfma_f32_16x16x32_bf16 v[134:137], v[102:105], v[192:195], v[134:137]
	v_mfma_f32_16x16x32_bf16 v[122:125], v[90:93], v[208:211], v[122:125]
	v_mfma_f32_16x16x32_bf16 v[118:121], v[102:105], v[208:211], v[118:121]
	v_mfma_f32_16x16x32_bf16 v[106:109], v[90:93], v[216:219], v[106:109]
	v_mfma_f32_16x16x32_bf16 v[98:101], v[102:105], v[216:219], v[98:101]
	s_setprio 0
	s_setprio 1
	v_mfma_f32_16x16x32_bf16 v[146:149], v[158:161], v[180:183], v[146:149]
	v_mfma_f32_16x16x32_bf16 v[142:145], v[166:169], v[180:183], v[142:145]
	v_mfma_f32_16x16x32_bf16 v[130:133], v[158:161], v[188:191], v[130:133]
	v_mfma_f32_16x16x32_bf16 v[126:129], v[166:169], v[188:191], v[126:129]
	v_mfma_f32_16x16x32_bf16 v[114:117], v[158:161], v[204:207], v[114:117]
	v_mfma_f32_16x16x32_bf16 v[110:113], v[166:169], v[204:207], v[110:113]
	v_mfma_f32_16x16x32_bf16 v[86:89], v[158:161], v[212:215], v[86:89]
	v_mfma_f32_16x16x32_bf16 v[78:81], v[166:169], v[212:215], v[78:81]
	v_mfma_f32_16x16x32_bf16 v[146:149], v[162:165], v[184:187], v[146:149]
	v_mfma_f32_16x16x32_bf16 v[142:145], v[170:173], v[184:187], v[142:145]
	v_mfma_f32_16x16x32_bf16 v[130:133], v[162:165], v[192:195], v[130:133]
	v_mfma_f32_16x16x32_bf16 v[126:129], v[170:173], v[192:195], v[126:129]
	v_mfma_f32_16x16x32_bf16 v[114:117], v[162:165], v[208:211], v[114:117]
	v_mfma_f32_16x16x32_bf16 v[110:113], v[170:173], v[208:211], v[110:113]
	v_mfma_f32_16x16x32_bf16 v[86:89], v[162:165], v[216:219], v[86:89]
	v_mfma_f32_16x16x32_bf16 v[78:81], v[170:173], v[216:219], v[78:81]
	s_setprio 0
	s_barrier
	s_add_i32 s83, s75, s55
	s_mov_b64 s[2:3], s[12:13]
	s_mov_b32 m0, s83
	ds_read_b128 v[180:183], v203 offset:16384
	ds_read_b128 v[184:187], v203 offset:17408
	ds_read_b128 v[188:191], v203 offset:18432
	ds_read_b128 v[192:195], v203 offset:19456
	ds_read_b128 v[204:207], v203 offset:20480
	ds_read_b128 v[208:211], v203 offset:21504
	ds_read_b128 v[212:215], v203 offset:22528
	ds_read_b128 v[216:219], v203 offset:23552
	s_nop 0
	global_load_lds_dwordx4 v221, s[2:3]
	s_add_i32 m0, s83, 0x2000
	s_nop 0
	global_load_lds_dwordx4 v8, s[2:3]
	s_add_u32 s2, s12, 0x40000
	s_addc_u32 s3, s13, 0
	s_add_i32 s83, s76, s55
	s_mov_b32 m0, s83
	s_nop 0
	global_load_lds_dwordx4 v221, s[2:3]
	s_add_i32 m0, s83, 0x2000
	s_nop 0
	global_load_lds_dwordx4 v8, s[2:3]
	s_mov_b64 s[2:3], s[58:59]
	s_mov_b32 m0, s57
	s_nop 0
	global_load_lds_dwordx4 v220, s[2:3]
	s_mov_b32 m0, s64
	s_nop 0
	global_load_lds_dwordx4 v222, s[2:3]
	s_cmp_lg_u32 s82, -2
	s_cbranch_scc1 .LinB_w8_1
	s_cmp_eq_u32 s33, 0
	s_cbranch_scc1 .LinB_w8_1
	s_waitcnt vmcnt(24)
	s_branch .LinB_wd_1

; #define PG8_STAGE(bufoff, gbase, voff) do { const char* gb_ = (const char*)(gbase); asm volatile("" : "+s"(gb_));     \
;         _Pragma("unroll") for (int _i = 0; _i < 2; ++_i) \
;         __builtin_amdgcn_global_load_lds((const unsigned*)(gb_ + (voff)[_i]), (PG8_LAS unsigned*)(lds + (bufoff) + ldsw + _i * 8192), 16, 0, 0); } while (0)
; #define PG8_LDA(dst, b, h) do { _Pragma("unroll") for (int m = 0; m < 4; ++m) _Pragma("unroll") for (int k = 0; k < 2; ++k) dst[m][k] = *(const PG8_LAS bf16x8*)(lds + PG8_SA(b, h) + aoff + m * 2048 + k * 1024); } while (0)
; #define PG8_LDB(dst, b, h) do { _Pragma("unroll") for (int n = 0; n < 2; ++n) _Pragma("unroll") for (int k = 0; k < 2; ++k) dst[n][k] = *(const PG8_LAS bf16x8*)(lds + PG8_SB(b, h) + boff + n * 2048 + k * 1024); } while (0)
; #define PG8_MMA(ai, bj, At, Bt) do { __builtin_amdgcn_s_setprio(1); _Pragma("unroll") for (int m = 0; m < 4; ++m) _Pragma("unroll") for (int n = 0; n < 2; ++n) _Pragma("unroll") for (int k = 0; k < 2; ++k) \
;         acc[ai][bj][m][n] = __builtin_amdgcn_mfma_f32_16x16x32_bf16(Bt[n][k], At[m][k], acc[ai][bj][m][n], 0, 0, 0); __builtin_amdgcn_s_setprio(0); } while (0)
; #define PG8_WAIT_V(n) asm volatile("s_waitcnt vmcnt(" #n ")" ::: "memory")
; #define PG8_WAIT_L(n) asm volatile("s_waitcnt lgkmcnt(" #n ")" ::: "memory")
; #define PG8_BAR __builtin_amdgcn_s_barrier()
; #define PG8_SCHED __builtin_amdgcn_sched_barrier(0)
; template <class Epi, class Sched, bool ALIGN_EPI = false, bool SP2 = false>
; __device__ __forceinline__ void gemm_phase(PG8_LAS unsigned char* lds, const Gemm g, const Sched& S, const Epi& E, int wid0) {
;     ...
;             PG8_WAIT_V(8); PG8_WAIT_L(0); PG8_BAR; PG8_MMA(1, 0, At, B0); PG8_MMA(1, 1, At, B1); PG8_BAR; PG8_SCHED;
;             PG8_LDB(B0, 1, 0); PG8_LDB(B1, 1, 1); PG8_SCHED; PG8_LDA(At, 1, 0); PG8_STAGE(PG8_SA(0, 1), a2 + hstepA, vA_);
;             PG8_WAIT_V(8); PG8_WAIT_L(0); PG8_BAR; PG8_MMA(0, 0, At, B0); PG8_MMA(0, 1, At, B1); PG8_BAR; PG8_SCHED;
.LinB_wd_1:
	s_waitcnt lgkmcnt(0)
	s_barrier
	s_setprio 1
	s_waitcnt lgkmcnt(0)
	v_mfma_f32_16x16x32_bf16 v[74:77], v[82:85], v[180:183], v[74:77]
	v_mfma_f32_16x16x32_bf16 v[70:73], v[94:97], v[180:183], v[70:73]
	v_mfma_f32_16x16x32_bf16 v[58:61], v[82:85], v[188:191], v[58:61]
	v_mfma_f32_16x16x32_bf16 v[54:57], v[94:97], v[188:191], v[54:57]
	v_mfma_f32_16x16x32_bf16 v[42:45], v[82:85], v[204:207], v[42:45]
	v_mfma_f32_16x16x32_bf16 v[38:41], v[94:97], v[204:207], v[38:41]
	v_mfma_f32_16x16x32_bf16 v[26:29], v[82:85], v[212:215], v[26:29]
	v_mfma_f32_16x16x32_bf16 v[22:25], v[94:97], v[212:215], v[22:25]
	v_mfma_f32_16x16x32_bf16 v[74:77], v[90:93], v[184:187], v[74:77]
	v_mfma_f32_16x16x32_bf16 v[70:73], v[102:105], v[184:187], v[70:73]
	v_mfma_f32_16x16x32_bf16 v[58:61], v[90:93], v[192:195], v[58:61]
	v_mfma_f32_16x16x32_bf16 v[54:57], v[102:105], v[192:195], v[54:57]
	v_mfma_f32_16x16x32_bf16 v[42:45], v[90:93], v[208:211], v[42:45]
	v_mfma_f32_16x16x32_bf16 v[38:41], v[102:105], v[208:211], v[38:41]
	v_mfma_f32_16x16x32_bf16 v[26:29], v[90:93], v[216:219], v[26:29]
	v_mfma_f32_16x16x32_bf16 v[22:25], v[102:105], v[216:219], v[22:25]
	s_setprio 0
	s_setprio 1
	v_mfma_f32_16x16x32_bf16 v[66:69], v[158:161], v[180:183], v[66:69]
	v_mfma_f32_16x16x32_bf16 v[62:65], v[166:169], v[180:183], v[62:65]
	v_mfma_f32_16x16x32_bf16 v[50:53], v[158:161], v[188:191], v[50:53]
	v_mfma_f32_16x16x32_bf16 v[46:49], v[166:169], v[188:191], v[46:49]
	v_mfma_f32_16x16x32_bf16 v[34:37], v[158:161], v[204:207], v[34:37]
	v_mfma_f32_16x16x32_bf16 v[30:33], v[166:169], v[204:207], v[30:33]
	v_mfma_f32_16x16x32_bf16 v[18:21], v[158:161], v[212:215], v[18:21]
	v_mfma_f32_16x16x32_bf16 v[14:17], v[166:169], v[212:215], v[14:17]
	v_mfma_f32_16x16x32_bf16 v[66:69], v[162:165], v[184:187], v[66:69]
	v_mfma_f32_16x16x32_bf16 v[62:65], v[170:173], v[184:187], v[62:65]
	v_mfma_f32_16x16x32_bf16 v[50:53], v[162:165], v[192:195], v[50:53]
	v_mfma_f32_16x16x32_bf16 v[46:49], v[170:173], v[192:195], v[46:49]
	v_mfma_f32_16x16x32_bf16 v[34:37], v[162:165], v[208:211], v[34:37]
	v_mfma_f32_16x16x32_bf16 v[30:33], v[170:173], v[208:211], v[30:33]
	v_mfma_f32_16x16x32_bf16 v[18:21], v[162:165], v[216:219], v[18:21]
	v_mfma_f32_16x16x32_bf16 v[14:17], v[170:173], v[216:219], v[14:17]
	s_setprio 0
	s_barrier
	s_add_i32 s83, 0, 0x18000
	s_add_i32 s84, 0, 0x1c000
	v_add_u32_e32 v102, s83, v175
	v_add_u32_e32 v170, s84, v175
	ds_read_b128 v[82:85], v102
	ds_read_b128 v[90:93], v102 offset:1024
	ds_read_b128 v[94:97], v102 offset:2048
	ds_read_b128 v[102:105], v102 offset:3072
	ds_read_b128 v[158:161], v170
	ds_read_b128 v[162:165], v170 offset:1024
	ds_read_b128 v[166:169], v170 offset:2048
	ds_read_b128 v[170:173], v170 offset:3072
	s_add_u32 s2, s58, 0x40000
	s_addc_u32 s3, s59, 0
	s_mov_b32 m0, s65
	ds_read_b128 v[180:183], v203 offset:32768
	ds_read_b128 v[184:187], v203 offset:33792
	ds_read_b128 v[188:191], v203 offset:34816
	ds_read_b128 v[192:195], v203 offset:35840
	ds_read_b128 v[204:207], v203 offset:36864
	ds_read_b128 v[208:211], v203 offset:37888
	ds_read_b128 v[212:215], v203 offset:38912
	ds_read_b128 v[216:219], v203 offset:39936
	s_nop 0
	global_load_lds_dwordx4 v220, s[2:3]
	s_mov_b32 m0, s66
	s_nop 0
	global_load_lds_dwordx4 v222, s[2:3]
	s_waitcnt vmcnt(8)
	s_waitcnt lgkmcnt(0)
	s_barrier
	s_setprio 1
	s_waitcnt lgkmcnt(0)
	v_mfma_f32_16x16x32_bf16 v[154:157], v[82:85], v[180:183], v[154:157]
	v_mfma_f32_16x16x32_bf16 v[150:153], v[94:97], v[180:183], v[150:153]
	v_mfma_f32_16x16x32_bf16 v[138:141], v[82:85], v[188:191], v[138:141]
	v_mfma_f32_16x16x32_bf16 v[134:137], v[94:97], v[188:191], v[134:137]
	v_mfma_f32_16x16x32_bf16 v[122:125], v[82:85], v[204:207], v[122:125]
	v_mfma_f32_16x16x32_bf16 v[118:121], v[94:97], v[204:207], v[118:121]
	v_mfma_f32_16x16x32_bf16 v[106:109], v[82:85], v[212:215], v[106:109]
	v_mfma_f32_16x16x32_bf16 v[98:101], v[94:97], v[212:215], v[98:101]
	v_mfma_f32_16x16x32_bf16 v[154:157], v[90:93], v[184:187], v[154:157]
	v_mfma_f32_16x16x32_bf16 v[150:153], v[102:105], v[184:187], v[150:153]
	v_mfma_f32_16x16x32_bf16 v[138:141], v[90:93], v[192:195], v[138:141]
	v_mfma_f32_16x16x32_bf16 v[134:137], v[102:105], v[192:195], v[134:137]
	v_mfma_f32_16x16x32_bf16 v[122:125], v[90:93], v[208:211], v[122:125]
	v_mfma_f32_16x16x32_bf16 v[118:121], v[102:105], v[208:211], v[118:121]
	v_mfma_f32_16x16x32_bf16 v[106:109], v[90:93], v[216:219], v[106:109]
	v_mfma_f32_16x16x32_bf16 v[98:101], v[102:105], v[216:219], v[98:101]
	s_setprio 0
	s_setprio 1
	v_mfma_f32_16x16x32_bf16 v[146:149], v[158:161], v[180:183], v[146:149]
	v_mfma_f32_16x16x32_bf16 v[142:145], v[166:169], v[180:183], v[142:145]
	v_mfma_f32_16x16x32_bf16 v[130:133], v[158:161], v[188:191], v[130:133]
	v_mfma_f32_16x16x32_bf16 v[126:129], v[166:169], v[188:191], v[126:129]
	v_mfma_f32_16x16x32_bf16 v[114:117], v[158:161], v[204:207], v[114:117]
	v_mfma_f32_16x16x32_bf16 v[110:113], v[166:169], v[204:207], v[110:113]
	v_mfma_f32_16x16x32_bf16 v[86:89], v[158:161], v[212:215], v[86:89]
	v_mfma_f32_16x16x32_bf16 v[78:81], v[166:169], v[212:215], v[78:81]
	v_mfma_f32_16x16x32_bf16 v[146:149], v[162:165], v[184:187], v[146:149]
	v_mfma_f32_16x16x32_bf16 v[142:145], v[170:173], v[184:187], v[142:145]
	v_mfma_f32_16x16x32_bf16 v[130:133], v[162:165], v[192:195], v[130:133]
	v_mfma_f32_16x16x32_bf16 v[126:129], v[170:173], v[192:195], v[126:129]
	v_mfma_f32_16x16x32_bf16 v[114:117], v[162:165], v[208:211], v[114:117]
	v_mfma_f32_16x16x32_bf16 v[110:113], v[170:173], v[208:211], v[110:113]
	v_mfma_f32_16x16x32_bf16 v[86:89], v[162:165], v[216:219], v[86:89]
	v_mfma_f32_16x16x32_bf16 v[78:81], v[170:173], v[216:219], v[78:81]
	s_setprio 0
	s_barrier
; #define PG8_STAGE(bufoff, gbase, voff) do { const char* gb_ = (const char*)(gbase); asm volatile("" : "+s"(gb_));     \
;         _Pragma("unroll") for (int _i = 0; _i < 2; ++_i) \
;         __builtin_amdgcn_global_load_lds((const unsigned*)(gb_ + (voff)[_i]), (PG8_LAS unsigned*)(lds + (bufoff) + ldsw + _i * 8192), 16, 0, 0); } while (0)
; #define PG8_LDA(dst, b, h) do { _Pragma("unroll") for (int m = 0; m < 4; ++m) _Pragma("unroll") for (int k = 0; k < 2; ++k) dst[m][k] = *(const PG8_LAS bf16x8*)(lds + PG8_SA(b, h) + aoff + m * 2048 + k * 1024); } while (0)
; #define PG8_MMA(ai, bj, At, Bt) do { __builtin_amdgcn_s_setprio(1); _Pragma("unroll") for (int m = 0; m < 4; ++m) _Pragma("unroll") for (int n = 0; n < 2; ++n) _Pragma("unroll") for (int k = 0; k < 2; ++k) \
;         acc[ai][bj][m][n] = __builtin_amdgcn_mfma_f32_16x16x32_bf16(Bt[n][k], At[m][k], acc[ai][bj][m][n], 0, 0, 0); __builtin_amdgcn_s_setprio(0); } while (0)
; #define PG8_WAIT_V(n) asm volatile("s_waitcnt vmcnt(" #n ")" ::: "memory")
; #define PG8_WAIT_L(n) asm volatile("s_waitcnt lgkmcnt(" #n ")" ::: "memory")
; #define PG8_BAR __builtin_amdgcn_s_barrier()
; #define PG8_SCHED __builtin_amdgcn_sched_barrier(0)
; template <class Epi, class Sched, bool ALIGN_EPI = false, bool SP2 = false>
; __device__ __forceinline__ void gemm_phase(PG8_LAS unsigned char* lds, const Gemm g, const Sched& S, const Epi& E, int wid0) {
;     ...
;         for (int t = 0; t < nt; t += 2) {
;     ...
;             PG8_LDA(At, 1, 1); PG8_STAGE(PG8_SB(1, 0), b3, vB_); PG8_STAGE(PG8_SB(1, 1), b3 + hstep, vB_); PG8_STAGE(PG8_SA(1, 0), a3, vA_);
;             PG8_WAIT_V(8); PG8_WAIT_L(0); PG8_BAR; PG8_MMA(1, 0, At, B0); PG8_MMA(1, 1, At, B1); PG8_BAR; PG8_SCHED;
	s_add_u32 s2, s12, 0x80
	s_addc_u32 s3, s13, 0
	s_add_i32 s58, s83, s55
	s_mov_b32 m0, s58
	ds_read_b128 v[180:183], v203 offset:49152
	ds_read_b128 v[184:187], v203 offset:50176
	ds_read_b128 v[188:191], v203 offset:51200
	ds_read_b128 v[192:195], v203 offset:52224
	ds_read_b128 v[204:207], v203 offset:53248
	ds_read_b128 v[208:211], v203 offset:54272
	ds_read_b128 v[212:215], v203 offset:55296
	ds_read_b128 v[216:219], v203 offset:56320
	s_nop 0
	global_load_lds_dwordx4 v221, s[2:3]
	s_add_i32 m0, s58, 0x2000
	s_nop 0
	global_load_lds_dwordx4 v8, s[2:3]
	s_add_u32 s2, s12, 0x40080
	s_addc_u32 s3, s13, 0
	s_add_i32 s12, s84, s55
	s_mov_b32 m0, s12
	s_nop 0
	global_load_lds_dwordx4 v221, s[2:3]
	s_add_i32 m0, s12, 0x2000
	s_nop 0
	global_load_lds_dwordx4 v8, s[2:3]
	s_mov_b32 m0, s69
	s_nop 0
	global_load_lds_dwordx4 v220, s[10:11]
	s_mov_b32 m0, s70
	s_nop 0
	global_load_lds_dwordx4 v222, s[10:11]
	s_waitcnt vmcnt(8)
	s_waitcnt lgkmcnt(0)
	s_barrier
	s_setprio 1
	s_waitcnt lgkmcnt(0)
	v_mfma_f32_16x16x32_bf16 v[74:77], v[82:85], v[180:183], v[74:77]
	v_mfma_f32_16x16x32_bf16 v[70:73], v[94:97], v[180:183], v[70:73]
	v_mfma_f32_16x16x32_bf16 v[58:61], v[82:85], v[188:191], v[58:61]
	v_mfma_f32_16x16x32_bf16 v[54:57], v[94:97], v[188:191], v[54:57]
	v_mfma_f32_16x16x32_bf16 v[42:45], v[82:85], v[204:207], v[42:45]
	v_mfma_f32_16x16x32_bf16 v[38:41], v[94:97], v[204:207], v[38:41]
	v_mfma_f32_16x16x32_bf16 v[26:29], v[82:85], v[212:215], v[26:29]
	v_mfma_f32_16x16x32_bf16 v[22:25], v[94:97], v[212:215], v[22:25]
	v_mfma_f32_16x16x32_bf16 v[74:77], v[90:93], v[184:187], v[74:77]
	v_mfma_f32_16x16x32_bf16 v[70:73], v[102:105], v[184:187], v[70:73]
	v_mfma_f32_16x16x32_bf16 v[58:61], v[90:93], v[192:195], v[58:61]
	v_mfma_f32_16x16x32_bf16 v[54:57], v[102:105], v[192:195], v[54:57]
	v_mfma_f32_16x16x32_bf16 v[42:45], v[90:93], v[208:211], v[42:45]
	v_mfma_f32_16x16x32_bf16 v[38:41], v[102:105], v[208:211], v[38:41]
	v_mfma_f32_16x16x32_bf16 v[26:29], v[90:93], v[216:219], v[26:29]
	v_mfma_f32_16x16x32_bf16 v[22:25], v[102:105], v[216:219], v[22:25]
	s_setprio 0
	s_setprio 1
	v_mfma_f32_16x16x32_bf16 v[66:69], v[158:161], v[180:183], v[66:69]
	v_mfma_f32_16x16x32_bf16 v[62:65], v[166:169], v[180:183], v[62:65]
	v_mfma_f32_16x16x32_bf16 v[50:53], v[158:161], v[188:191], v[50:53]
	v_mfma_f32_16x16x32_bf16 v[46:49], v[166:169], v[188:191], v[46:49]
	v_mfma_f32_16x16x32_bf16 v[34:37], v[158:161], v[204:207], v[34:37]
	v_mfma_f32_16x16x32_bf16 v[30:33], v[166:169], v[204:207], v[30:33]
	v_mfma_f32_16x16x32_bf16 v[18:21], v[158:161], v[212:215], v[18:21]
	v_mfma_f32_16x16x32_bf16 v[14:17], v[166:169], v[212:215], v[14:17]
	v_mfma_f32_16x16x32_bf16 v[66:69], v[162:165], v[184:187], v[66:69]
	v_mfma_f32_16x16x32_bf16 v[62:65], v[170:173], v[184:187], v[62:65]
	v_mfma_f32_16x16x32_bf16 v[50:53], v[162:165], v[192:195], v[50:53]
	v_mfma_f32_16x16x32_bf16 v[46:49], v[170:173], v[192:195], v[46:49]
	v_mfma_f32_16x16x32_bf16 v[34:37], v[162:165], v[208:211], v[34:37]
	v_mfma_f32_16x16x32_bf16 v[30:33], v[170:173], v[208:211], v[30:33]
	v_mfma_f32_16x16x32_bf16 v[18:21], v[162:165], v[216:219], v[18:21]
	v_mfma_f32_16x16x32_bf16 v[14:17], v[170:173], v[216:219], v[14:17]
	s_setprio 0
	s_barrier
	s_add_i32 s82, s82, 2
	s_add_u32 s80, s80, 0x100
	s_addc_u32 s81, s81, 0
	s_cmp_gt_u32 s82, 13
	s_mov_b64 s[2:3], s[8:9]
	s_cbranch_scc0 .LBB13_1336
	s_and_b64 vcc, exec, s[42:43]
	s_cbranch_vccz .LBB13_1339
	s_barrier

; __device__ __forceinline__ float swz_xor1(float v) { return __int_as_float(__builtin_amdgcn_ds_swizzle(__float_as_int(v), 0x041F)); }
; #define PG8_LAS __attribute__((address_space(3)))
; __device__ __forceinline__ float hsum4(const f32x4& a) { return (a[0] + a[1]) + (a[2] + a[3]); }
;     __device__ __forceinline__ void pre_finish(PG8_LAS unsigned char* lds, const Unit& u, int tid, const f32x4& q0, const f32x4& q1, const f32x4&) const {
;         const float s = hsum4(q0) + hsum4(q1), o = swz_xor1(s); const bool odd = tid & 1; const float sg = odd ? o : s, sa = odd ? s : o;
;         if (!odd) { f32x2 r; r.x = sqrtf((sa * (1.f / 512) + EPS) / (sg * (1.f / 512) + EPS)); r.y = rsqrtf(sa * (1.f / 512) + EPS);
;             *(PG8_LAS f32x2*)(lds + RSTAT_OFF + (u.ui & 1) * 2048 + (tid >> 1) * 8) = r; } }
.LBB13_1914:
	s_waitcnt vmcnt(24)
	v_add_f32_e32 v9, v4, v5
	v_add_f32_e32 v10, v6, v7
	v_add_f32_e32 v9, v9, v10
	v_add_f32_e32 v10, v0, v1
	v_add_f32_e32 v11, v2, v3
	v_add_f32_e32 v10, v10, v11
	v_add_f32_e32 v11, v9, v10
	ds_swizzle_b32 v10, v11 offset:swizzle(SWAP,1)
	s_and_saveexec_b64 s[6:7], s[4:5]
	s_xor_b64 s[6:7], exec, s[6:7]
	s_lshl_b32 s29, s27, 11
	s_and_b32 s29, s29, 0x800
	s_or_saveexec_b64 s[34:35], s[6:7]
	v_mov_b32_e32 v140, s29
	s_xor_b64 exec, exec, s[34:35]
	s_cbranch_execz .LBB13_1918
	s_waitcnt lgkmcnt(0)
	v_pk_fma_f32 v[10:11], v[10:11], s[24:25], v[180:181] op_sel_hi:[1,0,0]
	s_nop 0
	v_div_scale_f32 v9, s[6:7], v11, v11, v10
	v_rcp_f32_e32 v12, v9
	v_div_scale_f32 v13, vcc, v10, v11, v10
	v_fma_f32 v14, -v9, v12, 1.0
	v_fmac_f32_e32 v12, v14, v12
	v_mul_f32_e32 v14, v13, v12
	v_fma_f32 v15, -v9, v14, v13
	v_fmac_f32_e32 v14, v15, v12
	v_fma_f32 v9, -v9, v14, v13
	v_div_fmas_f32 v9, v9, v12, v14
	v_div_fixup_f32 v9, v9, v11, v10
	v_mul_f32_e32 v11, 0x4f800000, v9
	v_cmp_gt_f32_e32 vcc, s60, v9
	s_nop 1
	v_cndmask_b32_e32 v9, v9, v11, vcc
	v_sqrt_f32_e32 v11, v9
	s_nop 0
	v_add_u32_e32 v12, -1, v11
	v_fma_f32 v13, -v12, v11, v9
	v_cmp_ge_f32_e64 s[6:7], 0, v13
	v_add_u32_e32 v13, 1, v11
	s_nop 0
	v_cndmask_b32_e64 v12, v11, v12, s[6:7]
	v_fma_f32 v11, -v13, v11, v9
	v_cmp_lt_f32_e64 s[6:7], 0, v11
	s_nop 1
	v_cndmask_b32_e64 v11, v12, v13, s[6:7]
	v_mul_f32_e32 v13, 0x4b800000, v10
	v_cmp_gt_f32_e64 s[6:7], s61, v10
	v_mul_f32_e32 v12, 0x37800000, v11
	s_nop 0
	v_cndmask_b32_e64 v10, v10, v13, s[6:7]
	v_rsq_f32_e32 v13, v10
	v_cndmask_b32_e32 v10, v11, v12, vcc
	v_cmp_class_f32_e32 vcc, v9, v179
	s_nop 1
	v_cndmask_b32_e32 v10, v10, v9, vcc
	v_mul_f32_e32 v9, 0x45800000, v13
	v_cndmask_b32_e64 v11, v13, v9, s[6:7]
	s_lshl_b32 s6, s27, 11
	s_and_b32 s6, s6, 0x800
	v_add_u32_e32 v9, s6, v175
	v_mov_b32_e32 v140, s6
	ds_write_b64 v9, v[10:11]

;     __device__ float mid(int row) const { return rg(row) / ra(row); }
; #define PG8_STAGE(bufoff, gbase, voff) do { const char* gb_ = (const char*)(gbase); asm volatile("" : "+s"(gb_));     \
;         _Pragma("unroll") for (int _i = 0; _i < 2; ++_i) \
;         __builtin_amdgcn_global_load_lds((const unsigned*)(gb_ + (voff)[_i]), (PG8_LAS unsigned*)(lds + (bufoff) + ldsw + _i * 8192), 16, 0, 0); } while (0)
; #define PG8_LDA(dst, b, h) do { _Pragma("unroll") for (int m = 0; m < 4; ++m) _Pragma("unroll") for (int k = 0; k < 2; ++k) dst[m][k] = *(const PG8_LAS bf16x8*)(lds + PG8_SA(b, h) + aoff + m * 2048 + k * 1024); } while (0)
; #define PG8_LDB(dst, b, h) do { _Pragma("unroll") for (int n = 0; n < 2; ++n) _Pragma("unroll") for (int k = 0; k < 2; ++k) dst[n][k] = *(const PG8_LAS bf16x8*)(lds + PG8_SB(b, h) + boff + n * 2048 + k * 1024); } while (0)
; #define PG8_SCHED __builtin_amdgcn_sched_barrier(0)
; template <class Epi, class Sched, bool ALIGN_EPI = false, bool SP2 = false>
; __device__ __forceinline__ void gemm_phase(PG8_LAS unsigned char* lds, const Gemm g, const Sched& S, const Epi& E, int wid0) {
;     ...
;         for (int t = 0; t < nt; t += 2) {
;             const bool last = (t == nt - 2);
;             const char* a1 = cA + (size_t)(t + 1) * kstep;
;             const char* a2 = last ? nA : cA + (size_t)(t + 2) * kstep; const char* b2 = last ? nB : cB + (size_t)(t + 2) * kstep;
;             const char* a3 = a2 + kstep; const char* b3 = b2 + kstep;
;             if (last && has_next) S.a_ready(nxt);
;             if constexpr (Epi::HAS_MID) { if (t == Epi::MID_T) E.mid(acc, cur, wr, fr); }
;             unsigned vA_[2] = {voffA[0], voffA[1]}, vB_[2] = {voffB[0], voffB[1]};
;             asm volatile("" : "+v"(vA_[0]), "+v"(vA_[1]), "+v"(vB_[0]), "+v"(vB_[1]));
;             if constexpr (SP2) {
;             PG8_LDB(B0, 0, 0); PG8_LDB(B1, 0, 1); PG8_SCHED; PG8_LDA(At, 0, 0); PG8_STAGE(PG8_SA(1, 1), a1 + hstepA, vA_);
.LBB13_1920:
	v_mov_b32_e32 v9, v172
	v_mov_b32_e32 v170, v174
	v_mov_b32_e32 v171, v176
	v_mov_b32_e32 v182, v178
	v_add_u32_e32 v10, s62, v173
	ds_read_b128 v[142:145], v10
	ds_read_b128 v[146:149], v10 offset:1024
	ds_read_b128 v[150:153], v10 offset:2048
	ds_read_b128 v[154:157], v10 offset:3072
	v_add_u32_e32 v10, s63, v173
	s_add_u32 s6, s40, 0x100
	ds_read_b128 v[158:161], v10
	ds_read_b128 v[162:165], v10 offset:1024
	ds_read_b128 v[166:169], v10 offset:2048
	ds_read_b128 v[184:187], v10 offset:3072
	s_addc_u32 s7, s41, 0
	s_cmp_eq_u32 s68, 12
	s_cselect_b32 s48, s31, s6
	s_cselect_b32 s49, s27, s7
	s_cselect_b32 s43, s29, s67
	s_cselect_b32 s42, s65, s66
	s_add_u32 s44, s48, 0x80
	s_addc_u32 s45, s49, 0
	s_add_u32 s46, s42, 0x80
	s_addc_u32 s47, s43, 0
	s_add_u32 s40, s40, 0x80080
	s_addc_u32 s41, s41, 0
	s_add_i32 m0, s13, 0xc000
	ds_read_b128 v[188:191], v183
	ds_read_b128 v[192:195], v183 offset:1024
	ds_read_b128 v[196:199], v183 offset:2048
	ds_read_b128 v[200:203], v183 offset:3072
	ds_read_b128 v[204:207], v183 offset:4096
	ds_read_b128 v[208:211], v183 offset:5120
	ds_read_b128 v[212:215], v183 offset:6144
	ds_read_b128 v[216:219], v183 offset:7168
	s_nop 0
	global_load_lds_dwordx4 v9, s[40:41]
	s_add_i32 m0, s13, 0xe000
	s_nop 0
	global_load_lds_dwordx4 v171, s[40:41]
	s_cmp_lg_u32 s68, -2
	s_cbranch_scc1 .LoutB_w8_0
	s_cmp_eq_u32 s64, 1
	s_cbranch_scc1 .LoutB_w8_0
	s_waitcnt vmcnt(32)
	s_branch .LoutB_wd_0

; #define PG8_STAGE(bufoff, gbase, voff) do { const char* gb_ = (const char*)(gbase); asm volatile("" : "+s"(gb_));     \
;         _Pragma("unroll") for (int _i = 0; _i < 2; ++_i) \
;         __builtin_amdgcn_global_load_lds((const unsigned*)(gb_ + (voff)[_i]), (PG8_LAS unsigned*)(lds + (bufoff) + ldsw + _i * 8192), 16, 0, 0); } while (0)
; #define PG8_LDA(dst, b, h) do { _Pragma("unroll") for (int m = 0; m < 4; ++m) _Pragma("unroll") for (int k = 0; k < 2; ++k) dst[m][k] = *(const PG8_LAS bf16x8*)(lds + PG8_SA(b, h) + aoff + m * 2048 + k * 1024); } while (0)
; #define PG8_MMA(ai, bj, At, Bt) do { __builtin_amdgcn_s_setprio(1); _Pragma("unroll") for (int m = 0; m < 4; ++m) _Pragma("unroll") for (int n = 0; n < 2; ++n) _Pragma("unroll") for (int k = 0; k < 2; ++k) \
;         acc[ai][bj][m][n] = __builtin_amdgcn_mfma_f32_16x16x32_bf16(Bt[n][k], At[m][k], acc[ai][bj][m][n], 0, 0, 0); __builtin_amdgcn_s_setprio(0); } while (0)
; #define PG8_WAIT_V(n) asm volatile("s_waitcnt vmcnt(" #n ")" ::: "memory")
; #define PG8_WAIT_L(n) asm volatile("s_waitcnt lgkmcnt(" #n ")" ::: "memory")
; #define PG8_BAR __builtin_amdgcn_s_barrier()
; #define PG8_SCHED __builtin_amdgcn_sched_barrier(0)
; template <class Epi, class Sched, bool ALIGN_EPI = false, bool SP2 = false>
; __device__ __forceinline__ void gemm_phase(PG8_LAS unsigned char* lds, const Gemm g, const Sched& S, const Epi& E, int wid0) {
;     ...
;             PG8_WAIT_V(8); PG8_WAIT_L(0); PG8_BAR; PG8_MMA(0, 0, At, B0); PG8_MMA(0, 1, At, B1); PG8_BAR; PG8_SCHED;
;             PG8_LDA(At, 0, 1); PG8_STAGE(PG8_SB(0, 0), b2, vB_); PG8_STAGE(PG8_SB(0, 1), b2 + hstep, vB_); PG8_STAGE(PG8_SA(0, 0), a2, vA_);
.LoutB_wd_0:
	s_waitcnt lgkmcnt(0)
	s_barrier
	s_setprio 1
	s_waitcnt lgkmcnt(0)
	v_mfma_f32_16x16x32_bf16 v[136:139], v[142:145], v[188:191], v[136:139]
	v_mfma_f32_16x16x32_bf16 v[132:135], v[150:153], v[188:191], v[132:135]
	v_mfma_f32_16x16x32_bf16 v[128:131], v[142:145], v[196:199], v[128:131]
	v_mfma_f32_16x16x32_bf16 v[124:127], v[150:153], v[196:199], v[124:127]
	v_mfma_f32_16x16x32_bf16 v[120:123], v[142:145], v[204:207], v[120:123]
	v_mfma_f32_16x16x32_bf16 v[116:119], v[150:153], v[204:207], v[116:119]
	v_mfma_f32_16x16x32_bf16 v[112:115], v[142:145], v[212:215], v[112:115]
	v_mfma_f32_16x16x32_bf16 v[108:111], v[150:153], v[212:215], v[108:111]
	v_mfma_f32_16x16x32_bf16 v[136:139], v[146:149], v[192:195], v[136:139]
	v_mfma_f32_16x16x32_bf16 v[132:135], v[154:157], v[192:195], v[132:135]
	v_mfma_f32_16x16x32_bf16 v[128:131], v[146:149], v[200:203], v[128:131]
	v_mfma_f32_16x16x32_bf16 v[124:127], v[154:157], v[200:203], v[124:127]
	v_mfma_f32_16x16x32_bf16 v[120:123], v[146:149], v[208:211], v[120:123]
	v_mfma_f32_16x16x32_bf16 v[116:119], v[154:157], v[208:211], v[116:119]
	v_mfma_f32_16x16x32_bf16 v[112:115], v[146:149], v[216:219], v[112:115]
	v_mfma_f32_16x16x32_bf16 v[108:111], v[154:157], v[216:219], v[108:111]
	s_setprio 0
	s_setprio 1
	v_mfma_f32_16x16x32_bf16 v[72:75], v[158:161], v[188:191], v[72:75]
	v_mfma_f32_16x16x32_bf16 v[68:71], v[166:169], v[188:191], v[68:71]
	v_mfma_f32_16x16x32_bf16 v[64:67], v[158:161], v[196:199], v[64:67]
	v_mfma_f32_16x16x32_bf16 v[60:63], v[166:169], v[196:199], v[60:63]
	v_mfma_f32_16x16x32_bf16 v[56:59], v[158:161], v[204:207], v[56:59]
	v_mfma_f32_16x16x32_bf16 v[52:55], v[166:169], v[204:207], v[52:55]
	v_mfma_f32_16x16x32_bf16 v[48:51], v[158:161], v[212:215], v[48:51]
	v_mfma_f32_16x16x32_bf16 v[44:47], v[166:169], v[212:215], v[44:47]
	v_mfma_f32_16x16x32_bf16 v[72:75], v[162:165], v[192:195], v[72:75]
	v_mfma_f32_16x16x32_bf16 v[68:71], v[184:187], v[192:195], v[68:71]
	v_mfma_f32_16x16x32_bf16 v[64:67], v[162:165], v[200:203], v[64:67]
	v_mfma_f32_16x16x32_bf16 v[60:63], v[184:187], v[200:203], v[60:63]
	v_mfma_f32_16x16x32_bf16 v[56:59], v[162:165], v[208:211], v[56:59]
	v_mfma_f32_16x16x32_bf16 v[52:55], v[184:187], v[208:211], v[52:55]
	v_mfma_f32_16x16x32_bf16 v[48:51], v[162:165], v[216:219], v[48:51]
	v_mfma_f32_16x16x32_bf16 v[44:47], v[184:187], v[216:219], v[44:47]
	s_setprio 0
	s_barrier
	s_add_i32 s69, s62, s25
	s_mov_b64 s[40:41], s[42:43]
	s_mov_b32 m0, s69
	ds_read_b128 v[188:191], v183 offset:16384
	ds_read_b128 v[192:195], v183 offset:17408
	ds_read_b128 v[196:199], v183 offset:18432
	ds_read_b128 v[200:203], v183 offset:19456
	ds_read_b128 v[204:207], v183 offset:20480
	ds_read_b128 v[208:211], v183 offset:21504
	ds_read_b128 v[212:215], v183 offset:22528
	ds_read_b128 v[216:219], v183 offset:23552
	s_nop 0
	global_load_lds_dwordx4 v170, s[40:41]
	s_add_i32 m0, s69, 0x2000
	s_nop 0
	global_load_lds_dwordx4 v182, s[40:41]
	s_add_u32 s40, s42, 0x40000
	s_addc_u32 s41, s43, 0
	s_add_i32 s69, s63, s25
	s_mov_b32 m0, s69
	s_nop 0
	global_load_lds_dwordx4 v170, s[40:41]
	s_add_i32 m0, s69, 0x2000
	s_nop 0
	global_load_lds_dwordx4 v182, s[40:41]
	s_mov_b64 s[40:41], s[48:49]
	s_mov_b32 m0, s13
	s_nop 0
	global_load_lds_dwordx4 v9, s[40:41]
	s_mov_b32 m0, s51
	s_nop 0
	global_load_lds_dwordx4 v171, s[40:41]
	s_cmp_lg_u32 s68, -2
	s_cbranch_scc1 .LoutB_w8_1
	s_cmp_eq_u32 s64, 1
	s_cbranch_scc1 .LoutB_w8_1
	s_waitcnt vmcnt(32)
	s_branch .LoutB_wd_1

; #define PG8_STAGE(bufoff, gbase, voff) do { const char* gb_ = (const char*)(gbase); asm volatile("" : "+s"(gb_));     \
;         _Pragma("unroll") for (int _i = 0; _i < 2; ++_i) \
;         __builtin_amdgcn_global_load_lds((const unsigned*)(gb_ + (voff)[_i]), (PG8_LAS unsigned*)(lds + (bufoff) + ldsw + _i * 8192), 16, 0, 0); } while (0)
; #define PG8_LDA(dst, b, h) do { _Pragma("unroll") for (int m = 0; m < 4; ++m) _Pragma("unroll") for (int k = 0; k < 2; ++k) dst[m][k] = *(const PG8_LAS bf16x8*)(lds + PG8_SA(b, h) + aoff + m * 2048 + k * 1024); } while (0)
; #define PG8_LDB(dst, b, h) do { _Pragma("unroll") for (int n = 0; n < 2; ++n) _Pragma("unroll") for (int k = 0; k < 2; ++k) dst[n][k] = *(const PG8_LAS bf16x8*)(lds + PG8_SB(b, h) + boff + n * 2048 + k * 1024); } while (0)
; #define PG8_MMA(ai, bj, At, Bt) do { __builtin_amdgcn_s_setprio(1); _Pragma("unroll") for (int m = 0; m < 4; ++m) _Pragma("unroll") for (int n = 0; n < 2; ++n) _Pragma("unroll") for (int k = 0; k < 2; ++k) \
;         acc[ai][bj][m][n] = __builtin_amdgcn_mfma_f32_16x16x32_bf16(Bt[n][k], At[m][k], acc[ai][bj][m][n], 0, 0, 0); __builtin_amdgcn_s_setprio(0); } while (0)
; #define PG8_WAIT_V(n) asm volatile("s_waitcnt vmcnt(" #n ")" ::: "memory")
; #define PG8_WAIT_L(n) asm volatile("s_waitcnt lgkmcnt(" #n ")" ::: "memory")
; #define PG8_BAR __builtin_amdgcn_s_barrier()
; #define PG8_SCHED __builtin_amdgcn_sched_barrier(0)
; template <class Epi, class Sched, bool ALIGN_EPI = false, bool SP2 = false>
; __device__ __forceinline__ void gemm_phase(PG8_LAS unsigned char* lds, const Gemm g, const Sched& S, const Epi& E, int wid0) {
;     ...
;             PG8_WAIT_V(8); PG8_WAIT_L(0); PG8_BAR; PG8_MMA(1, 0, At, B0); PG8_MMA(1, 1, At, B1); PG8_BAR; PG8_SCHED;
;             PG8_LDB(B0, 1, 0); PG8_LDB(B1, 1, 1); PG8_SCHED; PG8_LDA(At, 1, 0); PG8_STAGE(PG8_SA(0, 1), a2 + hstepA, vA_);
;             PG8_WAIT_V(8); PG8_WAIT_L(0); PG8_BAR; PG8_MMA(0, 0, At, B0); PG8_MMA(0, 1, At, B1); PG8_BAR; PG8_SCHED;
.LoutB_wd_1:
	s_waitcnt lgkmcnt(0)
	s_barrier
	s_setprio 1
	s_waitcnt lgkmcnt(0)
	v_mfma_f32_16x16x32_bf16 v[104:107], v[142:145], v[188:191], v[104:107]
	v_mfma_f32_16x16x32_bf16 v[100:103], v[150:153], v[188:191], v[100:103]
	v_mfma_f32_16x16x32_bf16 v[96:99], v[142:145], v[196:199], v[96:99]
	v_mfma_f32_16x16x32_bf16 v[92:95], v[150:153], v[196:199], v[92:95]
	v_mfma_f32_16x16x32_bf16 v[88:91], v[142:145], v[204:207], v[88:91]
	v_mfma_f32_16x16x32_bf16 v[84:87], v[150:153], v[204:207], v[84:87]
	v_mfma_f32_16x16x32_bf16 v[80:83], v[142:145], v[212:215], v[80:83]
	v_mfma_f32_16x16x32_bf16 v[76:79], v[150:153], v[212:215], v[76:79]
	v_mfma_f32_16x16x32_bf16 v[104:107], v[146:149], v[192:195], v[104:107]
	v_mfma_f32_16x16x32_bf16 v[100:103], v[154:157], v[192:195], v[100:103]
	v_mfma_f32_16x16x32_bf16 v[96:99], v[146:149], v[200:203], v[96:99]
	v_mfma_f32_16x16x32_bf16 v[92:95], v[154:157], v[200:203], v[92:95]
	v_mfma_f32_16x16x32_bf16 v[88:91], v[146:149], v[208:211], v[88:91]
	v_mfma_f32_16x16x32_bf16 v[84:87], v[154:157], v[208:211], v[84:87]
	v_mfma_f32_16x16x32_bf16 v[80:83], v[146:149], v[216:219], v[80:83]
	v_mfma_f32_16x16x32_bf16 v[76:79], v[154:157], v[216:219], v[76:79]
	s_setprio 0
	s_setprio 1
	v_mfma_f32_16x16x32_bf16 v[40:43], v[158:161], v[188:191], v[40:43]
	v_mfma_f32_16x16x32_bf16 v[36:39], v[166:169], v[188:191], v[36:39]
	v_mfma_f32_16x16x32_bf16 v[32:35], v[158:161], v[196:199], v[32:35]
	v_mfma_f32_16x16x32_bf16 v[28:31], v[166:169], v[196:199], v[28:31]
	v_mfma_f32_16x16x32_bf16 v[24:27], v[158:161], v[204:207], v[24:27]
	v_mfma_f32_16x16x32_bf16 v[20:23], v[166:169], v[204:207], v[20:23]
	v_mfma_f32_16x16x32_bf16 v[16:19], v[158:161], v[212:215], v[16:19]
	v_mfma_f32_16x16x32_bf16 v[10:13], v[166:169], v[212:215], v[12:15]
	v_mfma_f32_16x16x32_bf16 v[40:43], v[162:165], v[192:195], v[40:43]
	v_mfma_f32_16x16x32_bf16 v[36:39], v[184:187], v[192:195], v[36:39]
	v_mfma_f32_16x16x32_bf16 v[32:35], v[162:165], v[200:203], v[32:35]
	v_mfma_f32_16x16x32_bf16 v[28:31], v[184:187], v[200:203], v[28:31]
	v_mfma_f32_16x16x32_bf16 v[24:27], v[162:165], v[208:211], v[24:27]
	v_mfma_f32_16x16x32_bf16 v[20:23], v[184:187], v[208:211], v[20:23]
	v_mfma_f32_16x16x32_bf16 v[16:19], v[162:165], v[216:219], v[16:19]
	v_mfma_f32_16x16x32_bf16 v[10:13], v[184:187], v[216:219], v[10:13]
	s_setprio 0
	s_barrier
	s_add_i32 s69, 0, 0x18000
	v_add_u32_e32 v14, s69, v173
	s_add_i32 s70, 0, 0x1c000
	ds_read_b128 v[142:145], v14
	ds_read_b128 v[146:149], v14 offset:1024
	ds_read_b128 v[150:153], v14 offset:2048
	ds_read_b128 v[154:157], v14 offset:3072
	v_add_u32_e32 v14, s70, v173
	ds_read_b128 v[158:161], v14
	ds_read_b128 v[162:165], v14 offset:1024
	ds_read_b128 v[166:169], v14 offset:2048
	ds_read_b128 v[184:187], v14 offset:3072
	s_add_u32 s40, s48, 0x80000
	s_addc_u32 s41, s49, 0
	s_mov_b32 m0, s52
	ds_read_b128 v[188:191], v183 offset:32768
	ds_read_b128 v[192:195], v183 offset:33792
	ds_read_b128 v[196:199], v183 offset:34816
	ds_read_b128 v[200:203], v183 offset:35840
	ds_read_b128 v[204:207], v183 offset:36864
	ds_read_b128 v[208:211], v183 offset:37888
	ds_read_b128 v[212:215], v183 offset:38912
	ds_read_b128 v[216:219], v183 offset:39936
	s_nop 0
	global_load_lds_dwordx4 v9, s[40:41]
	s_mov_b32 m0, s53
	s_nop 0
	global_load_lds_dwordx4 v171, s[40:41]
	s_waitcnt vmcnt(8)
	s_waitcnt lgkmcnt(0)
	s_barrier
	s_setprio 1
	s_waitcnt lgkmcnt(0)
	v_mfma_f32_16x16x32_bf16 v[136:139], v[142:145], v[188:191], v[136:139]
	v_mfma_f32_16x16x32_bf16 v[132:135], v[150:153], v[188:191], v[132:135]
	v_mfma_f32_16x16x32_bf16 v[128:131], v[142:145], v[196:199], v[128:131]
	v_mfma_f32_16x16x32_bf16 v[124:127], v[150:153], v[196:199], v[124:127]
	v_mfma_f32_16x16x32_bf16 v[120:123], v[142:145], v[204:207], v[120:123]
	v_mfma_f32_16x16x32_bf16 v[116:119], v[150:153], v[204:207], v[116:119]
	v_mfma_f32_16x16x32_bf16 v[112:115], v[142:145], v[212:215], v[112:115]
	v_mfma_f32_16x16x32_bf16 v[108:111], v[150:153], v[212:215], v[108:111]
	v_mfma_f32_16x16x32_bf16 v[136:139], v[146:149], v[192:195], v[136:139]
	v_mfma_f32_16x16x32_bf16 v[132:135], v[154:157], v[192:195], v[132:135]
	v_mfma_f32_16x16x32_bf16 v[128:131], v[146:149], v[200:203], v[128:131]
	v_mfma_f32_16x16x32_bf16 v[124:127], v[154:157], v[200:203], v[124:127]
	v_mfma_f32_16x16x32_bf16 v[120:123], v[146:149], v[208:211], v[120:123]
	v_mfma_f32_16x16x32_bf16 v[116:119], v[154:157], v[208:211], v[116:119]
	v_mfma_f32_16x16x32_bf16 v[112:115], v[146:149], v[216:219], v[112:115]
	v_mfma_f32_16x16x32_bf16 v[108:111], v[154:157], v[216:219], v[108:111]
	s_setprio 0
	s_setprio 1
	v_mfma_f32_16x16x32_bf16 v[72:75], v[158:161], v[188:191], v[72:75]
	v_mfma_f32_16x16x32_bf16 v[68:71], v[166:169], v[188:191], v[68:71]
	v_mfma_f32_16x16x32_bf16 v[64:67], v[158:161], v[196:199], v[64:67]
	v_mfma_f32_16x16x32_bf16 v[60:63], v[166:169], v[196:199], v[60:63]
	v_mfma_f32_16x16x32_bf16 v[56:59], v[158:161], v[204:207], v[56:59]
	v_mfma_f32_16x16x32_bf16 v[52:55], v[166:169], v[204:207], v[52:55]
	v_mfma_f32_16x16x32_bf16 v[48:51], v[158:161], v[212:215], v[48:51]
	v_mfma_f32_16x16x32_bf16 v[44:47], v[166:169], v[212:215], v[44:47]
	v_mfma_f32_16x16x32_bf16 v[72:75], v[162:165], v[192:195], v[72:75]
	v_mfma_f32_16x16x32_bf16 v[68:71], v[184:187], v[192:195], v[68:71]
	v_mfma_f32_16x16x32_bf16 v[64:67], v[162:165], v[200:203], v[64:67]
	v_mfma_f32_16x16x32_bf16 v[60:63], v[184:187], v[200:203], v[60:63]
	v_mfma_f32_16x16x32_bf16 v[56:59], v[162:165], v[208:211], v[56:59]
	v_mfma_f32_16x16x32_bf16 v[52:55], v[184:187], v[208:211], v[52:55]
	v_mfma_f32_16x16x32_bf16 v[48:51], v[162:165], v[216:219], v[48:51]
	v_mfma_f32_16x16x32_bf16 v[44:47], v[184:187], v[216:219], v[44:47]
	s_setprio 0
	s_barrier
; #define PG8_STAGE(bufoff, gbase, voff) do { const char* gb_ = (const char*)(gbase); asm volatile("" : "+s"(gb_));     \
;         _Pragma("unroll") for (int _i = 0; _i < 2; ++_i) \
;         __builtin_amdgcn_global_load_lds((const unsigned*)(gb_ + (voff)[_i]), (PG8_LAS unsigned*)(lds + (bufoff) + ldsw + _i * 8192), 16, 0, 0); } while (0)
; #define PG8_LDA(dst, b, h) do { _Pragma("unroll") for (int m = 0; m < 4; ++m) _Pragma("unroll") for (int k = 0; k < 2; ++k) dst[m][k] = *(const PG8_LAS bf16x8*)(lds + PG8_SA(b, h) + aoff + m * 2048 + k * 1024); } while (0)
; #define PG8_MMA(ai, bj, At, Bt) do { __builtin_amdgcn_s_setprio(1); _Pragma("unroll") for (int m = 0; m < 4; ++m) _Pragma("unroll") for (int n = 0; n < 2; ++n) _Pragma("unroll") for (int k = 0; k < 2; ++k) \
;         acc[ai][bj][m][n] = __builtin_amdgcn_mfma_f32_16x16x32_bf16(Bt[n][k], At[m][k], acc[ai][bj][m][n], 0, 0, 0); __builtin_amdgcn_s_setprio(0); } while (0)
; #define PG8_WAIT_V(n) asm volatile("s_waitcnt vmcnt(" #n ")" ::: "memory")
; #define PG8_WAIT_L(n) asm volatile("s_waitcnt lgkmcnt(" #n ")" ::: "memory")
; #define PG8_BAR __builtin_amdgcn_s_barrier()
; #define PG8_SCHED __builtin_amdgcn_sched_barrier(0)
; template <class Epi, class Sched, bool ALIGN_EPI = false, bool SP2 = false>
; __device__ __forceinline__ void gemm_phase(PG8_LAS unsigned char* lds, const Gemm g, const Sched& S, const Epi& E, int wid0) {
;     ...
;         for (int t = 0; t < nt; t += 2) {
;     ...
;             PG8_LDA(At, 1, 1); PG8_STAGE(PG8_SB(1, 0), b3, vB_); PG8_STAGE(PG8_SB(1, 1), b3 + hstep, vB_); PG8_STAGE(PG8_SA(1, 0), a3, vA_);
;             PG8_WAIT_V(8); PG8_WAIT_L(0); PG8_BAR; PG8_MMA(1, 0, At, B0); PG8_MMA(1, 1, At, B1); PG8_BAR; PG8_SCHED;
	s_add_i32 s40, s69, s25
	s_mov_b32 m0, s40
	ds_read_b128 v[188:191], v183 offset:49152
	ds_read_b128 v[192:195], v183 offset:50176
	ds_read_b128 v[196:199], v183 offset:51200
	ds_read_b128 v[200:203], v183 offset:52224
	ds_read_b128 v[204:207], v183 offset:53248
	ds_read_b128 v[208:211], v183 offset:54272
	ds_read_b128 v[212:215], v183 offset:55296
	ds_read_b128 v[216:219], v183 offset:56320
	s_nop 0
	global_load_lds_dwordx4 v170, s[46:47]
	s_add_i32 m0, s40, 0x2000
	s_add_u32 s40, s42, 0x40080
	s_addc_u32 s41, s43, 0
	s_add_i32 s42, s70, s25
	global_load_lds_dwordx4 v182, s[46:47]
	s_mov_b32 m0, s42
	s_nop 0
	global_load_lds_dwordx4 v170, s[40:41]
	s_add_i32 m0, s42, 0x2000
	s_nop 0
	global_load_lds_dwordx4 v182, s[40:41]
	s_mov_b32 m0, s57
	s_nop 0
	global_load_lds_dwordx4 v9, s[44:45]
	s_mov_b32 m0, s58
	s_nop 0
	global_load_lds_dwordx4 v171, s[44:45]
	s_waitcnt vmcnt(8)
	s_waitcnt lgkmcnt(0)
	s_barrier
	s_setprio 1
	s_waitcnt lgkmcnt(0)
	v_mfma_f32_16x16x32_bf16 v[104:107], v[142:145], v[188:191], v[104:107]
	v_mfma_f32_16x16x32_bf16 v[100:103], v[150:153], v[188:191], v[100:103]
	v_mfma_f32_16x16x32_bf16 v[96:99], v[142:145], v[196:199], v[96:99]
	v_mfma_f32_16x16x32_bf16 v[92:95], v[150:153], v[196:199], v[92:95]
	v_mfma_f32_16x16x32_bf16 v[88:91], v[142:145], v[204:207], v[88:91]
	v_mfma_f32_16x16x32_bf16 v[84:87], v[150:153], v[204:207], v[84:87]
	v_mfma_f32_16x16x32_bf16 v[80:83], v[142:145], v[212:215], v[80:83]
	v_mfma_f32_16x16x32_bf16 v[76:79], v[150:153], v[212:215], v[76:79]
	v_mfma_f32_16x16x32_bf16 v[104:107], v[146:149], v[192:195], v[104:107]
	v_mfma_f32_16x16x32_bf16 v[100:103], v[154:157], v[192:195], v[100:103]
	v_mfma_f32_16x16x32_bf16 v[96:99], v[146:149], v[200:203], v[96:99]
	v_mfma_f32_16x16x32_bf16 v[92:95], v[154:157], v[200:203], v[92:95]
	v_mfma_f32_16x16x32_bf16 v[88:91], v[146:149], v[208:211], v[88:91]
	v_mfma_f32_16x16x32_bf16 v[84:87], v[154:157], v[208:211], v[84:87]
	v_mfma_f32_16x16x32_bf16 v[80:83], v[146:149], v[216:219], v[80:83]
	v_mfma_f32_16x16x32_bf16 v[76:79], v[154:157], v[216:219], v[76:79]
	s_setprio 0
	s_setprio 1
	v_mfma_f32_16x16x32_bf16 v[40:43], v[158:161], v[188:191], v[40:43]
	v_mfma_f32_16x16x32_bf16 v[36:39], v[166:169], v[188:191], v[36:39]
	v_mfma_f32_16x16x32_bf16 v[32:35], v[158:161], v[196:199], v[32:35]
	v_mfma_f32_16x16x32_bf16 v[28:31], v[166:169], v[196:199], v[28:31]
	v_mfma_f32_16x16x32_bf16 v[24:27], v[158:161], v[204:207], v[24:27]
	v_mfma_f32_16x16x32_bf16 v[20:23], v[166:169], v[204:207], v[20:23]
	v_mfma_f32_16x16x32_bf16 v[14:17], v[158:161], v[212:215], v[16:19]
	v_mfma_f32_16x16x32_bf16 v[10:13], v[166:169], v[212:215], v[10:13]
	v_mfma_f32_16x16x32_bf16 v[40:43], v[162:165], v[192:195], v[40:43]
	v_mfma_f32_16x16x32_bf16 v[36:39], v[184:187], v[192:195], v[36:39]
	v_mfma_f32_16x16x32_bf16 v[32:35], v[162:165], v[200:203], v[32:35]
	v_mfma_f32_16x16x32_bf16 v[28:31], v[184:187], v[200:203], v[28:31]
	v_mfma_f32_16x16x32_bf16 v[24:27], v[162:165], v[208:211], v[24:27]
	v_mfma_f32_16x16x32_bf16 v[20:23], v[184:187], v[208:211], v[20:23]
	v_mfma_f32_16x16x32_bf16 v[16:19], v[162:165], v[216:219], v[14:17]
	v_mfma_f32_16x16x32_bf16 v[12:15], v[184:187], v[216:219], v[10:13]
	s_setprio 0
	s_barrier
	s_add_i32 s68, s68, 2
	s_add_u32 s66, s66, 0x100
	s_addc_u32 s67, s67, 0
	s_cmp_gt_u32 s68, 13
	s_cbranch_scc1 .LBB13_1922
	s_mov_b64 s[40:41], s[6:7]
	s_cmp_lg_u32 s68, 6
	s_cbranch_scc0 .LBB13_1919
	s_branch .LBB13_1920

;     __device__ float mid(int row) const { return rg(row) / ra(row); }
; #define PG8_STAGE(bufoff, gbase, voff) do { const char* gb_ = (const char*)(gbase); asm volatile("" : "+s"(gb_));     \
;         _Pragma("unroll") for (int _i = 0; _i < 2; ++_i) \
;         __builtin_amdgcn_global_load_lds((const unsigned*)(gb_ + (voff)[_i]), (PG8_LAS unsigned*)(lds + (bufoff) + ldsw + _i * 8192), 16, 0, 0); } while (0)
; #define PG8_LDA(dst, b, h) do { _Pragma("unroll") for (int m = 0; m < 4; ++m) _Pragma("unroll") for (int k = 0; k < 2; ++k) dst[m][k] = *(const PG8_LAS bf16x8*)(lds + PG8_SA(b, h) + aoff + m * 2048 + k * 1024); } while (0)
; #define PG8_LDB(dst, b, h) do { _Pragma("unroll") for (int n = 0; n < 2; ++n) _Pragma("unroll") for (int k = 0; k < 2; ++k) dst[n][k] = *(const PG8_LAS bf16x8*)(lds + PG8_SB(b, h) + boff + n * 2048 + k * 1024); } while (0)
; #define PG8_SCHED __builtin_amdgcn_sched_barrier(0)
; template <class Epi, class Sched, bool ALIGN_EPI = false, bool SP2 = false>
; __device__ __forceinline__ void gemm_phase(PG8_LAS unsigned char* lds, const Gemm g, const Sched& S, const Epi& E, int wid0) {
;     ...
;         for (int t = 0; t < nt; t += 2) {
;             const bool last = (t == nt - 2);
;             const char* a1 = cA + (size_t)(t + 1) * kstep;
;             const char* a2 = last ? nA : cA + (size_t)(t + 2) * kstep; const char* b2 = last ? nB : cB + (size_t)(t + 2) * kstep;
;             const char* a3 = a2 + kstep; const char* b3 = b2 + kstep;
;             if (last && has_next) S.a_ready(nxt);
;             if constexpr (Epi::HAS_MID) { if (t == Epi::MID_T) E.mid(acc, cur, wr, fr); }
;             unsigned vA_[2] = {voffA[0], voffA[1]}, vB_[2] = {voffB[0], voffB[1]};
;             asm volatile("" : "+v"(vA_[0]), "+v"(vA_[1]), "+v"(vB_[0]), "+v"(vB_[1]));
;             if constexpr (SP2) {
;             PG8_LDB(B0, 0, 0); PG8_LDB(B1, 0, 1); PG8_SCHED; PG8_LDA(At, 0, 0); PG8_STAGE(PG8_SA(1, 1), a1 + hstepA, vA_);
.LBB13_2163:
	v_mov_b32_e32 v202, v150
	v_mov_b32_e32 v203, v152
	v_mov_b32_e32 v204, v154
	v_mov_b32_e32 v205, v148
	ds_read_b128 v[128:131], v153
	ds_read_b128 v[132:135], v153 offset:1024
	ds_read_b128 v[136:139], v153 offset:2048
	ds_read_b128 v[140:143], v153 offset:3072
	ds_read_b128 v[144:147], v155
	ds_read_b128 v[158:161], v155 offset:1024
	ds_read_b128 v[162:165], v155 offset:2048
	ds_read_b128 v[166:169], v155 offset:3072
	s_add_u32 s26, s24, 0x100
	s_addc_u32 s27, s25, 0
	s_cmp_eq_u32 s53, 60
	s_cselect_b32 s34, s49, s26
	s_cselect_b32 s35, s11, s27
	s_cselect_b32 s30, s50, s51
	s_cselect_b32 s31, s13, s52
	s_add_u32 s28, s34, 0x80
	s_addc_u32 s29, s35, 0
	s_add_u32 s24, s24, 0x100080
	s_addc_u32 s25, s25, 0
	s_add_i32 m0, s21, 0xc000
	ds_read_b128 v[170:173], v156
	ds_read_b128 v[174:177], v156 offset:1024
	ds_read_b128 v[178:181], v156 offset:2048
	ds_read_b128 v[182:185], v156 offset:3072
	ds_read_b128 v[186:189], v156 offset:4096
	ds_read_b128 v[190:193], v156 offset:5120
	ds_read_b128 v[194:197], v156 offset:6144
	ds_read_b128 v[198:201], v156 offset:7168
	s_nop 0
	global_load_lds_dwordx4 v205, s[24:25]
	s_add_i32 m0, s21, 0xe000
	s_nop 0
	global_load_lds_dwordx4 v203, s[24:25]
	s_cmp_lg_u32 s53, -2
	s_cbranch_scc1 .Lff2B_w8_0
	s_cmp_eq_u32 s42, 1
	s_cbranch_scc1 .Lff2B_w8_0
	s_waitcnt vmcnt(16)
	s_branch .Lff2B_wd_0

; #define PG8_STAGE(bufoff, gbase, voff) do { const char* gb_ = (const char*)(gbase); asm volatile("" : "+s"(gb_));     \
;         _Pragma("unroll") for (int _i = 0; _i < 2; ++_i) \
;         __builtin_amdgcn_global_load_lds((const unsigned*)(gb_ + (voff)[_i]), (PG8_LAS unsigned*)(lds + (bufoff) + ldsw + _i * 8192), 16, 0, 0); } while (0)
; #define PG8_LDA(dst, b, h) do { _Pragma("unroll") for (int m = 0; m < 4; ++m) _Pragma("unroll") for (int k = 0; k < 2; ++k) dst[m][k] = *(const PG8_LAS bf16x8*)(lds + PG8_SA(b, h) + aoff + m * 2048 + k * 1024); } while (0)
; #define PG8_MMA(ai, bj, At, Bt) do { __builtin_amdgcn_s_setprio(1); _Pragma("unroll") for (int m = 0; m < 4; ++m) _Pragma("unroll") for (int n = 0; n < 2; ++n) _Pragma("unroll") for (int k = 0; k < 2; ++k) \
;         acc[ai][bj][m][n] = __builtin_amdgcn_mfma_f32_16x16x32_bf16(Bt[n][k], At[m][k], acc[ai][bj][m][n], 0, 0, 0); __builtin_amdgcn_s_setprio(0); } while (0)
; #define PG8_WAIT_V(n) asm volatile("s_waitcnt vmcnt(" #n ")" ::: "memory")
; #define PG8_WAIT_L(n) asm volatile("s_waitcnt lgkmcnt(" #n ")" ::: "memory")
; #define PG8_BAR __builtin_amdgcn_s_barrier()
; #define PG8_SCHED __builtin_amdgcn_sched_barrier(0)
; template <class Epi, class Sched, bool ALIGN_EPI = false, bool SP2 = false>
; __device__ __forceinline__ void gemm_phase(PG8_LAS unsigned char* lds, const Gemm g, const Sched& S, const Epi& E, int wid0) {
;     ...
;             PG8_WAIT_V(8); PG8_WAIT_L(0); PG8_BAR; PG8_MMA(0, 0, At, B0); PG8_MMA(0, 1, At, B1); PG8_BAR; PG8_SCHED;
;             PG8_LDA(At, 0, 1); PG8_STAGE(PG8_SB(0, 0), b2, vB_); PG8_STAGE(PG8_SB(0, 1), b2 + hstep, vB_); PG8_STAGE(PG8_SA(0, 0), a2, vA_);
.Lff2B_wd_0:
	s_waitcnt lgkmcnt(0)
	s_barrier
	s_setprio 1
	s_waitcnt lgkmcnt(0)
	v_mfma_f32_16x16x32_bf16 v[124:127], v[128:131], v[170:173], v[124:127]
	v_mfma_f32_16x16x32_bf16 v[120:123], v[136:139], v[170:173], v[120:123]
	v_mfma_f32_16x16x32_bf16 v[116:119], v[128:131], v[178:181], v[116:119]
	v_mfma_f32_16x16x32_bf16 v[112:115], v[136:139], v[178:181], v[112:115]
	v_mfma_f32_16x16x32_bf16 v[108:111], v[128:131], v[186:189], v[108:111]
	v_mfma_f32_16x16x32_bf16 v[104:107], v[136:139], v[186:189], v[104:107]
	v_mfma_f32_16x16x32_bf16 v[100:103], v[128:131], v[194:197], v[100:103]
	v_mfma_f32_16x16x32_bf16 v[96:99], v[136:139], v[194:197], v[96:99]
	v_mfma_f32_16x16x32_bf16 v[124:127], v[132:135], v[174:177], v[124:127]
	v_mfma_f32_16x16x32_bf16 v[120:123], v[140:143], v[174:177], v[120:123]
	v_mfma_f32_16x16x32_bf16 v[116:119], v[132:135], v[182:185], v[116:119]
	v_mfma_f32_16x16x32_bf16 v[112:115], v[140:143], v[182:185], v[112:115]
	v_mfma_f32_16x16x32_bf16 v[108:111], v[132:135], v[190:193], v[108:111]
	v_mfma_f32_16x16x32_bf16 v[104:107], v[140:143], v[190:193], v[104:107]
	v_mfma_f32_16x16x32_bf16 v[100:103], v[132:135], v[198:201], v[100:103]
	v_mfma_f32_16x16x32_bf16 v[96:99], v[140:143], v[198:201], v[96:99]
	s_setprio 0
	s_setprio 1
	v_mfma_f32_16x16x32_bf16 v[60:63], v[144:147], v[170:173], v[60:63]
	v_mfma_f32_16x16x32_bf16 v[56:59], v[162:165], v[170:173], v[56:59]
	v_mfma_f32_16x16x32_bf16 v[52:55], v[144:147], v[178:181], v[52:55]
	v_mfma_f32_16x16x32_bf16 v[48:51], v[162:165], v[178:181], v[48:51]
	v_mfma_f32_16x16x32_bf16 v[44:47], v[144:147], v[186:189], v[44:47]
	v_mfma_f32_16x16x32_bf16 v[40:43], v[162:165], v[186:189], v[40:43]
	v_mfma_f32_16x16x32_bf16 v[36:39], v[144:147], v[194:197], v[36:39]
	v_mfma_f32_16x16x32_bf16 v[32:35], v[162:165], v[194:197], v[32:35]
	v_mfma_f32_16x16x32_bf16 v[60:63], v[158:161], v[174:177], v[60:63]
	v_mfma_f32_16x16x32_bf16 v[56:59], v[166:169], v[174:177], v[56:59]
	v_mfma_f32_16x16x32_bf16 v[52:55], v[158:161], v[182:185], v[52:55]
	v_mfma_f32_16x16x32_bf16 v[48:51], v[166:169], v[182:185], v[48:51]
	v_mfma_f32_16x16x32_bf16 v[44:47], v[158:161], v[190:193], v[44:47]
	v_mfma_f32_16x16x32_bf16 v[40:43], v[166:169], v[190:193], v[40:43]
	v_mfma_f32_16x16x32_bf16 v[36:39], v[158:161], v[198:201], v[36:39]
	v_mfma_f32_16x16x32_bf16 v[32:35], v[166:169], v[198:201], v[32:35]
	s_setprio 0
	s_barrier
	s_add_i32 s54, s47, s33
	s_mov_b64 s[24:25], s[30:31]
	s_mov_b32 m0, s54
	ds_read_b128 v[170:173], v156 offset:16384
	ds_read_b128 v[174:177], v156 offset:17408
	ds_read_b128 v[178:181], v156 offset:18432
	ds_read_b128 v[182:185], v156 offset:19456
	ds_read_b128 v[186:189], v156 offset:20480
	ds_read_b128 v[190:193], v156 offset:21504
	ds_read_b128 v[194:197], v156 offset:22528
	ds_read_b128 v[198:201], v156 offset:23552
	s_nop 0
	global_load_lds_dwordx4 v202, s[24:25]
	s_add_i32 m0, s54, 0x2000
	s_nop 0
	global_load_lds_dwordx4 v204, s[24:25]
	s_add_u32 s24, s30, 0x100000
	s_addc_u32 s25, s31, 0
	s_add_i32 s54, s48, s33
	s_mov_b32 m0, s54
	s_nop 0
	global_load_lds_dwordx4 v202, s[24:25]
	s_add_i32 m0, s54, 0x2000
	s_nop 0
	global_load_lds_dwordx4 v204, s[24:25]
	s_mov_b64 s[24:25], s[34:35]
	s_mov_b32 m0, s21
	s_nop 0
	global_load_lds_dwordx4 v205, s[24:25]
	s_mov_b32 m0, s23
	s_nop 0
	global_load_lds_dwordx4 v203, s[24:25]
	s_cmp_lg_u32 s53, -2
	s_cbranch_scc1 .Lff2B_w8_1
	s_cmp_eq_u32 s42, 1
	s_cbranch_scc1 .Lff2B_w8_1
	s_waitcnt vmcnt(16)
	s_branch .Lff2B_wd_1

; #define PG8_STAGE(bufoff, gbase, voff) do { const char* gb_ = (const char*)(gbase); asm volatile("" : "+s"(gb_));     \
;         _Pragma("unroll") for (int _i = 0; _i < 2; ++_i) \
;         __builtin_amdgcn_global_load_lds((const unsigned*)(gb_ + (voff)[_i]), (PG8_LAS unsigned*)(lds + (bufoff) + ldsw + _i * 8192), 16, 0, 0); } while (0)
; #define PG8_LDA(dst, b, h) do { _Pragma("unroll") for (int m = 0; m < 4; ++m) _Pragma("unroll") for (int k = 0; k < 2; ++k) dst[m][k] = *(const PG8_LAS bf16x8*)(lds + PG8_SA(b, h) + aoff + m * 2048 + k * 1024); } while (0)
; #define PG8_LDB(dst, b, h) do { _Pragma("unroll") for (int n = 0; n < 2; ++n) _Pragma("unroll") for (int k = 0; k < 2; ++k) dst[n][k] = *(const PG8_LAS bf16x8*)(lds + PG8_SB(b, h) + boff + n * 2048 + k * 1024); } while (0)
; #define PG8_MMA(ai, bj, At, Bt) do { __builtin_amdgcn_s_setprio(1); _Pragma("unroll") for (int m = 0; m < 4; ++m) _Pragma("unroll") for (int n = 0; n < 2; ++n) _Pragma("unroll") for (int k = 0; k < 2; ++k) \
;         acc[ai][bj][m][n] = __builtin_amdgcn_mfma_f32_16x16x32_bf16(Bt[n][k], At[m][k], acc[ai][bj][m][n], 0, 0, 0); __builtin_amdgcn_s_setprio(0); } while (0)
; #define PG8_WAIT_V(n) asm volatile("s_waitcnt vmcnt(" #n ")" ::: "memory")
; #define PG8_WAIT_L(n) asm volatile("s_waitcnt lgkmcnt(" #n ")" ::: "memory")
; #define PG8_BAR __builtin_amdgcn_s_barrier()
; #define PG8_SCHED __builtin_amdgcn_sched_barrier(0)
; template <class Epi, class Sched, bool ALIGN_EPI = false, bool SP2 = false>
; __device__ __forceinline__ void gemm_phase(PG8_LAS unsigned char* lds, const Gemm g, const Sched& S, const Epi& E, int wid0) {
;     ...
;             PG8_WAIT_V(8); PG8_WAIT_L(0); PG8_BAR; PG8_MMA(1, 0, At, B0); PG8_MMA(1, 1, At, B1); PG8_BAR; PG8_SCHED;
;             PG8_LDB(B0, 1, 0); PG8_LDB(B1, 1, 1); PG8_SCHED; PG8_LDA(At, 1, 0); PG8_STAGE(PG8_SA(0, 1), a2 + hstepA, vA_);
;             PG8_WAIT_V(8); PG8_WAIT_L(0); PG8_BAR; PG8_MMA(0, 0, At, B0); PG8_MMA(0, 1, At, B1); PG8_BAR; PG8_SCHED;
.Lff2B_wd_1:
	s_waitcnt lgkmcnt(0)
	s_barrier
	s_setprio 1
	s_waitcnt lgkmcnt(0)
	v_mfma_f32_16x16x32_bf16 v[92:95], v[128:131], v[170:173], v[92:95]
	v_mfma_f32_16x16x32_bf16 v[88:91], v[136:139], v[170:173], v[88:91]
	v_mfma_f32_16x16x32_bf16 v[84:87], v[128:131], v[178:181], v[84:87]
	v_mfma_f32_16x16x32_bf16 v[80:83], v[136:139], v[178:181], v[80:83]
	v_mfma_f32_16x16x32_bf16 v[76:79], v[128:131], v[186:189], v[76:79]
	v_mfma_f32_16x16x32_bf16 v[72:75], v[136:139], v[186:189], v[72:75]
	v_mfma_f32_16x16x32_bf16 v[68:71], v[128:131], v[194:197], v[68:71]
	v_mfma_f32_16x16x32_bf16 v[64:67], v[136:139], v[194:197], v[64:67]
	v_mfma_f32_16x16x32_bf16 v[92:95], v[132:135], v[174:177], v[92:95]
	v_mfma_f32_16x16x32_bf16 v[88:91], v[140:143], v[174:177], v[88:91]
	v_mfma_f32_16x16x32_bf16 v[84:87], v[132:135], v[182:185], v[84:87]
	v_mfma_f32_16x16x32_bf16 v[80:83], v[140:143], v[182:185], v[80:83]
	v_mfma_f32_16x16x32_bf16 v[76:79], v[132:135], v[190:193], v[76:79]
	v_mfma_f32_16x16x32_bf16 v[72:75], v[140:143], v[190:193], v[72:75]
	v_mfma_f32_16x16x32_bf16 v[68:71], v[132:135], v[198:201], v[68:71]
	v_mfma_f32_16x16x32_bf16 v[64:67], v[140:143], v[198:201], v[64:67]
	s_setprio 0
	s_setprio 1
	v_mfma_f32_16x16x32_bf16 v[28:31], v[144:147], v[170:173], v[28:31]
	v_mfma_f32_16x16x32_bf16 v[24:27], v[162:165], v[170:173], v[24:27]
	v_mfma_f32_16x16x32_bf16 v[20:23], v[144:147], v[178:181], v[20:23]
	v_mfma_f32_16x16x32_bf16 v[16:19], v[162:165], v[178:181], v[16:19]
	v_mfma_f32_16x16x32_bf16 v[12:15], v[144:147], v[186:189], v[12:15]
	v_mfma_f32_16x16x32_bf16 v[8:11], v[162:165], v[186:189], v[8:11]
	v_mfma_f32_16x16x32_bf16 v[4:7], v[144:147], v[194:197], v[4:7]
	v_mfma_f32_16x16x32_bf16 v[0:3], v[162:165], v[194:197], v[0:3]
	v_mfma_f32_16x16x32_bf16 v[28:31], v[158:161], v[174:177], v[28:31]
	v_mfma_f32_16x16x32_bf16 v[24:27], v[166:169], v[174:177], v[24:27]
	v_mfma_f32_16x16x32_bf16 v[20:23], v[158:161], v[182:185], v[20:23]
	v_mfma_f32_16x16x32_bf16 v[16:19], v[166:169], v[182:185], v[16:19]
	v_mfma_f32_16x16x32_bf16 v[12:15], v[158:161], v[190:193], v[12:15]
	v_mfma_f32_16x16x32_bf16 v[8:11], v[166:169], v[190:193], v[8:11]
	v_mfma_f32_16x16x32_bf16 v[4:7], v[158:161], v[198:201], v[4:7]
	v_mfma_f32_16x16x32_bf16 v[0:3], v[166:169], v[198:201], v[0:3]
	s_setprio 0
	s_barrier
	s_add_i32 s54, 0, 0x18000
	s_add_i32 s55, 0, 0x1c000
	v_add_u32_e32 v140, s54, v149
	v_add_u32_e32 v166, s55, v149
	ds_read_b128 v[128:131], v140
	ds_read_b128 v[132:135], v140 offset:1024
	ds_read_b128 v[136:139], v140 offset:2048
	ds_read_b128 v[140:143], v140 offset:3072
	ds_read_b128 v[144:147], v166
	ds_read_b128 v[158:161], v166 offset:1024
	ds_read_b128 v[162:165], v166 offset:2048
	ds_read_b128 v[166:169], v166 offset:3072
	s_add_u32 s24, s34, 0x100000
	s_addc_u32 s25, s35, 0
	s_mov_b32 m0, s40
	ds_read_b128 v[170:173], v156 offset:32768
	ds_read_b128 v[174:177], v156 offset:33792
	ds_read_b128 v[178:181], v156 offset:34816
	ds_read_b128 v[182:185], v156 offset:35840
	ds_read_b128 v[186:189], v156 offset:36864
	ds_read_b128 v[190:193], v156 offset:37888
	ds_read_b128 v[194:197], v156 offset:38912
	ds_read_b128 v[198:201], v156 offset:39936
	s_nop 0
	global_load_lds_dwordx4 v205, s[24:25]
	s_mov_b32 m0, s41
	s_nop 0
	global_load_lds_dwordx4 v203, s[24:25]
	s_waitcnt vmcnt(8)
	s_waitcnt lgkmcnt(0)
	s_barrier
	s_setprio 1
	s_waitcnt lgkmcnt(0)
	v_mfma_f32_16x16x32_bf16 v[124:127], v[128:131], v[170:173], v[124:127]
	v_mfma_f32_16x16x32_bf16 v[120:123], v[136:139], v[170:173], v[120:123]
	v_mfma_f32_16x16x32_bf16 v[116:119], v[128:131], v[178:181], v[116:119]
	v_mfma_f32_16x16x32_bf16 v[112:115], v[136:139], v[178:181], v[112:115]
	v_mfma_f32_16x16x32_bf16 v[108:111], v[128:131], v[186:189], v[108:111]
	v_mfma_f32_16x16x32_bf16 v[104:107], v[136:139], v[186:189], v[104:107]
	v_mfma_f32_16x16x32_bf16 v[100:103], v[128:131], v[194:197], v[100:103]
	v_mfma_f32_16x16x32_bf16 v[96:99], v[136:139], v[194:197], v[96:99]
	v_mfma_f32_16x16x32_bf16 v[124:127], v[132:135], v[174:177], v[124:127]
	v_mfma_f32_16x16x32_bf16 v[120:123], v[140:143], v[174:177], v[120:123]
	v_mfma_f32_16x16x32_bf16 v[116:119], v[132:135], v[182:185], v[116:119]
	v_mfma_f32_16x16x32_bf16 v[112:115], v[140:143], v[182:185], v[112:115]
	v_mfma_f32_16x16x32_bf16 v[108:111], v[132:135], v[190:193], v[108:111]
	v_mfma_f32_16x16x32_bf16 v[104:107], v[140:143], v[190:193], v[104:107]
	v_mfma_f32_16x16x32_bf16 v[100:103], v[132:135], v[198:201], v[100:103]
	v_mfma_f32_16x16x32_bf16 v[96:99], v[140:143], v[198:201], v[96:99]
	s_setprio 0
	s_setprio 1
	v_mfma_f32_16x16x32_bf16 v[60:63], v[144:147], v[170:173], v[60:63]
	v_mfma_f32_16x16x32_bf16 v[56:59], v[162:165], v[170:173], v[56:59]
	v_mfma_f32_16x16x32_bf16 v[52:55], v[144:147], v[178:181], v[52:55]
	v_mfma_f32_16x16x32_bf16 v[48:51], v[162:165], v[178:181], v[48:51]
	v_mfma_f32_16x16x32_bf16 v[44:47], v[144:147], v[186:189], v[44:47]
	v_mfma_f32_16x16x32_bf16 v[40:43], v[162:165], v[186:189], v[40:43]
	v_mfma_f32_16x16x32_bf16 v[36:39], v[144:147], v[194:197], v[36:39]
	v_mfma_f32_16x16x32_bf16 v[32:35], v[162:165], v[194:197], v[32:35]
	v_mfma_f32_16x16x32_bf16 v[60:63], v[158:161], v[174:177], v[60:63]
	v_mfma_f32_16x16x32_bf16 v[56:59], v[166:169], v[174:177], v[56:59]
	v_mfma_f32_16x16x32_bf16 v[52:55], v[158:161], v[182:185], v[52:55]
	v_mfma_f32_16x16x32_bf16 v[48:51], v[166:169], v[182:185], v[48:51]
	v_mfma_f32_16x16x32_bf16 v[44:47], v[158:161], v[190:193], v[44:47]
	v_mfma_f32_16x16x32_bf16 v[40:43], v[166:169], v[190:193], v[40:43]
	v_mfma_f32_16x16x32_bf16 v[36:39], v[158:161], v[198:201], v[36:39]
	v_mfma_f32_16x16x32_bf16 v[32:35], v[166:169], v[198:201], v[32:35]
	s_setprio 0
	s_barrier
; #define PG8_STAGE(bufoff, gbase, voff) do { const char* gb_ = (const char*)(gbase); asm volatile("" : "+s"(gb_));     \
;         _Pragma("unroll") for (int _i = 0; _i < 2; ++_i) \
;         __builtin_amdgcn_global_load_lds((const unsigned*)(gb_ + (voff)[_i]), (PG8_LAS unsigned*)(lds + (bufoff) + ldsw + _i * 8192), 16, 0, 0); } while (0)
; #define PG8_LDA(dst, b, h) do { _Pragma("unroll") for (int m = 0; m < 4; ++m) _Pragma("unroll") for (int k = 0; k < 2; ++k) dst[m][k] = *(const PG8_LAS bf16x8*)(lds + PG8_SA(b, h) + aoff + m * 2048 + k * 1024); } while (0)
; #define PG8_MMA(ai, bj, At, Bt) do { __builtin_amdgcn_s_setprio(1); _Pragma("unroll") for (int m = 0; m < 4; ++m) _Pragma("unroll") for (int n = 0; n < 2; ++n) _Pragma("unroll") for (int k = 0; k < 2; ++k) \
;         acc[ai][bj][m][n] = __builtin_amdgcn_mfma_f32_16x16x32_bf16(Bt[n][k], At[m][k], acc[ai][bj][m][n], 0, 0, 0); __builtin_amdgcn_s_setprio(0); } while (0)
; #define PG8_WAIT_V(n) asm volatile("s_waitcnt vmcnt(" #n ")" ::: "memory")
; #define PG8_WAIT_L(n) asm volatile("s_waitcnt lgkmcnt(" #n ")" ::: "memory")
; #define PG8_BAR __builtin_amdgcn_s_barrier()
; #define PG8_SCHED __builtin_amdgcn_sched_barrier(0)
; template <class Epi, class Sched, bool ALIGN_EPI = false, bool SP2 = false>
; __device__ __forceinline__ void gemm_phase(PG8_LAS unsigned char* lds, const Gemm g, const Sched& S, const Epi& E, int wid0) {
;     ...
;         for (int t = 0; t < nt; t += 2) {
;     ...
;             PG8_LDA(At, 1, 1); PG8_STAGE(PG8_SB(1, 0), b3, vB_); PG8_STAGE(PG8_SB(1, 1), b3 + hstep, vB_); PG8_STAGE(PG8_SA(1, 0), a3, vA_);
;             PG8_WAIT_V(8); PG8_WAIT_L(0); PG8_BAR; PG8_MMA(1, 0, At, B0); PG8_MMA(1, 1, At, B1); PG8_BAR; PG8_SCHED;
	s_add_u32 s24, s30, 0x80
	s_addc_u32 s25, s31, 0
	s_add_i32 s34, s54, s33
	s_mov_b32 m0, s34
	ds_read_b128 v[170:173], v156 offset:49152
	ds_read_b128 v[174:177], v156 offset:50176
	ds_read_b128 v[178:181], v156 offset:51200
	ds_read_b128 v[182:185], v156 offset:52224
	ds_read_b128 v[186:189], v156 offset:53248
	ds_read_b128 v[190:193], v156 offset:54272
	ds_read_b128 v[194:197], v156 offset:55296
	ds_read_b128 v[198:201], v156 offset:56320
	s_nop 0
	global_load_lds_dwordx4 v202, s[24:25]
	s_add_i32 m0, s34, 0x2000
	s_nop 0
	global_load_lds_dwordx4 v204, s[24:25]
	s_add_u32 s24, s30, 0x100080
	s_addc_u32 s25, s31, 0
	s_add_i32 s30, s55, s33
	s_mov_b32 m0, s30
	s_nop 0
	global_load_lds_dwordx4 v202, s[24:25]
	s_add_i32 m0, s30, 0x2000
	s_nop 0
	global_load_lds_dwordx4 v204, s[24:25]
	s_mov_b32 m0, s45
	s_nop 0
	global_load_lds_dwordx4 v205, s[28:29]
	s_mov_b32 m0, s46
	s_nop 0
	global_load_lds_dwordx4 v203, s[28:29]
	s_waitcnt vmcnt(8)
	s_waitcnt lgkmcnt(0)
	s_barrier
	s_setprio 1
	s_waitcnt lgkmcnt(0)
	v_mfma_f32_16x16x32_bf16 v[92:95], v[128:131], v[170:173], v[92:95]
	v_mfma_f32_16x16x32_bf16 v[88:91], v[136:139], v[170:173], v[88:91]
	v_mfma_f32_16x16x32_bf16 v[84:87], v[128:131], v[178:181], v[84:87]
	v_mfma_f32_16x16x32_bf16 v[80:83], v[136:139], v[178:181], v[80:83]
	v_mfma_f32_16x16x32_bf16 v[76:79], v[128:131], v[186:189], v[76:79]
	v_mfma_f32_16x16x32_bf16 v[72:75], v[136:139], v[186:189], v[72:75]
	v_mfma_f32_16x16x32_bf16 v[68:71], v[128:131], v[194:197], v[68:71]
	v_mfma_f32_16x16x32_bf16 v[64:67], v[136:139], v[194:197], v[64:67]
	v_mfma_f32_16x16x32_bf16 v[92:95], v[132:135], v[174:177], v[92:95]
	v_mfma_f32_16x16x32_bf16 v[88:91], v[140:143], v[174:177], v[88:91]
	v_mfma_f32_16x16x32_bf16 v[84:87], v[132:135], v[182:185], v[84:87]
	v_mfma_f32_16x16x32_bf16 v[80:83], v[140:143], v[182:185], v[80:83]
	v_mfma_f32_16x16x32_bf16 v[76:79], v[132:135], v[190:193], v[76:79]
	v_mfma_f32_16x16x32_bf16 v[72:75], v[140:143], v[190:193], v[72:75]
	v_mfma_f32_16x16x32_bf16 v[68:71], v[132:135], v[198:201], v[68:71]
	v_mfma_f32_16x16x32_bf16 v[64:67], v[140:143], v[198:201], v[64:67]
	s_setprio 0
	s_setprio 1
	v_mfma_f32_16x16x32_bf16 v[28:31], v[144:147], v[170:173], v[28:31]
	v_mfma_f32_16x16x32_bf16 v[24:27], v[162:165], v[170:173], v[24:27]
	v_mfma_f32_16x16x32_bf16 v[20:23], v[144:147], v[178:181], v[20:23]
	v_mfma_f32_16x16x32_bf16 v[16:19], v[162:165], v[178:181], v[16:19]
	v_mfma_f32_16x16x32_bf16 v[12:15], v[144:147], v[186:189], v[12:15]
	v_mfma_f32_16x16x32_bf16 v[8:11], v[162:165], v[186:189], v[8:11]
	v_mfma_f32_16x16x32_bf16 v[4:7], v[144:147], v[194:197], v[4:7]
	v_mfma_f32_16x16x32_bf16 v[0:3], v[162:165], v[194:197], v[0:3]
	v_mfma_f32_16x16x32_bf16 v[28:31], v[158:161], v[174:177], v[28:31]
	v_mfma_f32_16x16x32_bf16 v[24:27], v[166:169], v[174:177], v[24:27]
	v_mfma_f32_16x16x32_bf16 v[20:23], v[158:161], v[182:185], v[20:23]
	v_mfma_f32_16x16x32_bf16 v[16:19], v[166:169], v[182:185], v[16:19]
	v_mfma_f32_16x16x32_bf16 v[12:15], v[158:161], v[190:193], v[12:15]
	v_mfma_f32_16x16x32_bf16 v[8:11], v[166:169], v[190:193], v[8:11]
	v_mfma_f32_16x16x32_bf16 v[4:7], v[158:161], v[198:201], v[4:7]
	v_mfma_f32_16x16x32_bf16 v[0:3], v[166:169], v[198:201], v[0:3]
	s_setprio 0
	s_barrier
	s_add_i32 s53, s53, 2
	s_add_u32 s51, s51, 0x100
	s_addc_u32 s52, s52, 0
	s_cmp_gt_u32 s53, 61
	s_mov_b64 s[24:25], s[26:27]
	s_cbranch_scc0 .LBB13_2163
	s_and_b64 vcc, exec, s[8:9]
	s_cbranch_vccz .LBB13_2166
	s_barrier
